# v24 plus: all s_setprio removed from GEMM K-loops (no priority flips)
# speedup vs baseline: 1.0093x; 1.0017x over previous
.LBB0_196:
	s_cmp_lg_u32 s22, 0
	s_mov_b32 s22, 0
	s_cbranch_scc0 .LBB0_198
	ds_read_b128 v[2:5], v161
	ds_read_b128 v[6:9], v161 offset:1024
	ds_read_b128 v[10:13], v161 offset:2048
	ds_read_b128 v[14:17], v161 offset:3072
	ds_read_b128 v[18:21], v162
	ds_read_b128 v[22:25], v162 offset:1024
	ds_read_b128 v[26:29], v162 offset:2048
	ds_read_b128 v[30:33], v162 offset:3072
	s_add_u32 s0, s4, 0x10000
	s_addc_u32 s1, s5, 0
	ds_read_b128 v[34:37], v163
	ds_read_b128 v[38:41], v163 offset:1024
	ds_read_b128 v[42:45], v163 offset:2048
	ds_read_b128 v[46:49], v163 offset:3072
	ds_read_b128 v[50:53], v163 offset:4096
	ds_read_b128 v[54:57], v163 offset:5120
	ds_read_b128 v[58:61], v163 offset:6144
	ds_read_b128 v[62:65], v163 offset:7168
	s_waitcnt vmcnt(24)
	s_waitcnt lgkmcnt(0)
	s_barrier
	v_mfma_f32_16x16x32_bf16 v[90:93], v[2:5], v[58:61], 0
	v_mfma_f32_16x16x32_bf16 v[66:69], v[2:5], v[34:37], 0
	v_mfma_f32_16x16x32_bf16 v[70:73], v[10:13], v[34:37], 0
	v_mfma_f32_16x16x32_bf16 v[74:77], v[2:5], v[42:45], 0
	v_mfma_f32_16x16x32_bf16 v[78:81], v[10:13], v[42:45], 0
	v_mfma_f32_16x16x32_bf16 v[82:85], v[2:5], v[50:53], 0
	v_mfma_f32_16x16x32_bf16 v[86:89], v[10:13], v[50:53], 0
	v_mfma_f32_16x16x32_bf16 v[100:103], v[6:9], v[62:65], v[90:93]
	v_mfma_f32_16x16x32_bf16 v[90:93], v[10:13], v[58:61], 0
	v_mfma_f32_16x16x32_bf16 v[66:69], v[6:9], v[38:41], v[66:69]
	v_mfma_f32_16x16x32_bf16 v[70:73], v[14:17], v[38:41], v[70:73]
	v_mfma_f32_16x16x32_bf16 v[74:77], v[6:9], v[46:49], v[74:77]
	v_mfma_f32_16x16x32_bf16 v[78:81], v[14:17], v[46:49], v[78:81]
	v_mfma_f32_16x16x32_bf16 v[82:85], v[6:9], v[54:57], v[82:85]
	v_mfma_f32_16x16x32_bf16 v[86:89], v[14:17], v[54:57], v[86:89]
	v_mfma_f32_16x16x32_bf16 v[104:107], v[14:17], v[62:65], v[90:93]
	v_mfma_f32_16x16x32_bf16 v[90:93], v[18:21], v[34:37], 0
	v_mfma_f32_16x16x32_bf16 v[34:37], v[26:29], v[34:37], 0
	v_mfma_f32_16x16x32_bf16 v[116:119], v[22:25], v[38:41], v[90:93]
	v_mfma_f32_16x16x32_bf16 v[34:37], v[30:33], v[38:41], v[34:37]
	v_mfma_f32_16x16x32_bf16 v[38:41], v[18:21], v[42:45], 0
	v_mfma_f32_16x16x32_bf16 v[42:45], v[26:29], v[42:45], 0
	v_mfma_f32_16x16x32_bf16 v[38:41], v[22:25], v[46:49], v[38:41]
	v_mfma_f32_16x16x32_bf16 v[42:45], v[30:33], v[46:49], v[42:45]
	v_mfma_f32_16x16x32_bf16 v[46:49], v[18:21], v[50:53], 0
	v_mfma_f32_16x16x32_bf16 v[50:53], v[26:29], v[50:53], 0
	v_mfma_f32_16x16x32_bf16 v[46:49], v[22:25], v[54:57], v[46:49]
	v_mfma_f32_16x16x32_bf16 v[50:53], v[30:33], v[54:57], v[50:53]
	v_mfma_f32_16x16x32_bf16 v[54:57], v[18:21], v[58:61], 0
	v_mfma_f32_16x16x32_bf16 v[58:61], v[26:29], v[58:61], 0
	v_mfma_f32_16x16x32_bf16 v[54:57], v[22:25], v[62:65], v[54:57]
	v_mfma_f32_16x16x32_bf16 v[58:61], v[30:33], v[62:65], v[58:61]
	s_barrier
	s_add_i32 s12, s60, s17
	v_lshl_add_u64 v[98:99], s[0:1], 0, v[134:135]
	s_mov_b32 m0, s12
	ds_read_b128 v[62:65], v163 offset:16384
	ds_read_b128 v[90:93], v163 offset:17408
	ds_read_b128 v[94:97], v163 offset:18432
	ds_read_b128 v[108:111], v163 offset:19456
	ds_read_b128 v[112:115], v163 offset:20480
	ds_read_b128 v[120:123], v163 offset:21504
	ds_read_b128 v[124:127], v163 offset:22528
	ds_read_b128 v[128:131], v163 offset:23552
	global_load_lds_dwordx4 v[98:99], off
	s_add_i32 m0, s12, 0x2000
	v_lshl_add_u64 v[98:99], s[0:1], 0, v[138:139]
	s_add_u32 s0, s4, 0x14000
	s_addc_u32 s1, s5, 0
	s_add_i32 s12, s61, s17
	global_load_lds_dwordx4 v[98:99], off
	v_lshl_add_u64 v[98:99], s[0:1], 0, v[134:135]
	s_mov_b32 m0, s12
	v_lshl_add_u64 v[156:157], s[8:9], 0, v[132:133]
	global_load_lds_dwordx4 v[98:99], off
	v_lshl_add_u64 v[98:99], s[0:1], 0, v[138:139]
	s_add_i32 m0, s12, 0x2000
	v_lshl_add_u64 v[144:145], s[8:9], 0, v[136:137]
	global_load_lds_dwordx4 v[98:99], off
	v_lshl_add_u64 v[98:99], v[156:157], 0, s[36:37]
	s_mov_b32 m0, s18
	s_nop 0
	global_load_lds_dwordx4 v[98:99], off
	v_lshl_add_u64 v[98:99], v[144:145], 0, s[36:37]
	s_mov_b32 m0, s19
	s_nop 0
	global_load_lds_dwordx4 v[98:99], off
	s_waitcnt vmcnt(24)
	s_waitcnt lgkmcnt(0)
	s_barrier
	v_mfma_f32_16x16x32_bf16 v[148:151], v[2:5], v[62:65], 0
	v_mfma_f32_16x16x32_bf16 v[166:169], v[2:5], v[94:97], 0
	v_mfma_f32_16x16x32_bf16 v[174:177], v[2:5], v[112:115], 0
	v_mfma_f32_16x16x32_bf16 v[2:5], v[2:5], v[124:127], 0
	v_mfma_f32_16x16x32_bf16 v[148:151], v[6:9], v[90:93], v[148:151]
	v_mfma_f32_16x16x32_bf16 v[166:169], v[6:9], v[108:111], v[166:169]
	v_mfma_f32_16x16x32_bf16 v[174:177], v[6:9], v[120:123], v[174:177]
	v_mfma_f32_16x16x32_bf16 v[2:5], v[6:9], v[128:131], v[2:5]
	v_mfma_f32_16x16x32_bf16 v[6:9], v[10:13], v[124:127], 0
	v_mfma_f32_16x16x32_bf16 v[152:155], v[10:13], v[62:65], 0
	v_mfma_f32_16x16x32_bf16 v[170:173], v[10:13], v[94:97], 0
	v_mfma_f32_16x16x32_bf16 v[178:181], v[10:13], v[112:115], 0
	v_mfma_f32_16x16x32_bf16 v[6:9], v[14:17], v[128:131], v[6:9]
	v_mfma_f32_16x16x32_bf16 v[152:155], v[14:17], v[90:93], v[152:155]
	v_mfma_f32_16x16x32_bf16 v[170:173], v[14:17], v[108:111], v[170:173]
	v_mfma_f32_16x16x32_bf16 v[178:181], v[14:17], v[120:123], v[178:181]
	v_mfma_f32_16x16x32_bf16 v[10:13], v[18:21], v[62:65], 0
	v_mfma_f32_16x16x32_bf16 v[182:185], v[22:25], v[90:93], v[10:13]
	v_mfma_f32_16x16x32_bf16 v[10:13], v[26:29], v[62:65], 0
	v_mfma_f32_16x16x32_bf16 v[186:189], v[30:33], v[90:93], v[10:13]
	v_mfma_f32_16x16x32_bf16 v[10:13], v[18:21], v[94:97], 0
	v_mfma_f32_16x16x32_bf16 v[190:193], v[22:25], v[108:111], v[10:13]
	v_mfma_f32_16x16x32_bf16 v[10:13], v[26:29], v[94:97], 0
	v_mfma_f32_16x16x32_bf16 v[194:197], v[30:33], v[108:111], v[10:13]
	v_mfma_f32_16x16x32_bf16 v[10:13], v[18:21], v[112:115], 0
	v_mfma_f32_16x16x32_bf16 v[198:201], v[22:25], v[120:123], v[10:13]
	v_mfma_f32_16x16x32_bf16 v[10:13], v[26:29], v[112:115], 0
	v_mfma_f32_16x16x32_bf16 v[202:205], v[30:33], v[120:123], v[10:13]
	v_mfma_f32_16x16x32_bf16 v[10:13], v[18:21], v[124:127], 0
	v_mfma_f32_16x16x32_bf16 v[206:209], v[22:25], v[128:131], v[10:13]
	v_mfma_f32_16x16x32_bf16 v[10:13], v[26:29], v[124:127], 0
	v_mfma_f32_16x16x32_bf16 v[210:213], v[30:33], v[128:131], v[10:13]
	s_barrier
	s_add_i32 s12, 0, 0x18000
	v_add_u32_e32 v1, s12, v160
	s_add_i32 s13, 0, 0x1c000
	s_nop 1
	ds_read_b128 v[10:13], v1
	ds_read_b128 v[14:17], v1 offset:1024
	ds_read_b128 v[20:23], v1 offset:2048
	ds_read_b128 v[24:27], v1 offset:3072
	v_add_u32_e32 v1, s13, v160
	ds_read_b128 v[214:217], v1
	ds_read_b128 v[218:221], v1 offset:1024
	ds_read_b128 v[222:225], v1 offset:2048
	ds_read_b128 v[226:229], v1 offset:3072
	s_add_u32 s0, s8, 0x100100
	s_addc_u32 s1, s9, 0
	s_mov_b32 m0, s20
	v_lshl_add_u64 v[18:19], s[0:1], 0, v[132:133]
	ds_read_b128 v[28:31], v163 offset:32768
	ds_read_b128 v[62:65], v163 offset:33792
	ds_read_b128 v[230:233], v163 offset:34816
	ds_read_b128 v[234:237], v163 offset:35840
	ds_read_b128 v[238:241], v163 offset:36864
	ds_read_b128 v[242:245], v163 offset:37888
	ds_read_b128 v[246:249], v163 offset:38912
	ds_read_b128 v[250:253], v163 offset:39936
	global_load_lds_dwordx4 v[18:19], off
	v_lshl_add_u64 v[18:19], s[0:1], 0, v[136:137]
	s_mov_b32 m0, s21
	s_nop 0
	global_load_lds_dwordx4 v[18:19], off
	s_waitcnt vmcnt(24)
	s_waitcnt lgkmcnt(0)
	s_barrier
	v_mfma_f32_16x16x32_bf16 v[66:69], v[10:13], v[28:31], v[66:69]
	v_mfma_f32_16x16x32_bf16 v[128:131], v[14:17], v[62:65], v[66:69]
	v_mfma_f32_16x16x32_bf16 v[66:69], v[20:23], v[28:31], v[70:73]
	v_mfma_f32_16x16x32_bf16 v[124:127], v[24:27], v[62:65], v[66:69]
	v_mfma_f32_16x16x32_bf16 v[66:69], v[10:13], v[230:233], v[74:77]
	v_mfma_f32_16x16x32_bf16 v[112:115], v[14:17], v[234:237], v[66:69]
	v_mfma_f32_16x16x32_bf16 v[66:69], v[20:23], v[230:233], v[78:81]
	v_mfma_f32_16x16x32_bf16 v[108:111], v[24:27], v[234:237], v[66:69]
	v_mfma_f32_16x16x32_bf16 v[66:69], v[10:13], v[238:241], v[82:85]
	v_mfma_f32_16x16x32_bf16 v[96:99], v[14:17], v[242:245], v[66:69]
	v_mfma_f32_16x16x32_bf16 v[66:69], v[20:23], v[238:241], v[86:89]
	v_mfma_f32_16x16x32_bf16 v[92:95], v[24:27], v[242:245], v[66:69]
	v_mfma_f32_16x16x32_bf16 v[66:69], v[10:13], v[246:249], v[100:103]
	v_mfma_f32_16x16x32_bf16 v[80:83], v[14:17], v[250:253], v[66:69]
	v_mfma_f32_16x16x32_bf16 v[66:69], v[20:23], v[246:249], v[104:107]
	v_mfma_f32_16x16x32_bf16 v[76:79], v[24:27], v[250:253], v[66:69]
	v_mfma_f32_16x16x32_bf16 v[66:69], v[214:217], v[28:31], v[116:119]
	v_mfma_f32_16x16x32_bf16 v[28:31], v[222:225], v[28:31], v[34:37]
	v_mfma_f32_16x16x32_bf16 v[116:119], v[226:229], v[62:65], v[28:31]
	v_mfma_f32_16x16x32_bf16 v[28:31], v[214:217], v[230:233], v[38:41]
	v_mfma_f32_16x16x32_bf16 v[104:107], v[218:221], v[234:237], v[28:31]
	v_mfma_f32_16x16x32_bf16 v[28:31], v[222:225], v[230:233], v[42:45]
	v_mfma_f32_16x16x32_bf16 v[100:103], v[226:229], v[234:237], v[28:31]
	v_mfma_f32_16x16x32_bf16 v[28:31], v[214:217], v[238:241], v[46:49]
	v_mfma_f32_16x16x32_bf16 v[88:91], v[218:221], v[242:245], v[28:31]
	v_mfma_f32_16x16x32_bf16 v[28:31], v[222:225], v[238:241], v[50:53]
	v_mfma_f32_16x16x32_bf16 v[84:87], v[226:229], v[242:245], v[28:31]
	v_mfma_f32_16x16x32_bf16 v[28:31], v[214:217], v[246:249], v[54:57]
	v_mfma_f32_16x16x32_bf16 v[72:75], v[218:221], v[250:253], v[28:31]
	v_mfma_f32_16x16x32_bf16 v[28:31], v[222:225], v[246:249], v[58:61]
	v_mfma_f32_16x16x32_bf16 v[120:123], v[218:221], v[62:65], v[66:69]
	v_mfma_f32_16x16x32_bf16 v[68:71], v[226:229], v[250:253], v[28:31]
	s_barrier
	s_add_u32 s0, s4, 0x18000
	s_addc_u32 s1, s5, 0
	s_add_i32 s12, s12, s17
	v_lshl_add_u64 v[18:19], s[0:1], 0, v[134:135]
	s_mov_b32 m0, s12
	ds_read_b128 v[36:39], v163 offset:49152
	ds_read_b128 v[40:43], v163 offset:50176
	ds_read_b128 v[230:233], v163 offset:51200
	ds_read_b128 v[234:237], v163 offset:52224
	ds_read_b128 v[238:241], v163 offset:53248
	ds_read_b128 v[242:245], v163 offset:54272
	ds_read_b128 v[246:249], v163 offset:55296
	ds_read_b128 v[250:253], v163 offset:56320
	global_load_lds_dwordx4 v[18:19], off
	s_add_i32 m0, s12, 0x2000
	v_lshl_add_u64 v[18:19], s[0:1], 0, v[138:139]
	s_add_u32 s0, s4, 0x1c000
	s_addc_u32 s1, s5, 0
	s_add_i32 s12, s13, s17
	global_load_lds_dwordx4 v[18:19], off
	v_lshl_add_u64 v[18:19], s[0:1], 0, v[134:135]
	s_mov_b32 m0, s12
	s_nop 0
	global_load_lds_dwordx4 v[18:19], off
	v_lshl_add_u64 v[18:19], s[0:1], 0, v[138:139]
	s_add_i32 m0, s12, 0x2000
	s_nop 0
	global_load_lds_dwordx4 v[18:19], off
	v_lshl_add_u64 v[18:19], v[156:157], 0, s[38:39]
	s_mov_b32 m0, s51
	s_nop 0
	global_load_lds_dwordx4 v[18:19], off
	v_lshl_add_u64 v[18:19], v[144:145], 0, s[38:39]
	s_mov_b32 m0, s56
	s_nop 0
	global_load_lds_dwordx4 v[18:19], off
	s_waitcnt vmcnt(8)
	s_waitcnt lgkmcnt(0)
	s_barrier
	v_mfma_f32_16x16x32_bf16 v[28:31], v[10:13], v[36:39], v[148:151]
	v_mfma_f32_16x16x32_bf16 v[64:67], v[14:17], v[40:43], v[28:31]
	v_mfma_f32_16x16x32_bf16 v[28:31], v[20:23], v[36:39], v[152:155]
	v_mfma_f32_16x16x32_bf16 v[60:63], v[24:27], v[40:43], v[28:31]
	v_mfma_f32_16x16x32_bf16 v[28:31], v[10:13], v[230:233], v[166:169]
	v_mfma_f32_16x16x32_bf16 v[48:51], v[14:17], v[234:237], v[28:31]
	v_mfma_f32_16x16x32_bf16 v[28:31], v[20:23], v[230:233], v[170:173]
	v_mfma_f32_16x16x32_bf16 v[44:47], v[24:27], v[234:237], v[28:31]
	v_mfma_f32_16x16x32_bf16 v[28:31], v[10:13], v[238:241], v[174:177]
	v_mfma_f32_16x16x32_bf16 v[2:5], v[10:13], v[246:249], v[2:5]
	v_mfma_f32_16x16x32_bf16 v[32:35], v[14:17], v[242:245], v[28:31]
	v_mfma_f32_16x16x32_bf16 v[28:31], v[20:23], v[238:241], v[178:181]
	v_mfma_f32_16x16x32_bf16 v[16:19], v[14:17], v[250:253], v[2:5]
	v_mfma_f32_16x16x32_bf16 v[2:5], v[20:23], v[246:249], v[6:9]
	v_mfma_f32_16x16x32_bf16 v[28:31], v[24:27], v[242:245], v[28:31]
	v_mfma_f32_16x16x32_bf16 v[12:15], v[24:27], v[250:253], v[2:5]
	v_mfma_f32_16x16x32_bf16 v[2:5], v[214:217], v[36:39], v[182:185]
	v_mfma_f32_16x16x32_bf16 v[56:59], v[218:221], v[40:43], v[2:5]
	v_mfma_f32_16x16x32_bf16 v[2:5], v[222:225], v[36:39], v[186:189]
	v_mfma_f32_16x16x32_bf16 v[52:55], v[226:229], v[40:43], v[2:5]
	v_mfma_f32_16x16x32_bf16 v[2:5], v[214:217], v[230:233], v[190:193]
	v_mfma_f32_16x16x32_bf16 v[40:43], v[218:221], v[234:237], v[2:5]
	v_mfma_f32_16x16x32_bf16 v[2:5], v[222:225], v[230:233], v[194:197]
	v_mfma_f32_16x16x32_bf16 v[36:39], v[226:229], v[234:237], v[2:5]
	v_mfma_f32_16x16x32_bf16 v[2:5], v[214:217], v[238:241], v[198:201]
	v_mfma_f32_16x16x32_bf16 v[24:27], v[218:221], v[242:245], v[2:5]
	v_mfma_f32_16x16x32_bf16 v[2:5], v[222:225], v[238:241], v[202:205]
	v_mfma_f32_16x16x32_bf16 v[20:23], v[226:229], v[242:245], v[2:5]
	v_mfma_f32_16x16x32_bf16 v[2:5], v[214:217], v[246:249], v[206:209]
	v_mfma_f32_16x16x32_bf16 v[8:11], v[218:221], v[250:253], v[2:5]
	v_mfma_f32_16x16x32_bf16 v[2:5], v[222:225], v[246:249], v[210:213]
	v_mfma_f32_16x16x32_bf16 v[4:7], v[226:229], v[250:253], v[2:5]
	s_barrier
	s_mov_b32 s22, 2
	s_branch .LBB0_199

.LBB0_200:
	ds_read_b128 v[150:153], v161
	ds_read_b128 v[154:157], v161 offset:1024
	ds_read_b128 v[166:169], v161 offset:2048
	ds_read_b128 v[170:173], v161 offset:3072
	ds_read_b128 v[174:177], v162
	ds_read_b128 v[178:181], v162 offset:1024
	ds_read_b128 v[182:185], v162 offset:2048
	ds_read_b128 v[186:189], v162 offset:3072
	s_add_u32 s8, s55, s26
	s_addc_u32 s9, s63, 0
	s_cmp_eq_u32 s26, s4
	s_cselect_b32 s23, s0, s9
	s_cselect_b32 s22, s1, s8
	s_cselect_b32 s9, s41, s54
	s_cselect_b32 s8, s43, s53
	s_add_i32 s65, s18, 0xc000
	v_lshl_add_u64 v[144:145], v[2:3], 0, s[26:27]
	s_mov_b32 m0, s65
	s_add_i32 s64, s18, 0xe000
	ds_read_b128 v[190:193], v163
	ds_read_b128 v[194:197], v163 offset:1024
	ds_read_b128 v[198:201], v163 offset:2048
	ds_read_b128 v[202:205], v163 offset:3072
	ds_read_b128 v[206:209], v163 offset:4096
	ds_read_b128 v[210:213], v163 offset:5120
	ds_read_b128 v[214:217], v163 offset:6144
	ds_read_b128 v[218:221], v163 offset:7168
	global_load_lds_dwordx4 v[144:145], off
	v_lshl_add_u64 v[144:145], v[148:149], 0, s[26:27]
	s_mov_b32 m0, s64
	s_nop 0
	global_load_lds_dwordx4 v[144:145], off
	s_waitcnt vmcnt(8)
	s_waitcnt lgkmcnt(0)
	s_barrier
	v_mfma_f32_16x16x32_bf16 v[128:131], v[150:153], v[190:193], v[128:131]
	v_mfma_f32_16x16x32_bf16 v[124:127], v[166:169], v[190:193], v[124:127]
	v_mfma_f32_16x16x32_bf16 v[112:115], v[150:153], v[198:201], v[112:115]
	v_mfma_f32_16x16x32_bf16 v[108:111], v[166:169], v[198:201], v[108:111]
	v_mfma_f32_16x16x32_bf16 v[96:99], v[150:153], v[206:209], v[96:99]
	v_mfma_f32_16x16x32_bf16 v[92:95], v[166:169], v[206:209], v[92:95]
	v_mfma_f32_16x16x32_bf16 v[80:83], v[150:153], v[214:217], v[80:83]
	v_mfma_f32_16x16x32_bf16 v[76:79], v[166:169], v[214:217], v[76:79]
	v_mfma_f32_16x16x32_bf16 v[128:131], v[154:157], v[194:197], v[128:131]
	v_mfma_f32_16x16x32_bf16 v[124:127], v[170:173], v[194:197], v[124:127]
	v_mfma_f32_16x16x32_bf16 v[112:115], v[154:157], v[202:205], v[112:115]
	v_mfma_f32_16x16x32_bf16 v[108:111], v[170:173], v[202:205], v[108:111]
	v_mfma_f32_16x16x32_bf16 v[96:99], v[154:157], v[210:213], v[96:99]
	v_mfma_f32_16x16x32_bf16 v[92:95], v[170:173], v[210:213], v[92:95]
	v_mfma_f32_16x16x32_bf16 v[80:83], v[154:157], v[218:221], v[80:83]
	v_mfma_f32_16x16x32_bf16 v[76:79], v[170:173], v[218:221], v[76:79]
	v_mfma_f32_16x16x32_bf16 v[120:123], v[174:177], v[190:193], v[120:123]
	v_mfma_f32_16x16x32_bf16 v[116:119], v[182:185], v[190:193], v[116:119]
	v_mfma_f32_16x16x32_bf16 v[104:107], v[174:177], v[198:201], v[104:107]
	v_mfma_f32_16x16x32_bf16 v[100:103], v[182:185], v[198:201], v[100:103]
	v_mfma_f32_16x16x32_bf16 v[88:91], v[174:177], v[206:209], v[88:91]
	v_mfma_f32_16x16x32_bf16 v[84:87], v[182:185], v[206:209], v[84:87]
	v_mfma_f32_16x16x32_bf16 v[72:75], v[174:177], v[214:217], v[72:75]
	v_mfma_f32_16x16x32_bf16 v[68:71], v[182:185], v[214:217], v[68:71]
	v_mfma_f32_16x16x32_bf16 v[120:123], v[178:181], v[194:197], v[120:123]
	v_mfma_f32_16x16x32_bf16 v[116:119], v[186:189], v[194:197], v[116:119]
	v_mfma_f32_16x16x32_bf16 v[104:107], v[178:181], v[202:205], v[104:107]
	v_mfma_f32_16x16x32_bf16 v[100:103], v[186:189], v[202:205], v[100:103]
	v_mfma_f32_16x16x32_bf16 v[88:91], v[178:181], v[210:213], v[88:91]
	v_mfma_f32_16x16x32_bf16 v[84:87], v[186:189], v[210:213], v[84:87]
	v_mfma_f32_16x16x32_bf16 v[72:75], v[178:181], v[218:221], v[72:75]
	v_mfma_f32_16x16x32_bf16 v[68:71], v[186:189], v[218:221], v[68:71]
	s_barrier
	s_add_i32 s12, s60, s17
	v_lshl_add_u64 v[144:145], s[8:9], 0, v[134:135]
	s_mov_b32 m0, s12
	ds_read_b128 v[190:193], v163 offset:16384
	ds_read_b128 v[194:197], v163 offset:17408
	ds_read_b128 v[198:201], v163 offset:18432
	ds_read_b128 v[202:205], v163 offset:19456
	ds_read_b128 v[206:209], v163 offset:20480
	ds_read_b128 v[210:213], v163 offset:21504
	ds_read_b128 v[214:217], v163 offset:22528
	ds_read_b128 v[218:221], v163 offset:23552
	global_load_lds_dwordx4 v[144:145], off
	s_add_i32 m0, s12, 0x2000
	s_add_u32 s12, s8, 0x4000
	v_lshl_add_u64 v[144:145], s[8:9], 0, v[138:139]
	s_addc_u32 s13, s9, 0
	s_add_i32 s14, s61, s17
	global_load_lds_dwordx4 v[144:145], off
	v_lshl_add_u64 v[144:145], s[12:13], 0, v[134:135]
	s_mov_b32 m0, s14
	v_lshl_add_u64 v[222:223], s[22:23], 0, v[136:137]
	global_load_lds_dwordx4 v[144:145], off
	v_lshl_add_u64 v[144:145], s[12:13], 0, v[138:139]
	s_add_i32 m0, s14, 0x2000
	s_nop 0
	global_load_lds_dwordx4 v[144:145], off
	v_lshl_add_u64 v[144:145], s[22:23], 0, v[132:133]
	s_mov_b32 m0, s18
	s_nop 0
	global_load_lds_dwordx4 v[144:145], off
	s_mov_b32 m0, s19
	s_nop 0
	global_load_lds_dwordx4 v[222:223], off
	s_waitcnt vmcnt(8)
	s_waitcnt lgkmcnt(0)
	s_barrier
	v_mfma_f32_16x16x32_bf16 v[64:67], v[150:153], v[190:193], v[64:67]
	v_mfma_f32_16x16x32_bf16 v[60:63], v[166:169], v[190:193], v[60:63]
	v_mfma_f32_16x16x32_bf16 v[48:51], v[150:153], v[198:201], v[48:51]
	v_mfma_f32_16x16x32_bf16 v[44:47], v[166:169], v[198:201], v[44:47]
	v_mfma_f32_16x16x32_bf16 v[32:35], v[150:153], v[206:209], v[32:35]
	v_mfma_f32_16x16x32_bf16 v[28:31], v[166:169], v[206:209], v[28:31]
	v_mfma_f32_16x16x32_bf16 v[16:19], v[150:153], v[214:217], v[16:19]
	v_mfma_f32_16x16x32_bf16 v[12:15], v[166:169], v[214:217], v[12:15]
	v_mfma_f32_16x16x32_bf16 v[64:67], v[154:157], v[194:197], v[64:67]
	v_mfma_f32_16x16x32_bf16 v[60:63], v[170:173], v[194:197], v[60:63]
	v_mfma_f32_16x16x32_bf16 v[48:51], v[154:157], v[202:205], v[48:51]
	v_mfma_f32_16x16x32_bf16 v[44:47], v[170:173], v[202:205], v[44:47]
	v_mfma_f32_16x16x32_bf16 v[32:35], v[154:157], v[210:213], v[32:35]
	v_mfma_f32_16x16x32_bf16 v[28:31], v[170:173], v[210:213], v[28:31]
	v_mfma_f32_16x16x32_bf16 v[16:19], v[154:157], v[218:221], v[16:19]
	v_mfma_f32_16x16x32_bf16 v[12:15], v[170:173], v[218:221], v[12:15]
	v_mfma_f32_16x16x32_bf16 v[56:59], v[174:177], v[190:193], v[56:59]
	v_mfma_f32_16x16x32_bf16 v[52:55], v[182:185], v[190:193], v[52:55]
	v_mfma_f32_16x16x32_bf16 v[40:43], v[174:177], v[198:201], v[40:43]
	v_mfma_f32_16x16x32_bf16 v[36:39], v[182:185], v[198:201], v[36:39]
	v_mfma_f32_16x16x32_bf16 v[24:27], v[174:177], v[206:209], v[24:27]
	v_mfma_f32_16x16x32_bf16 v[20:23], v[182:185], v[206:209], v[20:23]
	v_mfma_f32_16x16x32_bf16 v[8:11], v[174:177], v[214:217], v[8:11]
	v_mfma_f32_16x16x32_bf16 v[4:7], v[182:185], v[214:217], v[4:7]
	v_mfma_f32_16x16x32_bf16 v[56:59], v[178:181], v[194:197], v[56:59]
	v_mfma_f32_16x16x32_bf16 v[52:55], v[186:189], v[194:197], v[52:55]
	v_mfma_f32_16x16x32_bf16 v[40:43], v[178:181], v[202:205], v[40:43]
	v_mfma_f32_16x16x32_bf16 v[36:39], v[186:189], v[202:205], v[36:39]
	v_mfma_f32_16x16x32_bf16 v[24:27], v[178:181], v[210:213], v[24:27]
	v_mfma_f32_16x16x32_bf16 v[20:23], v[186:189], v[210:213], v[20:23]
	v_mfma_f32_16x16x32_bf16 v[8:11], v[178:181], v[218:221], v[8:11]
	v_mfma_f32_16x16x32_bf16 v[4:7], v[186:189], v[218:221], v[4:7]
	s_barrier
	s_add_i32 s14, 0, 0x18000
	v_add_u32_e32 v1, s14, v160
	s_add_i32 s66, 0, 0x1c000
	ds_read_b128 v[150:153], v1
	ds_read_b128 v[154:157], v1 offset:1024
	ds_read_b128 v[166:169], v1 offset:2048
	ds_read_b128 v[170:173], v1 offset:3072
	v_add_u32_e32 v1, s66, v160
	ds_read_b128 v[174:177], v1
	ds_read_b128 v[178:181], v1 offset:1024
	ds_read_b128 v[182:185], v1 offset:2048
	ds_read_b128 v[186:189], v1 offset:3072
	s_add_u32 s12, s22, 0x100000
	s_addc_u32 s13, s23, 0
	s_mov_b32 m0, s20
	v_lshl_add_u64 v[224:225], s[12:13], 0, v[132:133]
	ds_read_b128 v[190:193], v163 offset:32768
	ds_read_b128 v[194:197], v163 offset:33792
	ds_read_b128 v[198:201], v163 offset:34816
	ds_read_b128 v[202:205], v163 offset:35840
	ds_read_b128 v[206:209], v163 offset:36864
	ds_read_b128 v[210:213], v163 offset:37888
	ds_read_b128 v[214:217], v163 offset:38912
	ds_read_b128 v[218:221], v163 offset:39936
	global_load_lds_dwordx4 v[224:225], off
	v_lshl_add_u64 v[224:225], s[12:13], 0, v[136:137]
	s_mov_b32 m0, s21
	s_nop 0
	global_load_lds_dwordx4 v[224:225], off
	s_waitcnt vmcnt(8)
	s_waitcnt lgkmcnt(0)
	s_barrier
	v_mfma_f32_16x16x32_bf16 v[128:131], v[150:153], v[190:193], v[128:131]
	v_mfma_f32_16x16x32_bf16 v[124:127], v[166:169], v[190:193], v[124:127]
	v_mfma_f32_16x16x32_bf16 v[112:115], v[150:153], v[198:201], v[112:115]
	v_mfma_f32_16x16x32_bf16 v[108:111], v[166:169], v[198:201], v[108:111]
	v_mfma_f32_16x16x32_bf16 v[96:99], v[150:153], v[206:209], v[96:99]
	v_mfma_f32_16x16x32_bf16 v[92:95], v[166:169], v[206:209], v[92:95]
	v_mfma_f32_16x16x32_bf16 v[80:83], v[150:153], v[214:217], v[80:83]
	v_mfma_f32_16x16x32_bf16 v[76:79], v[166:169], v[214:217], v[76:79]
	v_mfma_f32_16x16x32_bf16 v[128:131], v[154:157], v[194:197], v[128:131]
	v_mfma_f32_16x16x32_bf16 v[124:127], v[170:173], v[194:197], v[124:127]
	v_mfma_f32_16x16x32_bf16 v[112:115], v[154:157], v[202:205], v[112:115]
	v_mfma_f32_16x16x32_bf16 v[108:111], v[170:173], v[202:205], v[108:111]
	v_mfma_f32_16x16x32_bf16 v[96:99], v[154:157], v[210:213], v[96:99]
	v_mfma_f32_16x16x32_bf16 v[92:95], v[170:173], v[210:213], v[92:95]
	v_mfma_f32_16x16x32_bf16 v[80:83], v[154:157], v[218:221], v[80:83]
	v_mfma_f32_16x16x32_bf16 v[76:79], v[170:173], v[218:221], v[76:79]
	v_mfma_f32_16x16x32_bf16 v[120:123], v[174:177], v[190:193], v[120:123]
	v_mfma_f32_16x16x32_bf16 v[116:119], v[182:185], v[190:193], v[116:119]
	v_mfma_f32_16x16x32_bf16 v[104:107], v[174:177], v[198:201], v[104:107]
	v_mfma_f32_16x16x32_bf16 v[100:103], v[182:185], v[198:201], v[100:103]
	v_mfma_f32_16x16x32_bf16 v[88:91], v[174:177], v[206:209], v[88:91]
	v_mfma_f32_16x16x32_bf16 v[84:87], v[182:185], v[206:209], v[84:87]
	v_mfma_f32_16x16x32_bf16 v[72:75], v[174:177], v[214:217], v[72:75]
	v_mfma_f32_16x16x32_bf16 v[68:71], v[182:185], v[214:217], v[68:71]
	v_mfma_f32_16x16x32_bf16 v[120:123], v[178:181], v[194:197], v[120:123]
	v_mfma_f32_16x16x32_bf16 v[116:119], v[186:189], v[194:197], v[116:119]
	v_mfma_f32_16x16x32_bf16 v[104:107], v[178:181], v[202:205], v[104:107]
	v_mfma_f32_16x16x32_bf16 v[100:103], v[186:189], v[202:205], v[100:103]
	v_mfma_f32_16x16x32_bf16 v[88:91], v[178:181], v[210:213], v[88:91]
	v_mfma_f32_16x16x32_bf16 v[84:87], v[186:189], v[210:213], v[84:87]
	v_mfma_f32_16x16x32_bf16 v[72:75], v[178:181], v[218:221], v[72:75]
	v_mfma_f32_16x16x32_bf16 v[68:71], v[186:189], v[218:221], v[68:71]
	s_barrier
	s_add_u32 s12, s8, 0x8000
	s_addc_u32 s13, s9, 0
	s_add_i32 s14, s14, s17
	v_lshl_add_u64 v[224:225], s[12:13], 0, v[134:135]
	s_mov_b32 m0, s14
	ds_read_b128 v[190:193], v163 offset:49152
	ds_read_b128 v[194:197], v163 offset:50176
	ds_read_b128 v[198:201], v163 offset:51200
	ds_read_b128 v[202:205], v163 offset:52224
	ds_read_b128 v[206:209], v163 offset:53248
	ds_read_b128 v[210:213], v163 offset:54272
	ds_read_b128 v[214:217], v163 offset:55296
	ds_read_b128 v[218:221], v163 offset:56320
	global_load_lds_dwordx4 v[224:225], off
	s_add_i32 m0, s14, 0x2000
	s_add_u32 s8, s8, 0xc000
	v_lshl_add_u64 v[224:225], s[12:13], 0, v[138:139]
	s_addc_u32 s9, s9, 0
	s_add_i32 s12, s66, s17
	global_load_lds_dwordx4 v[224:225], off
	v_lshl_add_u64 v[224:225], s[8:9], 0, v[134:135]
	s_mov_b32 m0, s12
	v_lshl_add_u64 v[144:145], v[144:145], 0, s[30:31]
	global_load_lds_dwordx4 v[224:225], off
	v_lshl_add_u64 v[224:225], s[8:9], 0, v[138:139]
	s_add_i32 m0, s12, 0x2000
	s_nop 0
	global_load_lds_dwordx4 v[224:225], off
	s_mov_b32 m0, s51
	s_nop 0
	global_load_lds_dwordx4 v[144:145], off
	v_lshl_add_u64 v[144:145], v[222:223], 0, s[30:31]
	s_mov_b32 m0, s56
	s_nop 0
	global_load_lds_dwordx4 v[144:145], off
	s_waitcnt vmcnt(8)
	s_waitcnt lgkmcnt(0)
	s_barrier
	v_mfma_f32_16x16x32_bf16 v[64:67], v[150:153], v[190:193], v[64:67]
	v_mfma_f32_16x16x32_bf16 v[60:63], v[166:169], v[190:193], v[60:63]
	v_mfma_f32_16x16x32_bf16 v[48:51], v[150:153], v[198:201], v[48:51]
	v_mfma_f32_16x16x32_bf16 v[44:47], v[166:169], v[198:201], v[44:47]
	v_mfma_f32_16x16x32_bf16 v[32:35], v[150:153], v[206:209], v[32:35]
	v_mfma_f32_16x16x32_bf16 v[28:31], v[166:169], v[206:209], v[28:31]
	v_mfma_f32_16x16x32_bf16 v[16:19], v[150:153], v[214:217], v[16:19]
	v_mfma_f32_16x16x32_bf16 v[12:15], v[166:169], v[214:217], v[12:15]
	v_mfma_f32_16x16x32_bf16 v[64:67], v[154:157], v[194:197], v[64:67]
	v_mfma_f32_16x16x32_bf16 v[60:63], v[170:173], v[194:197], v[60:63]
	v_mfma_f32_16x16x32_bf16 v[48:51], v[154:157], v[202:205], v[48:51]
	v_mfma_f32_16x16x32_bf16 v[44:47], v[170:173], v[202:205], v[44:47]
	v_mfma_f32_16x16x32_bf16 v[32:35], v[154:157], v[210:213], v[32:35]
	v_mfma_f32_16x16x32_bf16 v[28:31], v[170:173], v[210:213], v[28:31]
	v_mfma_f32_16x16x32_bf16 v[16:19], v[154:157], v[218:221], v[16:19]
	v_mfma_f32_16x16x32_bf16 v[12:15], v[170:173], v[218:221], v[12:15]
	v_mfma_f32_16x16x32_bf16 v[56:59], v[174:177], v[190:193], v[56:59]
	v_mfma_f32_16x16x32_bf16 v[52:55], v[182:185], v[190:193], v[52:55]
	v_mfma_f32_16x16x32_bf16 v[40:43], v[174:177], v[198:201], v[40:43]
	v_mfma_f32_16x16x32_bf16 v[36:39], v[182:185], v[198:201], v[36:39]
	v_mfma_f32_16x16x32_bf16 v[24:27], v[174:177], v[206:209], v[24:27]
	v_mfma_f32_16x16x32_bf16 v[20:23], v[182:185], v[206:209], v[20:23]
	v_mfma_f32_16x16x32_bf16 v[8:11], v[174:177], v[214:217], v[8:11]
	v_mfma_f32_16x16x32_bf16 v[4:7], v[182:185], v[214:217], v[4:7]
	v_mfma_f32_16x16x32_bf16 v[56:59], v[178:181], v[194:197], v[56:59]
	v_mfma_f32_16x16x32_bf16 v[52:55], v[186:189], v[194:197], v[52:55]
	v_mfma_f32_16x16x32_bf16 v[40:43], v[178:181], v[202:205], v[40:43]
	v_mfma_f32_16x16x32_bf16 v[36:39], v[186:189], v[202:205], v[36:39]
	v_mfma_f32_16x16x32_bf16 v[24:27], v[178:181], v[210:213], v[24:27]
	v_mfma_f32_16x16x32_bf16 v[20:23], v[186:189], v[210:213], v[20:23]
	v_mfma_f32_16x16x32_bf16 v[8:11], v[178:181], v[218:221], v[8:11]
	v_mfma_f32_16x16x32_bf16 v[4:7], v[186:189], v[218:221], v[4:7]
	s_barrier
	s_add_i32 s52, s52, 2
	s_add_u32 s53, s53, 0x10000
	s_addc_u32 s54, s54, 0
	s_add_u32 s55, s55, 0x100
	s_addc_u32 s63, s63, 0
	s_add_u32 s4, s4, 0xffffff00
	s_addc_u32 s5, s5, -1
	v_lshl_add_u64 v[2:3], v[2:3], 0, s[36:37]
	s_cmp_gt_u32 s52, 61
	v_lshl_add_u64 v[148:149], v[148:149], 0, s[36:37]
	s_cbranch_scc0 .LBB0_200
	s_and_b64 vcc, exec, s[34:35]
	s_cbranch_vccz .LBB0_203
	s_barrier

.LBB0_506:
	s_cmp_eq_u32 s22, 0
	s_mov_b32 s22, 0
	s_cbranch_scc1 .LBB0_508
	ds_read_b128 v[2:5], v153
	ds_read_b128 v[6:9], v153 offset:1024
	ds_read_b128 v[10:13], v153 offset:2048
	ds_read_b128 v[14:17], v153 offset:3072
	ds_read_b128 v[18:21], v154
	ds_read_b128 v[22:25], v154 offset:1024
	ds_read_b128 v[26:29], v154 offset:2048
	ds_read_b128 v[30:33], v154 offset:3072
	s_add_u32 s0, s8, 0x10000
	s_addc_u32 s1, s9, 0
	ds_read_b128 v[34:37], v155
	ds_read_b128 v[38:41], v155 offset:1024
	ds_read_b128 v[42:45], v155 offset:2048
	ds_read_b128 v[46:49], v155 offset:3072
	ds_read_b128 v[50:53], v155 offset:4096
	ds_read_b128 v[54:57], v155 offset:5120
	ds_read_b128 v[58:61], v155 offset:6144
	ds_read_b128 v[62:65], v155 offset:7168
	s_waitcnt vmcnt(24)
	s_waitcnt lgkmcnt(0)
	s_barrier
	v_mfma_f32_16x16x32_bf16 v[66:69], v[2:5], v[34:37], 0
	v_mfma_f32_16x16x32_bf16 v[70:73], v[10:13], v[34:37], 0
	v_mfma_f32_16x16x32_bf16 v[74:77], v[2:5], v[42:45], 0
	v_mfma_f32_16x16x32_bf16 v[78:81], v[10:13], v[42:45], 0
	v_mfma_f32_16x16x32_bf16 v[82:85], v[2:5], v[50:53], 0
	v_mfma_f32_16x16x32_bf16 v[86:89], v[10:13], v[50:53], 0
	v_mfma_f32_16x16x32_bf16 v[90:93], v[2:5], v[58:61], 0
	v_mfma_f32_16x16x32_bf16 v[94:97], v[10:13], v[58:61], 0
	v_mfma_f32_16x16x32_bf16 v[66:69], v[6:9], v[38:41], v[66:69]
	v_mfma_f32_16x16x32_bf16 v[70:73], v[14:17], v[38:41], v[70:73]
	v_mfma_f32_16x16x32_bf16 v[74:77], v[6:9], v[46:49], v[74:77]
	v_mfma_f32_16x16x32_bf16 v[78:81], v[14:17], v[46:49], v[78:81]
	v_mfma_f32_16x16x32_bf16 v[82:85], v[6:9], v[54:57], v[82:85]
	v_mfma_f32_16x16x32_bf16 v[86:89], v[14:17], v[54:57], v[86:89]
	v_mfma_f32_16x16x32_bf16 v[90:93], v[6:9], v[62:65], v[90:93]
	v_mfma_f32_16x16x32_bf16 v[104:107], v[14:17], v[62:65], v[94:97]
	v_mfma_f32_16x16x32_bf16 v[94:97], v[18:21], v[34:37], 0
	v_mfma_f32_16x16x32_bf16 v[34:37], v[26:29], v[34:37], 0
	v_mfma_f32_16x16x32_bf16 v[108:111], v[22:25], v[38:41], v[94:97]
	v_mfma_f32_16x16x32_bf16 v[34:37], v[30:33], v[38:41], v[34:37]
	v_mfma_f32_16x16x32_bf16 v[38:41], v[18:21], v[42:45], 0
	v_mfma_f32_16x16x32_bf16 v[42:45], v[26:29], v[42:45], 0
	v_mfma_f32_16x16x32_bf16 v[38:41], v[22:25], v[46:49], v[38:41]
	v_mfma_f32_16x16x32_bf16 v[42:45], v[30:33], v[46:49], v[42:45]
	v_mfma_f32_16x16x32_bf16 v[46:49], v[18:21], v[50:53], 0
	v_mfma_f32_16x16x32_bf16 v[50:53], v[26:29], v[50:53], 0
	v_mfma_f32_16x16x32_bf16 v[46:49], v[22:25], v[54:57], v[46:49]
	v_mfma_f32_16x16x32_bf16 v[50:53], v[30:33], v[54:57], v[50:53]
	v_mfma_f32_16x16x32_bf16 v[54:57], v[18:21], v[58:61], 0
	v_mfma_f32_16x16x32_bf16 v[58:61], v[26:29], v[58:61], 0
	v_mfma_f32_16x16x32_bf16 v[54:57], v[22:25], v[62:65], v[54:57]
	v_mfma_f32_16x16x32_bf16 v[58:61], v[30:33], v[62:65], v[58:61]
	s_barrier
	s_add_i32 s12, s58, s17
	v_lshl_add_u64 v[102:103], s[0:1], 0, v[134:135]
	s_mov_b32 m0, s12
	ds_read_b128 v[62:65], v155 offset:16384
	ds_read_b128 v[94:97], v155 offset:17408
	ds_read_b128 v[98:101], v155 offset:18432
	ds_read_b128 v[112:115], v155 offset:19456
	ds_read_b128 v[116:119], v155 offset:20480
	ds_read_b128 v[120:123], v155 offset:21504
	ds_read_b128 v[124:127], v155 offset:22528
	ds_read_b128 v[128:131], v155 offset:23552
	global_load_lds_dwordx4 v[102:103], off
	s_add_i32 m0, s12, 0x2000
	v_lshl_add_u64 v[102:103], s[0:1], 0, v[138:139]
	s_add_u32 s0, s8, 0x14000
	s_addc_u32 s1, s9, 0
	s_add_i32 s12, s59, s17
	global_load_lds_dwordx4 v[102:103], off
	v_lshl_add_u64 v[102:103], s[0:1], 0, v[134:135]
	s_mov_b32 m0, s12
	v_lshl_add_u64 v[148:149], s[56:57], 0, v[132:133]
	global_load_lds_dwordx4 v[102:103], off
	v_lshl_add_u64 v[102:103], s[0:1], 0, v[138:139]
	s_add_i32 m0, s12, 0x2000
	v_lshl_add_u64 v[144:145], s[56:57], 0, v[136:137]
	global_load_lds_dwordx4 v[102:103], off
	v_lshl_add_u64 v[102:103], v[148:149], 0, s[40:41]
	s_mov_b32 m0, s18
	s_nop 0
	global_load_lds_dwordx4 v[102:103], off
	v_lshl_add_u64 v[102:103], v[144:145], 0, s[40:41]
	s_mov_b32 m0, s19
	s_nop 0
	global_load_lds_dwordx4 v[102:103], off
	s_waitcnt vmcnt(24)
	s_waitcnt lgkmcnt(0)
	s_barrier
	v_mfma_f32_16x16x32_bf16 v[158:161], v[2:5], v[62:65], 0
	v_mfma_f32_16x16x32_bf16 v[166:169], v[2:5], v[98:101], 0
	v_mfma_f32_16x16x32_bf16 v[174:177], v[2:5], v[116:119], 0
	v_mfma_f32_16x16x32_bf16 v[2:5], v[2:5], v[124:127], 0
	v_mfma_f32_16x16x32_bf16 v[158:161], v[6:9], v[94:97], v[158:161]
	v_mfma_f32_16x16x32_bf16 v[166:169], v[6:9], v[112:115], v[166:169]
	v_mfma_f32_16x16x32_bf16 v[174:177], v[6:9], v[120:123], v[174:177]
	v_mfma_f32_16x16x32_bf16 v[2:5], v[6:9], v[128:131], v[2:5]
	v_mfma_f32_16x16x32_bf16 v[6:9], v[10:13], v[124:127], 0
	v_mfma_f32_16x16x32_bf16 v[162:165], v[10:13], v[62:65], 0
	v_mfma_f32_16x16x32_bf16 v[170:173], v[10:13], v[98:101], 0
	v_mfma_f32_16x16x32_bf16 v[178:181], v[10:13], v[116:119], 0
	v_mfma_f32_16x16x32_bf16 v[6:9], v[14:17], v[128:131], v[6:9]
	v_mfma_f32_16x16x32_bf16 v[162:165], v[14:17], v[94:97], v[162:165]
	v_mfma_f32_16x16x32_bf16 v[170:173], v[14:17], v[112:115], v[170:173]
	v_mfma_f32_16x16x32_bf16 v[178:181], v[14:17], v[120:123], v[178:181]
	v_mfma_f32_16x16x32_bf16 v[14:17], v[26:29], v[62:65], 0
	v_mfma_f32_16x16x32_bf16 v[182:185], v[30:33], v[94:97], v[14:17]
	v_mfma_f32_16x16x32_bf16 v[14:17], v[18:21], v[98:101], 0
	v_mfma_f32_16x16x32_bf16 v[186:189], v[22:25], v[112:115], v[14:17]
	v_mfma_f32_16x16x32_bf16 v[14:17], v[26:29], v[98:101], 0
	v_mfma_f32_16x16x32_bf16 v[190:193], v[30:33], v[112:115], v[14:17]
	v_mfma_f32_16x16x32_bf16 v[14:17], v[18:21], v[116:119], 0
	v_mfma_f32_16x16x32_bf16 v[194:197], v[22:25], v[120:123], v[14:17]
	v_mfma_f32_16x16x32_bf16 v[14:17], v[26:29], v[116:119], 0
	v_mfma_f32_16x16x32_bf16 v[10:13], v[18:21], v[62:65], 0
	v_mfma_f32_16x16x32_bf16 v[198:201], v[30:33], v[120:123], v[14:17]
	v_mfma_f32_16x16x32_bf16 v[14:17], v[18:21], v[124:127], 0
	v_mfma_f32_16x16x32_bf16 v[10:13], v[22:25], v[94:97], v[10:13]
	v_mfma_f32_16x16x32_bf16 v[202:205], v[22:25], v[128:131], v[14:17]
	v_mfma_f32_16x16x32_bf16 v[14:17], v[26:29], v[124:127], 0
	v_mfma_f32_16x16x32_bf16 v[206:209], v[30:33], v[128:131], v[14:17]
	s_barrier
	s_add_i32 s12, 0, 0x18000
	v_add_u32_e32 v1, s12, v151
	s_add_i32 s13, 0, 0x1c000
	s_nop 1
	ds_read_b128 v[14:17], v1
	ds_read_b128 v[24:27], v1 offset:1024
	ds_read_b128 v[28:31], v1 offset:2048
	ds_read_b128 v[210:213], v1 offset:3072
	v_add_u32_e32 v1, s13, v151
	ds_read_b128 v[214:217], v1
	ds_read_b128 v[218:221], v1 offset:1024
	ds_read_b128 v[222:225], v1 offset:2048
	ds_read_b128 v[226:229], v1 offset:3072
	s_add_u32 s0, s56, 0x100100
	s_addc_u32 s1, s57, 0
	s_mov_b32 m0, s20
	v_lshl_add_u64 v[22:23], s[0:1], 0, v[132:133]
	ds_read_b128 v[18:21], v155 offset:32768
	ds_read_b128 v[120:123], v155 offset:33792
	ds_read_b128 v[230:233], v155 offset:34816
	ds_read_b128 v[234:237], v155 offset:35840
	ds_read_b128 v[238:241], v155 offset:36864
	ds_read_b128 v[242:245], v155 offset:37888
	ds_read_b128 v[246:249], v155 offset:38912
	ds_read_b128 v[250:253], v155 offset:39936
	global_load_lds_dwordx4 v[22:23], off
	v_lshl_add_u64 v[22:23], s[0:1], 0, v[136:137]
	s_mov_b32 m0, s21
	s_nop 0
	global_load_lds_dwordx4 v[22:23], off
	s_waitcnt vmcnt(24)
	s_waitcnt lgkmcnt(0)
	s_barrier
	v_mfma_f32_16x16x32_bf16 v[62:65], v[14:17], v[18:21], v[66:69]
	v_mfma_f32_16x16x32_bf16 v[128:131], v[24:27], v[120:123], v[62:65]
	v_mfma_f32_16x16x32_bf16 v[62:65], v[28:31], v[18:21], v[70:73]
	v_mfma_f32_16x16x32_bf16 v[116:119], v[210:213], v[120:123], v[62:65]
	v_mfma_f32_16x16x32_bf16 v[62:65], v[14:17], v[230:233], v[74:77]
	v_mfma_f32_16x16x32_bf16 v[112:115], v[24:27], v[234:237], v[62:65]
	v_mfma_f32_16x16x32_bf16 v[62:65], v[28:31], v[230:233], v[78:81]
	v_mfma_f32_16x16x32_bf16 v[100:103], v[210:213], v[234:237], v[62:65]
	v_mfma_f32_16x16x32_bf16 v[62:65], v[14:17], v[238:241], v[82:85]
	v_mfma_f32_16x16x32_bf16 v[96:99], v[24:27], v[242:245], v[62:65]
	v_mfma_f32_16x16x32_bf16 v[62:65], v[28:31], v[238:241], v[86:89]
	v_mfma_f32_16x16x32_bf16 v[84:87], v[210:213], v[242:245], v[62:65]
	v_mfma_f32_16x16x32_bf16 v[62:65], v[14:17], v[246:249], v[90:93]
	v_mfma_f32_16x16x32_bf16 v[80:83], v[24:27], v[250:253], v[62:65]
	v_mfma_f32_16x16x32_bf16 v[62:65], v[28:31], v[246:249], v[104:107]
	v_mfma_f32_16x16x32_bf16 v[64:67], v[210:213], v[250:253], v[62:65]
	v_mfma_f32_16x16x32_bf16 v[68:71], v[214:217], v[18:21], v[108:111]
	v_mfma_f32_16x16x32_bf16 v[18:21], v[222:225], v[18:21], v[34:37]
	v_mfma_f32_16x16x32_bf16 v[124:127], v[218:221], v[120:123], v[68:71]
	v_mfma_f32_16x16x32_bf16 v[120:123], v[226:229], v[120:123], v[18:21]
	v_mfma_f32_16x16x32_bf16 v[18:21], v[214:217], v[230:233], v[38:41]
	v_mfma_f32_16x16x32_bf16 v[108:111], v[218:221], v[234:237], v[18:21]
	v_mfma_f32_16x16x32_bf16 v[18:21], v[222:225], v[230:233], v[42:45]
	v_mfma_f32_16x16x32_bf16 v[104:107], v[226:229], v[234:237], v[18:21]
	v_mfma_f32_16x16x32_bf16 v[18:21], v[214:217], v[238:241], v[46:49]
	v_mfma_f32_16x16x32_bf16 v[92:95], v[218:221], v[242:245], v[18:21]
	v_mfma_f32_16x16x32_bf16 v[18:21], v[222:225], v[238:241], v[50:53]
	v_mfma_f32_16x16x32_bf16 v[88:91], v[226:229], v[242:245], v[18:21]
	v_mfma_f32_16x16x32_bf16 v[18:21], v[214:217], v[246:249], v[54:57]
	v_mfma_f32_16x16x32_bf16 v[72:75], v[218:221], v[250:253], v[18:21]
	v_mfma_f32_16x16x32_bf16 v[18:21], v[222:225], v[246:249], v[58:61]
	v_mfma_f32_16x16x32_bf16 v[68:71], v[226:229], v[250:253], v[18:21]
	s_barrier
	s_add_u32 s0, s8, 0x18000
	s_addc_u32 s1, s9, 0
	s_add_i32 s12, s12, s17
	s_nop 1
	v_lshl_add_u64 v[18:19], s[0:1], 0, v[134:135]
	s_mov_b32 m0, s12
	ds_read_b128 v[40:43], v155 offset:49152
	ds_read_b128 v[44:47], v155 offset:50176
	ds_read_b128 v[230:233], v155 offset:51200
	ds_read_b128 v[234:237], v155 offset:52224
	ds_read_b128 v[238:241], v155 offset:53248
	ds_read_b128 v[242:245], v155 offset:54272
	ds_read_b128 v[246:249], v155 offset:55296
	ds_read_b128 v[250:253], v155 offset:56320
	global_load_lds_dwordx4 v[18:19], off
	s_add_i32 m0, s12, 0x2000
	v_lshl_add_u64 v[18:19], s[0:1], 0, v[138:139]
	s_add_u32 s0, s8, 0x1c000
	s_addc_u32 s1, s9, 0
	s_add_i32 s12, s13, s17
	global_load_lds_dwordx4 v[18:19], off
	v_lshl_add_u64 v[18:19], s[0:1], 0, v[134:135]
	s_mov_b32 m0, s12
	s_nop 0
	global_load_lds_dwordx4 v[18:19], off
	v_lshl_add_u64 v[18:19], s[0:1], 0, v[138:139]
	s_add_i32 m0, s12, 0x2000
	s_nop 0
	global_load_lds_dwordx4 v[18:19], off
	v_lshl_add_u64 v[18:19], v[148:149], 0, s[42:43]
	s_mov_b32 m0, s25
	s_nop 0
	global_load_lds_dwordx4 v[18:19], off
	v_lshl_add_u64 v[18:19], v[144:145], 0, s[42:43]
	s_mov_b32 m0, s33
	s_nop 0
	global_load_lds_dwordx4 v[18:19], off
	s_waitcnt vmcnt(8)
	s_waitcnt lgkmcnt(0)
	s_barrier
	v_mfma_f32_16x16x32_bf16 v[18:21], v[14:17], v[40:43], v[158:161]
	v_mfma_f32_16x16x32_bf16 v[76:79], v[24:27], v[44:47], v[18:21]
	v_mfma_f32_16x16x32_bf16 v[18:21], v[28:31], v[40:43], v[162:165]
	v_mfma_f32_16x16x32_bf16 v[52:55], v[210:213], v[44:47], v[18:21]
	v_mfma_f32_16x16x32_bf16 v[18:21], v[14:17], v[230:233], v[166:169]
	v_mfma_f32_16x16x32_bf16 v[48:51], v[24:27], v[234:237], v[18:21]
	v_mfma_f32_16x16x32_bf16 v[18:21], v[28:31], v[230:233], v[170:173]
	v_mfma_f32_16x16x32_bf16 v[36:39], v[210:213], v[234:237], v[18:21]
	v_mfma_f32_16x16x32_bf16 v[18:21], v[14:17], v[238:241], v[174:177]
	v_mfma_f32_16x16x32_bf16 v[32:35], v[24:27], v[242:245], v[18:21]
	v_mfma_f32_16x16x32_bf16 v[18:21], v[28:31], v[238:241], v[178:181]
	v_mfma_f32_16x16x32_bf16 v[2:5], v[14:17], v[246:249], v[2:5]
	v_mfma_f32_16x16x32_bf16 v[20:23], v[210:213], v[242:245], v[18:21]
	v_mfma_f32_16x16x32_bf16 v[16:19], v[24:27], v[250:253], v[2:5]
	v_mfma_f32_16x16x32_bf16 v[2:5], v[28:31], v[246:249], v[6:9]
	v_mfma_f32_16x16x32_bf16 v[4:7], v[210:213], v[250:253], v[2:5]
	v_mfma_f32_16x16x32_bf16 v[8:11], v[214:217], v[40:43], v[10:13]
	v_mfma_f32_16x16x32_bf16 v[60:63], v[218:221], v[44:47], v[8:11]
	v_mfma_f32_16x16x32_bf16 v[8:11], v[222:225], v[40:43], v[182:185]
	v_mfma_f32_16x16x32_bf16 v[56:59], v[226:229], v[44:47], v[8:11]
	v_mfma_f32_16x16x32_bf16 v[8:11], v[214:217], v[230:233], v[186:189]
	v_mfma_f32_16x16x32_bf16 v[44:47], v[218:221], v[234:237], v[8:11]
	v_mfma_f32_16x16x32_bf16 v[8:11], v[222:225], v[230:233], v[190:193]
	v_mfma_f32_16x16x32_bf16 v[40:43], v[226:229], v[234:237], v[8:11]
	v_mfma_f32_16x16x32_bf16 v[8:11], v[214:217], v[238:241], v[194:197]
	v_mfma_f32_16x16x32_bf16 v[28:31], v[218:221], v[242:245], v[8:11]
	v_mfma_f32_16x16x32_bf16 v[8:11], v[222:225], v[238:241], v[198:201]
	v_mfma_f32_16x16x32_bf16 v[24:27], v[226:229], v[242:245], v[8:11]
	v_mfma_f32_16x16x32_bf16 v[8:11], v[214:217], v[246:249], v[202:205]
	v_mfma_f32_16x16x32_bf16 v[12:15], v[218:221], v[250:253], v[8:11]
	v_mfma_f32_16x16x32_bf16 v[8:11], v[222:225], v[246:249], v[206:209]
	v_mfma_f32_16x16x32_bf16 v[8:11], v[226:229], v[250:253], v[8:11]
	s_barrier
	s_mov_b32 s22, 2
	s_branch .LBB0_509

.LBB0_510:
	ds_read_b128 v[158:161], v153
	ds_read_b128 v[162:165], v153 offset:1024
	ds_read_b128 v[166:169], v153 offset:2048
	ds_read_b128 v[170:173], v153 offset:3072
	ds_read_b128 v[174:177], v154
	ds_read_b128 v[178:181], v154 offset:1024
	ds_read_b128 v[182:185], v154 offset:2048
	ds_read_b128 v[186:189], v154 offset:3072
	s_add_u32 s12, s64, s26
	s_addc_u32 s13, s65, 0
	s_cmp_eq_u32 s26, s8
	s_cselect_b32 s23, s0, s13
	s_cselect_b32 s22, s1, s12
	s_cselect_b32 s57, s45, s63
	s_cselect_b32 s56, s47, s62
	s_add_i32 s67, s18, 0xc000
	v_lshl_add_u64 v[144:145], v[2:3], 0, s[26:27]
	s_mov_b32 m0, s67
	s_add_i32 s66, s18, 0xe000
	ds_read_b128 v[190:193], v155
	ds_read_b128 v[194:197], v155 offset:1024
	ds_read_b128 v[198:201], v155 offset:2048
	ds_read_b128 v[202:205], v155 offset:3072
	ds_read_b128 v[206:209], v155 offset:4096
	ds_read_b128 v[210:213], v155 offset:5120
	ds_read_b128 v[214:217], v155 offset:6144
	ds_read_b128 v[218:221], v155 offset:7168
	global_load_lds_dwordx4 v[144:145], off
	v_lshl_add_u64 v[144:145], v[148:149], 0, s[26:27]
	s_mov_b32 m0, s66
	s_nop 0
	global_load_lds_dwordx4 v[144:145], off
	s_waitcnt vmcnt(8)
	s_waitcnt lgkmcnt(0)
	s_barrier
	v_mfma_f32_16x16x32_bf16 v[128:131], v[158:161], v[190:193], v[128:131]
	v_mfma_f32_16x16x32_bf16 v[116:119], v[166:169], v[190:193], v[116:119]
	v_mfma_f32_16x16x32_bf16 v[112:115], v[158:161], v[198:201], v[112:115]
	v_mfma_f32_16x16x32_bf16 v[100:103], v[166:169], v[198:201], v[100:103]
	v_mfma_f32_16x16x32_bf16 v[96:99], v[158:161], v[206:209], v[96:99]
	v_mfma_f32_16x16x32_bf16 v[84:87], v[166:169], v[206:209], v[84:87]
	v_mfma_f32_16x16x32_bf16 v[80:83], v[158:161], v[214:217], v[80:83]
	v_mfma_f32_16x16x32_bf16 v[64:67], v[166:169], v[214:217], v[64:67]
	v_mfma_f32_16x16x32_bf16 v[128:131], v[162:165], v[194:197], v[128:131]
	v_mfma_f32_16x16x32_bf16 v[116:119], v[170:173], v[194:197], v[116:119]
	v_mfma_f32_16x16x32_bf16 v[112:115], v[162:165], v[202:205], v[112:115]
	v_mfma_f32_16x16x32_bf16 v[100:103], v[170:173], v[202:205], v[100:103]
	v_mfma_f32_16x16x32_bf16 v[96:99], v[162:165], v[210:213], v[96:99]
	v_mfma_f32_16x16x32_bf16 v[84:87], v[170:173], v[210:213], v[84:87]
	v_mfma_f32_16x16x32_bf16 v[80:83], v[162:165], v[218:221], v[80:83]
	v_mfma_f32_16x16x32_bf16 v[64:67], v[170:173], v[218:221], v[64:67]
	v_mfma_f32_16x16x32_bf16 v[124:127], v[174:177], v[190:193], v[124:127]
	v_mfma_f32_16x16x32_bf16 v[120:123], v[182:185], v[190:193], v[120:123]
	v_mfma_f32_16x16x32_bf16 v[108:111], v[174:177], v[198:201], v[108:111]
	v_mfma_f32_16x16x32_bf16 v[104:107], v[182:185], v[198:201], v[104:107]
	v_mfma_f32_16x16x32_bf16 v[92:95], v[174:177], v[206:209], v[92:95]
	v_mfma_f32_16x16x32_bf16 v[88:91], v[182:185], v[206:209], v[88:91]
	v_mfma_f32_16x16x32_bf16 v[72:75], v[174:177], v[214:217], v[72:75]
	v_mfma_f32_16x16x32_bf16 v[68:71], v[182:185], v[214:217], v[68:71]
	v_mfma_f32_16x16x32_bf16 v[124:127], v[178:181], v[194:197], v[124:127]
	v_mfma_f32_16x16x32_bf16 v[120:123], v[186:189], v[194:197], v[120:123]
	v_mfma_f32_16x16x32_bf16 v[108:111], v[178:181], v[202:205], v[108:111]
	v_mfma_f32_16x16x32_bf16 v[104:107], v[186:189], v[202:205], v[104:107]
	v_mfma_f32_16x16x32_bf16 v[92:95], v[178:181], v[210:213], v[92:95]
	v_mfma_f32_16x16x32_bf16 v[88:91], v[186:189], v[210:213], v[88:91]
	v_mfma_f32_16x16x32_bf16 v[72:75], v[178:181], v[218:221], v[72:75]
	v_mfma_f32_16x16x32_bf16 v[68:71], v[186:189], v[218:221], v[68:71]
	s_barrier
	s_add_i32 s12, s58, s17
	v_lshl_add_u64 v[144:145], s[56:57], 0, v[134:135]
	s_mov_b32 m0, s12
	ds_read_b128 v[190:193], v155 offset:16384
	ds_read_b128 v[194:197], v155 offset:17408
	ds_read_b128 v[198:201], v155 offset:18432
	ds_read_b128 v[202:205], v155 offset:19456
	ds_read_b128 v[206:209], v155 offset:20480
	ds_read_b128 v[210:213], v155 offset:21504
	ds_read_b128 v[214:217], v155 offset:22528
	ds_read_b128 v[218:221], v155 offset:23552
	global_load_lds_dwordx4 v[144:145], off
	s_add_i32 m0, s12, 0x2000
	s_add_u32 s12, s56, 0x4000
	v_lshl_add_u64 v[144:145], s[56:57], 0, v[138:139]
	s_addc_u32 s13, s57, 0
	s_add_i32 s14, s59, s17
	global_load_lds_dwordx4 v[144:145], off
	v_lshl_add_u64 v[144:145], s[12:13], 0, v[134:135]
	s_mov_b32 m0, s14
	v_lshl_add_u64 v[222:223], s[22:23], 0, v[136:137]
	global_load_lds_dwordx4 v[144:145], off
	v_lshl_add_u64 v[144:145], s[12:13], 0, v[138:139]
	s_add_i32 m0, s14, 0x2000
	s_nop 0
	global_load_lds_dwordx4 v[144:145], off
	v_lshl_add_u64 v[144:145], s[22:23], 0, v[132:133]
	s_mov_b32 m0, s18
	s_nop 0
	global_load_lds_dwordx4 v[144:145], off
	s_mov_b32 m0, s19
	s_nop 0
	global_load_lds_dwordx4 v[222:223], off
	s_waitcnt vmcnt(8)
	s_waitcnt lgkmcnt(0)
	s_barrier
	v_mfma_f32_16x16x32_bf16 v[76:79], v[158:161], v[190:193], v[76:79]
	v_mfma_f32_16x16x32_bf16 v[52:55], v[166:169], v[190:193], v[52:55]
	v_mfma_f32_16x16x32_bf16 v[48:51], v[158:161], v[198:201], v[48:51]
	v_mfma_f32_16x16x32_bf16 v[36:39], v[166:169], v[198:201], v[36:39]
	v_mfma_f32_16x16x32_bf16 v[32:35], v[158:161], v[206:209], v[32:35]
	v_mfma_f32_16x16x32_bf16 v[20:23], v[166:169], v[206:209], v[20:23]
	v_mfma_f32_16x16x32_bf16 v[16:19], v[158:161], v[214:217], v[16:19]
	v_mfma_f32_16x16x32_bf16 v[4:7], v[166:169], v[214:217], v[4:7]
	v_mfma_f32_16x16x32_bf16 v[76:79], v[162:165], v[194:197], v[76:79]
	v_mfma_f32_16x16x32_bf16 v[52:55], v[170:173], v[194:197], v[52:55]
	v_mfma_f32_16x16x32_bf16 v[48:51], v[162:165], v[202:205], v[48:51]
	v_mfma_f32_16x16x32_bf16 v[36:39], v[170:173], v[202:205], v[36:39]
	v_mfma_f32_16x16x32_bf16 v[32:35], v[162:165], v[210:213], v[32:35]
	v_mfma_f32_16x16x32_bf16 v[20:23], v[170:173], v[210:213], v[20:23]
	v_mfma_f32_16x16x32_bf16 v[16:19], v[162:165], v[218:221], v[16:19]
	v_mfma_f32_16x16x32_bf16 v[4:7], v[170:173], v[218:221], v[4:7]
	v_mfma_f32_16x16x32_bf16 v[60:63], v[174:177], v[190:193], v[60:63]
	v_mfma_f32_16x16x32_bf16 v[56:59], v[182:185], v[190:193], v[56:59]
	v_mfma_f32_16x16x32_bf16 v[44:47], v[174:177], v[198:201], v[44:47]
	v_mfma_f32_16x16x32_bf16 v[40:43], v[182:185], v[198:201], v[40:43]
	v_mfma_f32_16x16x32_bf16 v[28:31], v[174:177], v[206:209], v[28:31]
	v_mfma_f32_16x16x32_bf16 v[24:27], v[182:185], v[206:209], v[24:27]
	v_mfma_f32_16x16x32_bf16 v[12:15], v[174:177], v[214:217], v[12:15]
	v_mfma_f32_16x16x32_bf16 v[8:11], v[182:185], v[214:217], v[8:11]
	v_mfma_f32_16x16x32_bf16 v[60:63], v[178:181], v[194:197], v[60:63]
	v_mfma_f32_16x16x32_bf16 v[56:59], v[186:189], v[194:197], v[56:59]
	v_mfma_f32_16x16x32_bf16 v[44:47], v[178:181], v[202:205], v[44:47]
	v_mfma_f32_16x16x32_bf16 v[40:43], v[186:189], v[202:205], v[40:43]
	v_mfma_f32_16x16x32_bf16 v[28:31], v[178:181], v[210:213], v[28:31]
	v_mfma_f32_16x16x32_bf16 v[24:27], v[186:189], v[210:213], v[24:27]
	v_mfma_f32_16x16x32_bf16 v[12:15], v[178:181], v[218:221], v[12:15]
	v_mfma_f32_16x16x32_bf16 v[8:11], v[186:189], v[218:221], v[8:11]
	s_barrier
	s_add_i32 s14, 0, 0x18000
	v_add_u32_e32 v1, s14, v151
	s_add_i32 s68, 0, 0x1c000
	ds_read_b128 v[158:161], v1
	ds_read_b128 v[162:165], v1 offset:1024
	ds_read_b128 v[166:169], v1 offset:2048
	ds_read_b128 v[170:173], v1 offset:3072
	v_add_u32_e32 v1, s68, v151
	ds_read_b128 v[174:177], v1
	ds_read_b128 v[178:181], v1 offset:1024
	ds_read_b128 v[182:185], v1 offset:2048
	ds_read_b128 v[186:189], v1 offset:3072
	s_add_u32 s12, s22, 0x100000
	s_addc_u32 s13, s23, 0
	s_mov_b32 m0, s20
	v_lshl_add_u64 v[224:225], s[12:13], 0, v[132:133]
	ds_read_b128 v[190:193], v155 offset:32768
	ds_read_b128 v[194:197], v155 offset:33792
	ds_read_b128 v[198:201], v155 offset:34816
	ds_read_b128 v[202:205], v155 offset:35840
	ds_read_b128 v[206:209], v155 offset:36864
	ds_read_b128 v[210:213], v155 offset:37888
	ds_read_b128 v[214:217], v155 offset:38912
	ds_read_b128 v[218:221], v155 offset:39936
	global_load_lds_dwordx4 v[224:225], off
	v_lshl_add_u64 v[224:225], s[12:13], 0, v[136:137]
	s_mov_b32 m0, s21
	s_nop 0
	global_load_lds_dwordx4 v[224:225], off
	s_waitcnt vmcnt(8)
	s_waitcnt lgkmcnt(0)
	s_barrier
	v_mfma_f32_16x16x32_bf16 v[128:131], v[158:161], v[190:193], v[128:131]
	v_mfma_f32_16x16x32_bf16 v[116:119], v[166:169], v[190:193], v[116:119]
	v_mfma_f32_16x16x32_bf16 v[112:115], v[158:161], v[198:201], v[112:115]
	v_mfma_f32_16x16x32_bf16 v[100:103], v[166:169], v[198:201], v[100:103]
	v_mfma_f32_16x16x32_bf16 v[96:99], v[158:161], v[206:209], v[96:99]
	v_mfma_f32_16x16x32_bf16 v[84:87], v[166:169], v[206:209], v[84:87]
	v_mfma_f32_16x16x32_bf16 v[80:83], v[158:161], v[214:217], v[80:83]
	v_mfma_f32_16x16x32_bf16 v[64:67], v[166:169], v[214:217], v[64:67]
	v_mfma_f32_16x16x32_bf16 v[128:131], v[162:165], v[194:197], v[128:131]
	v_mfma_f32_16x16x32_bf16 v[116:119], v[170:173], v[194:197], v[116:119]
	v_mfma_f32_16x16x32_bf16 v[112:115], v[162:165], v[202:205], v[112:115]
	v_mfma_f32_16x16x32_bf16 v[100:103], v[170:173], v[202:205], v[100:103]
	v_mfma_f32_16x16x32_bf16 v[96:99], v[162:165], v[210:213], v[96:99]
	v_mfma_f32_16x16x32_bf16 v[84:87], v[170:173], v[210:213], v[84:87]
	v_mfma_f32_16x16x32_bf16 v[80:83], v[162:165], v[218:221], v[80:83]
	v_mfma_f32_16x16x32_bf16 v[64:67], v[170:173], v[218:221], v[64:67]
	v_mfma_f32_16x16x32_bf16 v[124:127], v[174:177], v[190:193], v[124:127]
	v_mfma_f32_16x16x32_bf16 v[120:123], v[182:185], v[190:193], v[120:123]
	v_mfma_f32_16x16x32_bf16 v[108:111], v[174:177], v[198:201], v[108:111]
	v_mfma_f32_16x16x32_bf16 v[104:107], v[182:185], v[198:201], v[104:107]
	v_mfma_f32_16x16x32_bf16 v[92:95], v[174:177], v[206:209], v[92:95]
	v_mfma_f32_16x16x32_bf16 v[88:91], v[182:185], v[206:209], v[88:91]
	v_mfma_f32_16x16x32_bf16 v[72:75], v[174:177], v[214:217], v[72:75]
	v_mfma_f32_16x16x32_bf16 v[68:71], v[182:185], v[214:217], v[68:71]
	v_mfma_f32_16x16x32_bf16 v[124:127], v[178:181], v[194:197], v[124:127]
	v_mfma_f32_16x16x32_bf16 v[120:123], v[186:189], v[194:197], v[120:123]
	v_mfma_f32_16x16x32_bf16 v[108:111], v[178:181], v[202:205], v[108:111]
	v_mfma_f32_16x16x32_bf16 v[104:107], v[186:189], v[202:205], v[104:107]
	v_mfma_f32_16x16x32_bf16 v[92:95], v[178:181], v[210:213], v[92:95]
	v_mfma_f32_16x16x32_bf16 v[88:91], v[186:189], v[210:213], v[88:91]
	v_mfma_f32_16x16x32_bf16 v[72:75], v[178:181], v[218:221], v[72:75]
	v_mfma_f32_16x16x32_bf16 v[68:71], v[186:189], v[218:221], v[68:71]
	s_barrier
	s_add_u32 s12, s56, 0x8000
	s_addc_u32 s13, s57, 0
	s_add_i32 s14, s14, s17
	v_lshl_add_u64 v[224:225], s[12:13], 0, v[134:135]
	s_mov_b32 m0, s14
	ds_read_b128 v[190:193], v155 offset:49152
	ds_read_b128 v[194:197], v155 offset:50176
	ds_read_b128 v[198:201], v155 offset:51200
	ds_read_b128 v[202:205], v155 offset:52224
	ds_read_b128 v[206:209], v155 offset:53248
	ds_read_b128 v[210:213], v155 offset:54272
	ds_read_b128 v[214:217], v155 offset:55296
	ds_read_b128 v[218:221], v155 offset:56320
	global_load_lds_dwordx4 v[224:225], off
	s_add_i32 m0, s14, 0x2000
	v_lshl_add_u64 v[224:225], s[12:13], 0, v[138:139]
	s_add_u32 s12, s56, 0xc000
	s_addc_u32 s13, s57, 0
	s_add_i32 s14, s68, s17
	global_load_lds_dwordx4 v[224:225], off
	v_lshl_add_u64 v[224:225], s[12:13], 0, v[134:135]
	s_mov_b32 m0, s14
	v_lshl_add_u64 v[144:145], v[144:145], 0, s[36:37]
	global_load_lds_dwordx4 v[224:225], off
	v_lshl_add_u64 v[224:225], s[12:13], 0, v[138:139]
	s_add_i32 m0, s14, 0x2000
	s_nop 0
	global_load_lds_dwordx4 v[224:225], off
	s_mov_b32 m0, s25
	s_nop 0
	global_load_lds_dwordx4 v[144:145], off
	v_lshl_add_u64 v[144:145], v[222:223], 0, s[36:37]
	s_mov_b32 m0, s33
	s_nop 0
	global_load_lds_dwordx4 v[144:145], off
	s_waitcnt vmcnt(8)
	s_waitcnt lgkmcnt(0)
	s_barrier
	v_mfma_f32_16x16x32_bf16 v[76:79], v[158:161], v[190:193], v[76:79]
	v_mfma_f32_16x16x32_bf16 v[52:55], v[166:169], v[190:193], v[52:55]
	v_mfma_f32_16x16x32_bf16 v[48:51], v[158:161], v[198:201], v[48:51]
	v_mfma_f32_16x16x32_bf16 v[36:39], v[166:169], v[198:201], v[36:39]
	v_mfma_f32_16x16x32_bf16 v[32:35], v[158:161], v[206:209], v[32:35]
	v_mfma_f32_16x16x32_bf16 v[20:23], v[166:169], v[206:209], v[20:23]
	v_mfma_f32_16x16x32_bf16 v[16:19], v[158:161], v[214:217], v[16:19]
	v_mfma_f32_16x16x32_bf16 v[4:7], v[166:169], v[214:217], v[4:7]
	v_mfma_f32_16x16x32_bf16 v[76:79], v[162:165], v[194:197], v[76:79]
	v_mfma_f32_16x16x32_bf16 v[52:55], v[170:173], v[194:197], v[52:55]
	v_mfma_f32_16x16x32_bf16 v[48:51], v[162:165], v[202:205], v[48:51]
	v_mfma_f32_16x16x32_bf16 v[36:39], v[170:173], v[202:205], v[36:39]
	v_mfma_f32_16x16x32_bf16 v[32:35], v[162:165], v[210:213], v[32:35]
	v_mfma_f32_16x16x32_bf16 v[20:23], v[170:173], v[210:213], v[20:23]
	v_mfma_f32_16x16x32_bf16 v[16:19], v[162:165], v[218:221], v[16:19]
	v_mfma_f32_16x16x32_bf16 v[4:7], v[170:173], v[218:221], v[4:7]
	v_mfma_f32_16x16x32_bf16 v[60:63], v[174:177], v[190:193], v[60:63]
	v_mfma_f32_16x16x32_bf16 v[56:59], v[182:185], v[190:193], v[56:59]
	v_mfma_f32_16x16x32_bf16 v[44:47], v[174:177], v[198:201], v[44:47]
	v_mfma_f32_16x16x32_bf16 v[40:43], v[182:185], v[198:201], v[40:43]
	v_mfma_f32_16x16x32_bf16 v[28:31], v[174:177], v[206:209], v[28:31]
	v_mfma_f32_16x16x32_bf16 v[24:27], v[182:185], v[206:209], v[24:27]
	v_mfma_f32_16x16x32_bf16 v[12:15], v[174:177], v[214:217], v[12:15]
	v_mfma_f32_16x16x32_bf16 v[8:11], v[182:185], v[214:217], v[8:11]
	v_mfma_f32_16x16x32_bf16 v[60:63], v[178:181], v[194:197], v[60:63]
	v_mfma_f32_16x16x32_bf16 v[56:59], v[186:189], v[194:197], v[56:59]
	v_mfma_f32_16x16x32_bf16 v[44:47], v[178:181], v[202:205], v[44:47]
	v_mfma_f32_16x16x32_bf16 v[40:43], v[186:189], v[202:205], v[40:43]
	v_mfma_f32_16x16x32_bf16 v[28:31], v[178:181], v[210:213], v[28:31]
	v_mfma_f32_16x16x32_bf16 v[24:27], v[186:189], v[210:213], v[24:27]
	v_mfma_f32_16x16x32_bf16 v[12:15], v[178:181], v[218:221], v[12:15]
	v_mfma_f32_16x16x32_bf16 v[8:11], v[186:189], v[218:221], v[8:11]
	s_barrier
	s_add_i32 s61, s61, 2
	s_add_u32 s62, s62, 0x10000
	s_addc_u32 s63, s63, 0
	s_add_u32 s64, s64, 0x100
	s_addc_u32 s65, s65, 0
	s_add_u32 s8, s8, 0xffffff00
	s_addc_u32 s9, s9, -1
	v_lshl_add_u64 v[2:3], v[2:3], 0, s[40:41]
	s_cmp_gt_u32 s61, 61
	v_lshl_add_u64 v[148:149], v[148:149], 0, s[40:41]
	s_cbranch_scc0 .LBB0_510
	s_and_b64 vcc, exec, s[38:39]
	s_cbranch_vccz .LBB0_513
	s_barrier

.LBB0_664:
	s_cmp_lg_u32 s65, 0
	s_mov_b32 s22, 0
	s_cbranch_scc0 .LBB0_666
	ds_read_b128 v[2:5], v155
	ds_read_b128 v[6:9], v155 offset:1024
	ds_read_b128 v[10:13], v155 offset:2048
	ds_read_b128 v[14:17], v155 offset:3072
	ds_read_b128 v[18:21], v156
	ds_read_b128 v[22:25], v156 offset:1024
	ds_read_b128 v[26:29], v156 offset:2048
	ds_read_b128 v[30:33], v156 offset:3072
	s_add_u32 s0, s54, 0x10000
	s_addc_u32 s1, s55, 0
	ds_read_b128 v[34:37], v157
	ds_read_b128 v[38:41], v157 offset:1024
	ds_read_b128 v[42:45], v157 offset:2048
	ds_read_b128 v[46:49], v157 offset:3072
	ds_read_b128 v[50:53], v157 offset:4096
	ds_read_b128 v[54:57], v157 offset:5120
	ds_read_b128 v[58:61], v157 offset:6144
	ds_read_b128 v[62:65], v157 offset:7168
	s_waitcnt vmcnt(16)
	s_waitcnt lgkmcnt(0)
	s_barrier
	v_mfma_f32_16x16x32_bf16 v[86:89], v[10:13], v[50:53], 0
	v_mfma_f32_16x16x32_bf16 v[92:95], v[14:17], v[54:57], v[86:89]
	v_mfma_f32_16x16x32_bf16 v[86:89], v[2:5], v[58:61], 0
	v_mfma_f32_16x16x32_bf16 v[66:69], v[2:5], v[34:37], 0
	v_mfma_f32_16x16x32_bf16 v[70:73], v[10:13], v[34:37], 0
	v_mfma_f32_16x16x32_bf16 v[74:77], v[2:5], v[42:45], 0
	v_mfma_f32_16x16x32_bf16 v[78:81], v[10:13], v[42:45], 0
	v_mfma_f32_16x16x32_bf16 v[82:85], v[2:5], v[50:53], 0
	v_mfma_f32_16x16x32_bf16 v[96:99], v[6:9], v[62:65], v[86:89]
	v_mfma_f32_16x16x32_bf16 v[86:89], v[10:13], v[58:61], 0
	v_mfma_f32_16x16x32_bf16 v[66:69], v[6:9], v[38:41], v[66:69]
	v_mfma_f32_16x16x32_bf16 v[70:73], v[14:17], v[38:41], v[70:73]
	v_mfma_f32_16x16x32_bf16 v[74:77], v[6:9], v[46:49], v[74:77]
	v_mfma_f32_16x16x32_bf16 v[78:81], v[14:17], v[46:49], v[78:81]
	v_mfma_f32_16x16x32_bf16 v[82:85], v[6:9], v[54:57], v[82:85]
	v_mfma_f32_16x16x32_bf16 v[108:111], v[14:17], v[62:65], v[86:89]
	v_mfma_f32_16x16x32_bf16 v[86:89], v[18:21], v[34:37], 0
	v_mfma_f32_16x16x32_bf16 v[34:37], v[26:29], v[34:37], 0
	v_mfma_f32_16x16x32_bf16 v[112:115], v[22:25], v[38:41], v[86:89]
	v_mfma_f32_16x16x32_bf16 v[34:37], v[30:33], v[38:41], v[34:37]
	v_mfma_f32_16x16x32_bf16 v[38:41], v[18:21], v[42:45], 0
	v_mfma_f32_16x16x32_bf16 v[42:45], v[26:29], v[42:45], 0
	v_mfma_f32_16x16x32_bf16 v[38:41], v[22:25], v[46:49], v[38:41]
	v_mfma_f32_16x16x32_bf16 v[42:45], v[30:33], v[46:49], v[42:45]
	v_mfma_f32_16x16x32_bf16 v[46:49], v[18:21], v[50:53], 0
	v_mfma_f32_16x16x32_bf16 v[50:53], v[26:29], v[50:53], 0
	v_mfma_f32_16x16x32_bf16 v[46:49], v[22:25], v[54:57], v[46:49]
	v_mfma_f32_16x16x32_bf16 v[50:53], v[30:33], v[54:57], v[50:53]
	v_mfma_f32_16x16x32_bf16 v[54:57], v[18:21], v[58:61], 0
	v_mfma_f32_16x16x32_bf16 v[58:61], v[26:29], v[58:61], 0
	v_mfma_f32_16x16x32_bf16 v[54:57], v[22:25], v[62:65], v[54:57]
	v_mfma_f32_16x16x32_bf16 v[58:61], v[30:33], v[62:65], v[58:61]
	s_barrier
	s_add_i32 s12, s58, s20
	v_lshl_add_u64 v[90:91], s[0:1], 0, v[134:135]
	s_mov_b32 m0, s12
	ds_read_b128 v[62:65], v157 offset:16384
	ds_read_b128 v[86:89], v157 offset:17408
	ds_read_b128 v[100:103], v157 offset:18432
	ds_read_b128 v[104:107], v157 offset:19456
	ds_read_b128 v[116:119], v157 offset:20480
	ds_read_b128 v[120:123], v157 offset:21504
	ds_read_b128 v[124:127], v157 offset:22528
	ds_read_b128 v[128:131], v157 offset:23552
	global_load_lds_dwordx4 v[90:91], off
	s_add_i32 m0, s12, 0x2000
	v_lshl_add_u64 v[90:91], s[0:1], 0, v[138:139]
	s_add_u32 s0, s54, 0x14000
	s_addc_u32 s1, s55, 0
	s_add_i32 s12, s59, s20
	global_load_lds_dwordx4 v[90:91], off
	v_lshl_add_u64 v[90:91], s[0:1], 0, v[134:135]
	s_mov_b32 m0, s12
	v_lshl_add_u64 v[148:149], s[6:7], 0, v[132:133]
	global_load_lds_dwordx4 v[90:91], off
	v_lshl_add_u64 v[90:91], s[0:1], 0, v[138:139]
	s_add_i32 m0, s12, 0x2000
	v_lshl_add_u64 v[144:145], s[6:7], 0, v[136:137]
	global_load_lds_dwordx4 v[90:91], off
	v_lshl_add_u64 v[90:91], v[148:149], 0, s[38:39]
	s_mov_b32 m0, s21
	s_nop 0
	global_load_lds_dwordx4 v[90:91], off
	v_lshl_add_u64 v[90:91], v[144:145], 0, s[38:39]
	s_mov_b32 m0, s24
	s_nop 0
	global_load_lds_dwordx4 v[90:91], off
	s_waitcnt vmcnt(16)
	s_waitcnt lgkmcnt(0)
	s_barrier
	v_mfma_f32_16x16x32_bf16 v[158:161], v[2:5], v[62:65], 0
	v_mfma_f32_16x16x32_bf16 v[166:169], v[2:5], v[100:103], 0
	v_mfma_f32_16x16x32_bf16 v[174:177], v[2:5], v[116:119], 0
	v_mfma_f32_16x16x32_bf16 v[2:5], v[2:5], v[124:127], 0
	v_mfma_f32_16x16x32_bf16 v[158:161], v[6:9], v[86:89], v[158:161]
	v_mfma_f32_16x16x32_bf16 v[162:165], v[10:13], v[62:65], 0
	v_mfma_f32_16x16x32_bf16 v[166:169], v[6:9], v[104:107], v[166:169]
	v_mfma_f32_16x16x32_bf16 v[170:173], v[10:13], v[100:103], 0
	v_mfma_f32_16x16x32_bf16 v[174:177], v[6:9], v[120:123], v[174:177]
	v_mfma_f32_16x16x32_bf16 v[178:181], v[10:13], v[116:119], 0
	v_mfma_f32_16x16x32_bf16 v[2:5], v[6:9], v[128:131], v[2:5]
	v_mfma_f32_16x16x32_bf16 v[6:9], v[10:13], v[124:127], 0
	v_mfma_f32_16x16x32_bf16 v[162:165], v[14:17], v[86:89], v[162:165]
	v_mfma_f32_16x16x32_bf16 v[170:173], v[14:17], v[104:107], v[170:173]
	v_mfma_f32_16x16x32_bf16 v[178:181], v[14:17], v[120:123], v[178:181]
	v_mfma_f32_16x16x32_bf16 v[12:15], v[14:17], v[128:131], v[6:9]
	v_mfma_f32_16x16x32_bf16 v[6:9], v[18:21], v[62:65], 0
	v_mfma_f32_16x16x32_bf16 v[182:185], v[22:25], v[86:89], v[6:9]
	v_mfma_f32_16x16x32_bf16 v[6:9], v[26:29], v[62:65], 0
	v_mfma_f32_16x16x32_bf16 v[186:189], v[30:33], v[86:89], v[6:9]
	v_mfma_f32_16x16x32_bf16 v[6:9], v[18:21], v[100:103], 0
	v_mfma_f32_16x16x32_bf16 v[190:193], v[22:25], v[104:107], v[6:9]
	v_mfma_f32_16x16x32_bf16 v[6:9], v[26:29], v[100:103], 0
	v_mfma_f32_16x16x32_bf16 v[194:197], v[30:33], v[104:107], v[6:9]
	v_mfma_f32_16x16x32_bf16 v[6:9], v[18:21], v[116:119], 0
	v_mfma_f32_16x16x32_bf16 v[198:201], v[22:25], v[120:123], v[6:9]
	v_mfma_f32_16x16x32_bf16 v[6:9], v[26:29], v[116:119], 0
	v_mfma_f32_16x16x32_bf16 v[202:205], v[30:33], v[120:123], v[6:9]
	v_mfma_f32_16x16x32_bf16 v[6:9], v[18:21], v[124:127], 0
	v_mfma_f32_16x16x32_bf16 v[16:19], v[22:25], v[128:131], v[6:9]
	v_mfma_f32_16x16x32_bf16 v[6:9], v[26:29], v[124:127], 0
	v_mfma_f32_16x16x32_bf16 v[206:209], v[30:33], v[128:131], v[6:9]
	s_barrier
	s_add_i32 s12, 0, 0x18000
	v_add_u32_e32 v1, s12, v152
	s_add_i32 s13, 0, 0x1c000
	s_nop 1
	ds_read_b128 v[6:9], v1
	ds_read_b128 v[28:31], v1 offset:1024
	ds_read_b128 v[62:65], v1 offset:2048
	ds_read_b128 v[210:213], v1 offset:3072
	v_add_u32_e32 v1, s13, v152
	ds_read_b128 v[214:217], v1
	ds_read_b128 v[218:221], v1 offset:1024
	ds_read_b128 v[222:225], v1 offset:2048
	ds_read_b128 v[226:229], v1 offset:3072
	s_add_u32 s0, s6, 0x100100
	s_addc_u32 s1, s7, 0
	s_mov_b32 m0, s25
	v_lshl_add_u64 v[10:11], s[0:1], 0, v[132:133]
	ds_read_b128 v[20:23], v157 offset:32768
	ds_read_b128 v[24:27], v157 offset:33792
	ds_read_b128 v[230:233], v157 offset:34816
	ds_read_b128 v[234:237], v157 offset:35840
	ds_read_b128 v[238:241], v157 offset:36864
	ds_read_b128 v[242:245], v157 offset:37888
	ds_read_b128 v[246:249], v157 offset:38912
	ds_read_b128 v[250:253], v157 offset:39936
	global_load_lds_dwordx4 v[10:11], off
	v_lshl_add_u64 v[10:11], s[0:1], 0, v[136:137]
	s_mov_b32 m0, s33
	s_nop 0
	global_load_lds_dwordx4 v[10:11], off
	s_waitcnt vmcnt(16)
	s_waitcnt lgkmcnt(0)
	s_barrier
	v_mfma_f32_16x16x32_bf16 v[66:69], v[6:9], v[20:23], v[66:69]
	v_mfma_f32_16x16x32_bf16 v[120:123], v[28:31], v[24:27], v[66:69]
	v_mfma_f32_16x16x32_bf16 v[66:69], v[62:65], v[20:23], v[70:73]
	v_mfma_f32_16x16x32_bf16 v[116:119], v[210:213], v[24:27], v[66:69]
	v_mfma_f32_16x16x32_bf16 v[66:69], v[6:9], v[230:233], v[74:77]
	v_mfma_f32_16x16x32_bf16 v[104:107], v[28:31], v[234:237], v[66:69]
	v_mfma_f32_16x16x32_bf16 v[66:69], v[62:65], v[230:233], v[78:81]
	v_mfma_f32_16x16x32_bf16 v[100:103], v[210:213], v[234:237], v[66:69]
	v_mfma_f32_16x16x32_bf16 v[66:69], v[6:9], v[238:241], v[82:85]
	v_mfma_f32_16x16x32_bf16 v[88:91], v[28:31], v[242:245], v[66:69]
	v_mfma_f32_16x16x32_bf16 v[66:69], v[62:65], v[238:241], v[92:95]
	v_mfma_f32_16x16x32_bf16 v[84:87], v[210:213], v[242:245], v[66:69]
	v_mfma_f32_16x16x32_bf16 v[66:69], v[6:9], v[246:249], v[96:99]
	v_mfma_f32_16x16x32_bf16 v[72:75], v[28:31], v[250:253], v[66:69]
	v_mfma_f32_16x16x32_bf16 v[66:69], v[62:65], v[246:249], v[108:111]
	v_mfma_f32_16x16x32_bf16 v[68:71], v[210:213], v[250:253], v[66:69]
	v_mfma_f32_16x16x32_bf16 v[76:79], v[214:217], v[20:23], v[112:115]
	v_mfma_f32_16x16x32_bf16 v[20:23], v[222:225], v[20:23], v[34:37]
	v_mfma_f32_16x16x32_bf16 v[124:127], v[226:229], v[24:27], v[20:23]
	v_mfma_f32_16x16x32_bf16 v[20:23], v[214:217], v[230:233], v[38:41]
	v_mfma_f32_16x16x32_bf16 v[112:115], v[218:221], v[234:237], v[20:23]
	v_mfma_f32_16x16x32_bf16 v[20:23], v[222:225], v[230:233], v[42:45]
	v_mfma_f32_16x16x32_bf16 v[108:111], v[226:229], v[234:237], v[20:23]
	v_mfma_f32_16x16x32_bf16 v[20:23], v[214:217], v[238:241], v[46:49]
	v_mfma_f32_16x16x32_bf16 v[96:99], v[218:221], v[242:245], v[20:23]
	v_mfma_f32_16x16x32_bf16 v[20:23], v[222:225], v[238:241], v[50:53]
	v_mfma_f32_16x16x32_bf16 v[92:95], v[226:229], v[242:245], v[20:23]
	v_mfma_f32_16x16x32_bf16 v[20:23], v[214:217], v[246:249], v[54:57]
	v_mfma_f32_16x16x32_bf16 v[80:83], v[218:221], v[250:253], v[20:23]
	v_mfma_f32_16x16x32_bf16 v[20:23], v[222:225], v[246:249], v[58:61]
	v_mfma_f32_16x16x32_bf16 v[128:131], v[218:221], v[24:27], v[76:79]
	v_mfma_f32_16x16x32_bf16 v[76:79], v[226:229], v[250:253], v[20:23]
	s_barrier
	s_add_u32 s0, s54, 0x18000
	s_addc_u32 s1, s55, 0
	s_add_i32 s12, s12, s20
	v_lshl_add_u64 v[10:11], s[0:1], 0, v[134:135]
	s_mov_b32 m0, s12
	ds_read_b128 v[32:35], v157 offset:49152
	ds_read_b128 v[44:47], v157 offset:50176
	ds_read_b128 v[230:233], v157 offset:51200
	ds_read_b128 v[234:237], v157 offset:52224
	ds_read_b128 v[238:241], v157 offset:53248
	ds_read_b128 v[242:245], v157 offset:54272
	ds_read_b128 v[246:249], v157 offset:55296
	ds_read_b128 v[250:253], v157 offset:56320
	global_load_lds_dwordx4 v[10:11], off
	s_add_i32 m0, s12, 0x2000
	v_lshl_add_u64 v[10:11], s[0:1], 0, v[138:139]
	s_add_u32 s0, s54, 0x1c000
	s_addc_u32 s1, s55, 0
	s_add_i32 s12, s13, s20
	global_load_lds_dwordx4 v[10:11], off
	v_lshl_add_u64 v[10:11], s[0:1], 0, v[134:135]
	s_mov_b32 m0, s12
	s_nop 0
	global_load_lds_dwordx4 v[10:11], off
	v_lshl_add_u64 v[10:11], s[0:1], 0, v[138:139]
	s_add_i32 m0, s12, 0x2000
	s_nop 0
	global_load_lds_dwordx4 v[10:11], off
	v_lshl_add_u64 v[10:11], v[148:149], 0, s[40:41]
	s_mov_b32 m0, s51
	s_nop 0
	global_load_lds_dwordx4 v[10:11], off
	v_lshl_add_u64 v[10:11], v[144:145], 0, s[40:41]
	s_mov_b32 m0, s53
	s_nop 0
	global_load_lds_dwordx4 v[10:11], off
	s_waitcnt vmcnt(8)
	s_waitcnt lgkmcnt(0)
	s_barrier
	v_mfma_f32_16x16x32_bf16 v[20:23], v[6:9], v[32:35], v[158:161]
	v_mfma_f32_16x16x32_bf16 v[56:59], v[28:31], v[44:47], v[20:23]
	v_mfma_f32_16x16x32_bf16 v[20:23], v[62:65], v[32:35], v[162:165]
	v_mfma_f32_16x16x32_bf16 v[52:55], v[210:213], v[44:47], v[20:23]
	v_mfma_f32_16x16x32_bf16 v[20:23], v[6:9], v[230:233], v[166:169]
	v_mfma_f32_16x16x32_bf16 v[40:43], v[28:31], v[234:237], v[20:23]
	v_mfma_f32_16x16x32_bf16 v[20:23], v[62:65], v[230:233], v[170:173]
	v_mfma_f32_16x16x32_bf16 v[36:39], v[210:213], v[234:237], v[20:23]
	v_mfma_f32_16x16x32_bf16 v[20:23], v[6:9], v[238:241], v[174:177]
	v_mfma_f32_16x16x32_bf16 v[2:5], v[6:9], v[246:249], v[2:5]
	v_mfma_f32_16x16x32_bf16 v[24:27], v[28:31], v[242:245], v[20:23]
	v_mfma_f32_16x16x32_bf16 v[20:23], v[62:65], v[238:241], v[178:181]
	v_mfma_f32_16x16x32_bf16 v[8:11], v[28:31], v[250:253], v[2:5]
	v_mfma_f32_16x16x32_bf16 v[2:5], v[62:65], v[246:249], v[12:15]
	v_mfma_f32_16x16x32_bf16 v[20:23], v[210:213], v[242:245], v[20:23]
	v_mfma_f32_16x16x32_bf16 v[4:7], v[210:213], v[250:253], v[2:5]
	v_mfma_f32_16x16x32_bf16 v[12:15], v[214:217], v[32:35], v[182:185]
	v_mfma_f32_16x16x32_bf16 v[64:67], v[218:221], v[44:47], v[12:15]
	v_mfma_f32_16x16x32_bf16 v[12:15], v[222:225], v[32:35], v[186:189]
	v_mfma_f32_16x16x32_bf16 v[60:63], v[226:229], v[44:47], v[12:15]
	v_mfma_f32_16x16x32_bf16 v[12:15], v[214:217], v[230:233], v[190:193]
	v_mfma_f32_16x16x32_bf16 v[48:51], v[218:221], v[234:237], v[12:15]
	v_mfma_f32_16x16x32_bf16 v[12:15], v[222:225], v[230:233], v[194:197]
	v_mfma_f32_16x16x32_bf16 v[44:47], v[226:229], v[234:237], v[12:15]
	v_mfma_f32_16x16x32_bf16 v[12:15], v[214:217], v[238:241], v[198:201]
	v_mfma_f32_16x16x32_bf16 v[32:35], v[218:221], v[242:245], v[12:15]
	v_mfma_f32_16x16x32_bf16 v[12:15], v[222:225], v[238:241], v[202:205]
	v_mfma_f32_16x16x32_bf16 v[28:31], v[226:229], v[242:245], v[12:15]
	v_mfma_f32_16x16x32_bf16 v[12:15], v[214:217], v[246:249], v[16:19]
	v_mfma_f32_16x16x32_bf16 v[16:19], v[218:221], v[250:253], v[12:15]
	v_mfma_f32_16x16x32_bf16 v[12:15], v[222:225], v[246:249], v[206:209]
	v_mfma_f32_16x16x32_bf16 v[12:15], v[226:229], v[250:253], v[12:15]
	s_barrier
	s_mov_b32 s22, 2
	s_branch .LBB0_667

.LBB0_668:
	ds_read_b128 v[158:161], v155
	ds_read_b128 v[162:165], v155 offset:1024
	ds_read_b128 v[166:169], v155 offset:2048
	ds_read_b128 v[170:173], v155 offset:3072
	ds_read_b128 v[174:177], v156
	ds_read_b128 v[178:181], v156 offset:1024
	ds_read_b128 v[182:185], v156 offset:2048
	ds_read_b128 v[186:189], v156 offset:3072
	s_add_u32 s12, s70, s34
	s_addc_u32 s13, s71, 0
	s_cmp_eq_u32 s34, s6
	s_cselect_b32 s23, s0, s13
	s_cselect_b32 s22, s1, s12
	s_cselect_b32 s55, s43, s69
	s_cselect_b32 s54, s66, s68
	s_add_i32 s73, s21, 0xc000
	v_lshl_add_u64 v[144:145], v[2:3], 0, s[34:35]
	s_mov_b32 m0, s73
	s_add_i32 s72, s21, 0xe000
	ds_read_b128 v[190:193], v157
	ds_read_b128 v[194:197], v157 offset:1024
	ds_read_b128 v[198:201], v157 offset:2048
	ds_read_b128 v[202:205], v157 offset:3072
	ds_read_b128 v[206:209], v157 offset:4096
	ds_read_b128 v[210:213], v157 offset:5120
	ds_read_b128 v[214:217], v157 offset:6144
	ds_read_b128 v[218:221], v157 offset:7168
	global_load_lds_dwordx4 v[144:145], off
	v_lshl_add_u64 v[144:145], v[148:149], 0, s[34:35]
	s_mov_b32 m0, s72
	s_nop 0
	global_load_lds_dwordx4 v[144:145], off
	s_waitcnt vmcnt(8)
	s_waitcnt lgkmcnt(0)
	s_barrier
	v_mfma_f32_16x16x32_bf16 v[120:123], v[158:161], v[190:193], v[120:123]
	v_mfma_f32_16x16x32_bf16 v[116:119], v[166:169], v[190:193], v[116:119]
	v_mfma_f32_16x16x32_bf16 v[104:107], v[158:161], v[198:201], v[104:107]
	v_mfma_f32_16x16x32_bf16 v[100:103], v[166:169], v[198:201], v[100:103]
	v_mfma_f32_16x16x32_bf16 v[88:91], v[158:161], v[206:209], v[88:91]
	v_mfma_f32_16x16x32_bf16 v[84:87], v[166:169], v[206:209], v[84:87]
	v_mfma_f32_16x16x32_bf16 v[72:75], v[158:161], v[214:217], v[72:75]
	v_mfma_f32_16x16x32_bf16 v[68:71], v[166:169], v[214:217], v[68:71]
	v_mfma_f32_16x16x32_bf16 v[120:123], v[162:165], v[194:197], v[120:123]
	v_mfma_f32_16x16x32_bf16 v[116:119], v[170:173], v[194:197], v[116:119]
	v_mfma_f32_16x16x32_bf16 v[104:107], v[162:165], v[202:205], v[104:107]
	v_mfma_f32_16x16x32_bf16 v[100:103], v[170:173], v[202:205], v[100:103]
	v_mfma_f32_16x16x32_bf16 v[88:91], v[162:165], v[210:213], v[88:91]
	v_mfma_f32_16x16x32_bf16 v[84:87], v[170:173], v[210:213], v[84:87]
	v_mfma_f32_16x16x32_bf16 v[72:75], v[162:165], v[218:221], v[72:75]
	v_mfma_f32_16x16x32_bf16 v[68:71], v[170:173], v[218:221], v[68:71]
	v_mfma_f32_16x16x32_bf16 v[128:131], v[174:177], v[190:193], v[128:131]
	v_mfma_f32_16x16x32_bf16 v[124:127], v[182:185], v[190:193], v[124:127]
	v_mfma_f32_16x16x32_bf16 v[112:115], v[174:177], v[198:201], v[112:115]
	v_mfma_f32_16x16x32_bf16 v[108:111], v[182:185], v[198:201], v[108:111]
	v_mfma_f32_16x16x32_bf16 v[96:99], v[174:177], v[206:209], v[96:99]
	v_mfma_f32_16x16x32_bf16 v[92:95], v[182:185], v[206:209], v[92:95]
	v_mfma_f32_16x16x32_bf16 v[80:83], v[174:177], v[214:217], v[80:83]
	v_mfma_f32_16x16x32_bf16 v[76:79], v[182:185], v[214:217], v[76:79]
	v_mfma_f32_16x16x32_bf16 v[128:131], v[178:181], v[194:197], v[128:131]
	v_mfma_f32_16x16x32_bf16 v[124:127], v[186:189], v[194:197], v[124:127]
	v_mfma_f32_16x16x32_bf16 v[112:115], v[178:181], v[202:205], v[112:115]
	v_mfma_f32_16x16x32_bf16 v[108:111], v[186:189], v[202:205], v[108:111]
	v_mfma_f32_16x16x32_bf16 v[96:99], v[178:181], v[210:213], v[96:99]
	v_mfma_f32_16x16x32_bf16 v[92:95], v[186:189], v[210:213], v[92:95]
	v_mfma_f32_16x16x32_bf16 v[80:83], v[178:181], v[218:221], v[80:83]
	v_mfma_f32_16x16x32_bf16 v[76:79], v[186:189], v[218:221], v[76:79]
	s_barrier
	s_add_i32 s12, s58, s20
	v_lshl_add_u64 v[144:145], s[54:55], 0, v[134:135]
	s_mov_b32 m0, s12
	ds_read_b128 v[190:193], v157 offset:16384
	ds_read_b128 v[194:197], v157 offset:17408
	ds_read_b128 v[198:201], v157 offset:18432
	ds_read_b128 v[202:205], v157 offset:19456
	ds_read_b128 v[206:209], v157 offset:20480
	ds_read_b128 v[210:213], v157 offset:21504
	ds_read_b128 v[214:217], v157 offset:22528
	ds_read_b128 v[218:221], v157 offset:23552
	global_load_lds_dwordx4 v[144:145], off
	s_add_i32 m0, s12, 0x2000
	s_add_u32 s12, s54, 0x4000
	v_lshl_add_u64 v[144:145], s[54:55], 0, v[138:139]
	s_addc_u32 s13, s55, 0
	s_add_i32 s14, s59, s20
	global_load_lds_dwordx4 v[144:145], off
	v_lshl_add_u64 v[144:145], s[12:13], 0, v[134:135]
	s_mov_b32 m0, s14
	v_lshl_add_u64 v[222:223], s[22:23], 0, v[136:137]
	global_load_lds_dwordx4 v[144:145], off
	v_lshl_add_u64 v[144:145], s[12:13], 0, v[138:139]
	s_add_i32 m0, s14, 0x2000
	s_nop 0
	global_load_lds_dwordx4 v[144:145], off
	v_lshl_add_u64 v[144:145], s[22:23], 0, v[132:133]
	s_mov_b32 m0, s21
	s_nop 0
	global_load_lds_dwordx4 v[144:145], off
	s_mov_b32 m0, s24
	s_nop 0
	global_load_lds_dwordx4 v[222:223], off
	s_waitcnt vmcnt(8)
	s_waitcnt lgkmcnt(0)
	s_barrier
	v_mfma_f32_16x16x32_bf16 v[56:59], v[158:161], v[190:193], v[56:59]
	v_mfma_f32_16x16x32_bf16 v[52:55], v[166:169], v[190:193], v[52:55]
	v_mfma_f32_16x16x32_bf16 v[40:43], v[158:161], v[198:201], v[40:43]
	v_mfma_f32_16x16x32_bf16 v[36:39], v[166:169], v[198:201], v[36:39]
	v_mfma_f32_16x16x32_bf16 v[24:27], v[158:161], v[206:209], v[24:27]
	v_mfma_f32_16x16x32_bf16 v[20:23], v[166:169], v[206:209], v[20:23]
	v_mfma_f32_16x16x32_bf16 v[8:11], v[158:161], v[214:217], v[8:11]
	v_mfma_f32_16x16x32_bf16 v[4:7], v[166:169], v[214:217], v[4:7]
	v_mfma_f32_16x16x32_bf16 v[56:59], v[162:165], v[194:197], v[56:59]
	v_mfma_f32_16x16x32_bf16 v[52:55], v[170:173], v[194:197], v[52:55]
	v_mfma_f32_16x16x32_bf16 v[40:43], v[162:165], v[202:205], v[40:43]
	v_mfma_f32_16x16x32_bf16 v[36:39], v[170:173], v[202:205], v[36:39]
	v_mfma_f32_16x16x32_bf16 v[24:27], v[162:165], v[210:213], v[24:27]
	v_mfma_f32_16x16x32_bf16 v[20:23], v[170:173], v[210:213], v[20:23]
	v_mfma_f32_16x16x32_bf16 v[8:11], v[162:165], v[218:221], v[8:11]
	v_mfma_f32_16x16x32_bf16 v[4:7], v[170:173], v[218:221], v[4:7]
	v_mfma_f32_16x16x32_bf16 v[64:67], v[174:177], v[190:193], v[64:67]
	v_mfma_f32_16x16x32_bf16 v[60:63], v[182:185], v[190:193], v[60:63]
	v_mfma_f32_16x16x32_bf16 v[48:51], v[174:177], v[198:201], v[48:51]
	v_mfma_f32_16x16x32_bf16 v[44:47], v[182:185], v[198:201], v[44:47]
	v_mfma_f32_16x16x32_bf16 v[32:35], v[174:177], v[206:209], v[32:35]
	v_mfma_f32_16x16x32_bf16 v[28:31], v[182:185], v[206:209], v[28:31]
	v_mfma_f32_16x16x32_bf16 v[16:19], v[174:177], v[214:217], v[16:19]
	v_mfma_f32_16x16x32_bf16 v[12:15], v[182:185], v[214:217], v[12:15]
	v_mfma_f32_16x16x32_bf16 v[64:67], v[178:181], v[194:197], v[64:67]
	v_mfma_f32_16x16x32_bf16 v[60:63], v[186:189], v[194:197], v[60:63]
	v_mfma_f32_16x16x32_bf16 v[48:51], v[178:181], v[202:205], v[48:51]
	v_mfma_f32_16x16x32_bf16 v[44:47], v[186:189], v[202:205], v[44:47]
	v_mfma_f32_16x16x32_bf16 v[32:35], v[178:181], v[210:213], v[32:35]
	v_mfma_f32_16x16x32_bf16 v[28:31], v[186:189], v[210:213], v[28:31]
	v_mfma_f32_16x16x32_bf16 v[16:19], v[178:181], v[218:221], v[16:19]
	v_mfma_f32_16x16x32_bf16 v[12:15], v[186:189], v[218:221], v[12:15]
	s_barrier
	s_add_i32 s14, 0, 0x18000
	v_add_u32_e32 v1, s14, v152
	s_add_i32 s74, 0, 0x1c000
	ds_read_b128 v[158:161], v1
	ds_read_b128 v[162:165], v1 offset:1024
	ds_read_b128 v[166:169], v1 offset:2048
	ds_read_b128 v[170:173], v1 offset:3072
	v_add_u32_e32 v1, s74, v152
	ds_read_b128 v[174:177], v1
	ds_read_b128 v[178:181], v1 offset:1024
	ds_read_b128 v[182:185], v1 offset:2048
	ds_read_b128 v[186:189], v1 offset:3072
	s_add_u32 s12, s22, 0x100000
	s_addc_u32 s13, s23, 0
	s_mov_b32 m0, s25
	v_lshl_add_u64 v[224:225], s[12:13], 0, v[132:133]
	ds_read_b128 v[190:193], v157 offset:32768
	ds_read_b128 v[194:197], v157 offset:33792
	ds_read_b128 v[198:201], v157 offset:34816
	ds_read_b128 v[202:205], v157 offset:35840
	ds_read_b128 v[206:209], v157 offset:36864
	ds_read_b128 v[210:213], v157 offset:37888
	ds_read_b128 v[214:217], v157 offset:38912
	ds_read_b128 v[218:221], v157 offset:39936
	global_load_lds_dwordx4 v[224:225], off
	v_lshl_add_u64 v[224:225], s[12:13], 0, v[136:137]
	s_mov_b32 m0, s33
	s_nop 0
	global_load_lds_dwordx4 v[224:225], off
	s_waitcnt vmcnt(8)
	s_waitcnt lgkmcnt(0)
	s_barrier
	v_mfma_f32_16x16x32_bf16 v[120:123], v[158:161], v[190:193], v[120:123]
	v_mfma_f32_16x16x32_bf16 v[116:119], v[166:169], v[190:193], v[116:119]
	v_mfma_f32_16x16x32_bf16 v[104:107], v[158:161], v[198:201], v[104:107]
	v_mfma_f32_16x16x32_bf16 v[100:103], v[166:169], v[198:201], v[100:103]
	v_mfma_f32_16x16x32_bf16 v[88:91], v[158:161], v[206:209], v[88:91]
	v_mfma_f32_16x16x32_bf16 v[84:87], v[166:169], v[206:209], v[84:87]
	v_mfma_f32_16x16x32_bf16 v[72:75], v[158:161], v[214:217], v[72:75]
	v_mfma_f32_16x16x32_bf16 v[68:71], v[166:169], v[214:217], v[68:71]
	v_mfma_f32_16x16x32_bf16 v[120:123], v[162:165], v[194:197], v[120:123]
	v_mfma_f32_16x16x32_bf16 v[116:119], v[170:173], v[194:197], v[116:119]
	v_mfma_f32_16x16x32_bf16 v[104:107], v[162:165], v[202:205], v[104:107]
	v_mfma_f32_16x16x32_bf16 v[100:103], v[170:173], v[202:205], v[100:103]
	v_mfma_f32_16x16x32_bf16 v[88:91], v[162:165], v[210:213], v[88:91]
	v_mfma_f32_16x16x32_bf16 v[84:87], v[170:173], v[210:213], v[84:87]
	v_mfma_f32_16x16x32_bf16 v[72:75], v[162:165], v[218:221], v[72:75]
	v_mfma_f32_16x16x32_bf16 v[68:71], v[170:173], v[218:221], v[68:71]
	v_mfma_f32_16x16x32_bf16 v[128:131], v[174:177], v[190:193], v[128:131]
	v_mfma_f32_16x16x32_bf16 v[124:127], v[182:185], v[190:193], v[124:127]
	v_mfma_f32_16x16x32_bf16 v[112:115], v[174:177], v[198:201], v[112:115]
	v_mfma_f32_16x16x32_bf16 v[108:111], v[182:185], v[198:201], v[108:111]
	v_mfma_f32_16x16x32_bf16 v[96:99], v[174:177], v[206:209], v[96:99]
	v_mfma_f32_16x16x32_bf16 v[92:95], v[182:185], v[206:209], v[92:95]
	v_mfma_f32_16x16x32_bf16 v[80:83], v[174:177], v[214:217], v[80:83]
	v_mfma_f32_16x16x32_bf16 v[76:79], v[182:185], v[214:217], v[76:79]
	v_mfma_f32_16x16x32_bf16 v[128:131], v[178:181], v[194:197], v[128:131]
	v_mfma_f32_16x16x32_bf16 v[124:127], v[186:189], v[194:197], v[124:127]
	v_mfma_f32_16x16x32_bf16 v[112:115], v[178:181], v[202:205], v[112:115]
	v_mfma_f32_16x16x32_bf16 v[108:111], v[186:189], v[202:205], v[108:111]
	v_mfma_f32_16x16x32_bf16 v[96:99], v[178:181], v[210:213], v[96:99]
	v_mfma_f32_16x16x32_bf16 v[92:95], v[186:189], v[210:213], v[92:95]
	v_mfma_f32_16x16x32_bf16 v[80:83], v[178:181], v[218:221], v[80:83]
	v_mfma_f32_16x16x32_bf16 v[76:79], v[186:189], v[218:221], v[76:79]
	s_barrier
	s_add_u32 s12, s54, 0x8000
	s_addc_u32 s13, s55, 0
	s_add_i32 s14, s14, s20
	v_lshl_add_u64 v[224:225], s[12:13], 0, v[134:135]
	s_mov_b32 m0, s14
	ds_read_b128 v[190:193], v157 offset:49152
	ds_read_b128 v[194:197], v157 offset:50176
	ds_read_b128 v[198:201], v157 offset:51200
	ds_read_b128 v[202:205], v157 offset:52224
	ds_read_b128 v[206:209], v157 offset:53248
	ds_read_b128 v[210:213], v157 offset:54272
	ds_read_b128 v[214:217], v157 offset:55296
	ds_read_b128 v[218:221], v157 offset:56320
	global_load_lds_dwordx4 v[224:225], off
	s_add_i32 m0, s14, 0x2000
	v_lshl_add_u64 v[224:225], s[12:13], 0, v[138:139]
	s_add_u32 s12, s54, 0xc000
	s_addc_u32 s13, s55, 0
	s_add_i32 s14, s74, s20
	global_load_lds_dwordx4 v[224:225], off
	v_lshl_add_u64 v[224:225], s[12:13], 0, v[134:135]
	s_mov_b32 m0, s14
	v_lshl_add_u64 v[144:145], v[144:145], 0, s[30:31]
	global_load_lds_dwordx4 v[224:225], off
	v_lshl_add_u64 v[224:225], s[12:13], 0, v[138:139]
	s_add_i32 m0, s14, 0x2000
	s_nop 0
	global_load_lds_dwordx4 v[224:225], off
	s_mov_b32 m0, s51
	s_nop 0
	global_load_lds_dwordx4 v[144:145], off
	v_lshl_add_u64 v[144:145], v[222:223], 0, s[30:31]
	s_mov_b32 m0, s53
	s_nop 0
	global_load_lds_dwordx4 v[144:145], off
	s_waitcnt vmcnt(8)
	s_waitcnt lgkmcnt(0)
	s_barrier
	v_mfma_f32_16x16x32_bf16 v[56:59], v[158:161], v[190:193], v[56:59]
	v_mfma_f32_16x16x32_bf16 v[52:55], v[166:169], v[190:193], v[52:55]
	v_mfma_f32_16x16x32_bf16 v[40:43], v[158:161], v[198:201], v[40:43]
	v_mfma_f32_16x16x32_bf16 v[36:39], v[166:169], v[198:201], v[36:39]
	v_mfma_f32_16x16x32_bf16 v[24:27], v[158:161], v[206:209], v[24:27]
	v_mfma_f32_16x16x32_bf16 v[20:23], v[166:169], v[206:209], v[20:23]
	v_mfma_f32_16x16x32_bf16 v[8:11], v[158:161], v[214:217], v[8:11]
	v_mfma_f32_16x16x32_bf16 v[4:7], v[166:169], v[214:217], v[4:7]
	v_mfma_f32_16x16x32_bf16 v[56:59], v[162:165], v[194:197], v[56:59]
	v_mfma_f32_16x16x32_bf16 v[52:55], v[170:173], v[194:197], v[52:55]
	v_mfma_f32_16x16x32_bf16 v[40:43], v[162:165], v[202:205], v[40:43]
	v_mfma_f32_16x16x32_bf16 v[36:39], v[170:173], v[202:205], v[36:39]
	v_mfma_f32_16x16x32_bf16 v[24:27], v[162:165], v[210:213], v[24:27]
	v_mfma_f32_16x16x32_bf16 v[20:23], v[170:173], v[210:213], v[20:23]
	v_mfma_f32_16x16x32_bf16 v[8:11], v[162:165], v[218:221], v[8:11]
	v_mfma_f32_16x16x32_bf16 v[4:7], v[170:173], v[218:221], v[4:7]
	v_mfma_f32_16x16x32_bf16 v[64:67], v[174:177], v[190:193], v[64:67]
	v_mfma_f32_16x16x32_bf16 v[60:63], v[182:185], v[190:193], v[60:63]
	v_mfma_f32_16x16x32_bf16 v[48:51], v[174:177], v[198:201], v[48:51]
	v_mfma_f32_16x16x32_bf16 v[44:47], v[182:185], v[198:201], v[44:47]
	v_mfma_f32_16x16x32_bf16 v[32:35], v[174:177], v[206:209], v[32:35]
	v_mfma_f32_16x16x32_bf16 v[28:31], v[182:185], v[206:209], v[28:31]
	v_mfma_f32_16x16x32_bf16 v[16:19], v[174:177], v[214:217], v[16:19]
	v_mfma_f32_16x16x32_bf16 v[12:15], v[182:185], v[214:217], v[12:15]
	v_mfma_f32_16x16x32_bf16 v[64:67], v[178:181], v[194:197], v[64:67]
	v_mfma_f32_16x16x32_bf16 v[60:63], v[186:189], v[194:197], v[60:63]
	v_mfma_f32_16x16x32_bf16 v[48:51], v[178:181], v[202:205], v[48:51]
	v_mfma_f32_16x16x32_bf16 v[44:47], v[186:189], v[202:205], v[44:47]
	v_mfma_f32_16x16x32_bf16 v[32:35], v[178:181], v[210:213], v[32:35]
	v_mfma_f32_16x16x32_bf16 v[28:31], v[186:189], v[210:213], v[28:31]
	v_mfma_f32_16x16x32_bf16 v[16:19], v[178:181], v[218:221], v[16:19]
	v_mfma_f32_16x16x32_bf16 v[12:15], v[186:189], v[218:221], v[12:15]
	s_barrier
	s_add_i32 s67, s67, 2
	s_add_u32 s68, s68, 0x10000
	s_addc_u32 s69, s69, 0
	s_add_u32 s70, s70, 0x100
	s_addc_u32 s71, s71, 0
	s_add_u32 s6, s6, 0xffffff00
	s_addc_u32 s7, s7, -1
	v_lshl_add_u64 v[2:3], v[2:3], 0, s[38:39]
	s_cmp_gt_u32 s67, 61
	v_lshl_add_u64 v[148:149], v[148:149], 0, s[38:39]
	s_cbranch_scc0 .LBB0_668
	s_and_b64 vcc, exec, s[36:37]
	s_cbranch_vccnz .LBB0_676
	s_and_b64 s[0:1], s[10:11], s[4:5]
	s_andn2_b64 vcc, exec, s[0:1]
	s_cbranch_vccz .LBB0_677

.LBB0_757:
	ds_read_b128 v[2:5], v153
	ds_read_b128 v[6:9], v153 offset:1024
	ds_read_b128 v[10:13], v153 offset:2048
	ds_read_b128 v[14:17], v153 offset:3072
	ds_read_b128 v[18:21], v154
	ds_read_b128 v[22:25], v154 offset:1024
	ds_read_b128 v[26:29], v154 offset:2048
	ds_read_b128 v[30:33], v154 offset:3072
	s_add_u32 s0, s50, 0x10000
	s_addc_u32 s1, s51, 0
	ds_read_b128 v[34:37], v155
	ds_read_b128 v[38:41], v155 offset:1024
	ds_read_b128 v[42:45], v155 offset:2048
	ds_read_b128 v[46:49], v155 offset:3072
	ds_read_b128 v[50:53], v155 offset:4096
	ds_read_b128 v[54:57], v155 offset:5120
	ds_read_b128 v[58:61], v155 offset:6144
	ds_read_b128 v[62:65], v155 offset:7168
	s_waitcnt vmcnt(24)
	s_waitcnt lgkmcnt(0)
	s_barrier
	v_mfma_f32_16x16x32_bf16 v[66:69], v[2:5], v[34:37], 0
	v_mfma_f32_16x16x32_bf16 v[70:73], v[10:13], v[34:37], 0
	v_mfma_f32_16x16x32_bf16 v[74:77], v[2:5], v[42:45], 0
	v_mfma_f32_16x16x32_bf16 v[78:81], v[10:13], v[42:45], 0
	v_mfma_f32_16x16x32_bf16 v[82:85], v[2:5], v[50:53], 0
	v_mfma_f32_16x16x32_bf16 v[86:89], v[10:13], v[50:53], 0
	v_mfma_f32_16x16x32_bf16 v[90:93], v[2:5], v[58:61], 0
	v_mfma_f32_16x16x32_bf16 v[94:97], v[10:13], v[58:61], 0
	v_mfma_f32_16x16x32_bf16 v[66:69], v[6:9], v[38:41], v[66:69]
	v_mfma_f32_16x16x32_bf16 v[70:73], v[14:17], v[38:41], v[70:73]
	v_mfma_f32_16x16x32_bf16 v[74:77], v[6:9], v[46:49], v[74:77]
	v_mfma_f32_16x16x32_bf16 v[78:81], v[14:17], v[46:49], v[78:81]
	v_mfma_f32_16x16x32_bf16 v[82:85], v[6:9], v[54:57], v[82:85]
	v_mfma_f32_16x16x32_bf16 v[86:89], v[14:17], v[54:57], v[86:89]
	v_mfma_f32_16x16x32_bf16 v[90:93], v[6:9], v[62:65], v[90:93]
	v_mfma_f32_16x16x32_bf16 v[104:107], v[14:17], v[62:65], v[94:97]
	v_mfma_f32_16x16x32_bf16 v[94:97], v[18:21], v[34:37], 0
	v_mfma_f32_16x16x32_bf16 v[34:37], v[26:29], v[34:37], 0
	v_mfma_f32_16x16x32_bf16 v[108:111], v[22:25], v[38:41], v[94:97]
	v_mfma_f32_16x16x32_bf16 v[34:37], v[30:33], v[38:41], v[34:37]
	v_mfma_f32_16x16x32_bf16 v[38:41], v[18:21], v[42:45], 0
	v_mfma_f32_16x16x32_bf16 v[42:45], v[26:29], v[42:45], 0
	v_mfma_f32_16x16x32_bf16 v[38:41], v[22:25], v[46:49], v[38:41]
	v_mfma_f32_16x16x32_bf16 v[42:45], v[30:33], v[46:49], v[42:45]
	v_mfma_f32_16x16x32_bf16 v[46:49], v[18:21], v[50:53], 0
	v_mfma_f32_16x16x32_bf16 v[50:53], v[26:29], v[50:53], 0
	v_mfma_f32_16x16x32_bf16 v[46:49], v[22:25], v[54:57], v[46:49]
	v_mfma_f32_16x16x32_bf16 v[50:53], v[30:33], v[54:57], v[50:53]
	v_mfma_f32_16x16x32_bf16 v[54:57], v[18:21], v[58:61], 0
	v_mfma_f32_16x16x32_bf16 v[58:61], v[26:29], v[58:61], 0
	v_mfma_f32_16x16x32_bf16 v[54:57], v[22:25], v[62:65], v[54:57]
	v_mfma_f32_16x16x32_bf16 v[58:61], v[30:33], v[62:65], v[58:61]
	s_barrier
	s_add_i32 s12, s57, s2
	v_lshl_add_u64 v[102:103], s[0:1], 0, v[134:135]
	s_mov_b32 m0, s12
	ds_read_b128 v[62:65], v155 offset:16384
	ds_read_b128 v[94:97], v155 offset:17408
	ds_read_b128 v[98:101], v155 offset:18432
	ds_read_b128 v[112:115], v155 offset:19456
	ds_read_b128 v[116:119], v155 offset:20480
	ds_read_b128 v[120:123], v155 offset:21504
	ds_read_b128 v[124:127], v155 offset:22528
	ds_read_b128 v[128:131], v155 offset:23552
	global_load_lds_dwordx4 v[102:103], off
	s_add_i32 m0, s12, 0x2000
	v_lshl_add_u64 v[102:103], s[0:1], 0, v[138:139]
	s_add_u32 s0, s50, 0x14000
	s_addc_u32 s1, s51, 0
	s_add_i32 s12, s58, s2
	global_load_lds_dwordx4 v[102:103], off
	v_lshl_add_u64 v[102:103], s[0:1], 0, v[134:135]
	s_mov_b32 m0, s12
	v_lshl_add_u64 v[148:149], s[52:53], 0, v[132:133]
	global_load_lds_dwordx4 v[102:103], off
	v_lshl_add_u64 v[102:103], s[0:1], 0, v[138:139]
	s_add_i32 m0, s12, 0x2000
	v_lshl_add_u64 v[144:145], s[52:53], 0, v[136:137]
	global_load_lds_dwordx4 v[102:103], off
	v_lshl_add_u64 v[102:103], v[148:149], 0, s[44:45]
	s_mov_b32 m0, s19
	s_nop 0
	global_load_lds_dwordx4 v[102:103], off
	v_lshl_add_u64 v[102:103], v[144:145], 0, s[44:45]
	s_mov_b32 m0, s20
	s_nop 0
	global_load_lds_dwordx4 v[102:103], off
	s_waitcnt vmcnt(24)
	s_waitcnt lgkmcnt(0)
	s_barrier
	v_mfma_f32_16x16x32_bf16 v[158:161], v[2:5], v[62:65], 0
	v_mfma_f32_16x16x32_bf16 v[166:169], v[2:5], v[98:101], 0
	v_mfma_f32_16x16x32_bf16 v[174:177], v[2:5], v[116:119], 0
	v_mfma_f32_16x16x32_bf16 v[2:5], v[2:5], v[124:127], 0
	v_mfma_f32_16x16x32_bf16 v[158:161], v[6:9], v[94:97], v[158:161]
	v_mfma_f32_16x16x32_bf16 v[166:169], v[6:9], v[112:115], v[166:169]
	v_mfma_f32_16x16x32_bf16 v[174:177], v[6:9], v[120:123], v[174:177]
	v_mfma_f32_16x16x32_bf16 v[2:5], v[6:9], v[128:131], v[2:5]
	v_mfma_f32_16x16x32_bf16 v[6:9], v[10:13], v[124:127], 0
	v_mfma_f32_16x16x32_bf16 v[162:165], v[10:13], v[62:65], 0
	v_mfma_f32_16x16x32_bf16 v[170:173], v[10:13], v[98:101], 0
	v_mfma_f32_16x16x32_bf16 v[178:181], v[10:13], v[116:119], 0
	v_mfma_f32_16x16x32_bf16 v[6:9], v[14:17], v[128:131], v[6:9]
	v_mfma_f32_16x16x32_bf16 v[162:165], v[14:17], v[94:97], v[162:165]
	v_mfma_f32_16x16x32_bf16 v[170:173], v[14:17], v[112:115], v[170:173]
	v_mfma_f32_16x16x32_bf16 v[178:181], v[14:17], v[120:123], v[178:181]
	v_mfma_f32_16x16x32_bf16 v[14:17], v[26:29], v[62:65], 0
	v_mfma_f32_16x16x32_bf16 v[182:185], v[30:33], v[94:97], v[14:17]
	v_mfma_f32_16x16x32_bf16 v[14:17], v[18:21], v[98:101], 0
	v_mfma_f32_16x16x32_bf16 v[186:189], v[22:25], v[112:115], v[14:17]
	v_mfma_f32_16x16x32_bf16 v[14:17], v[26:29], v[98:101], 0
	v_mfma_f32_16x16x32_bf16 v[190:193], v[30:33], v[112:115], v[14:17]
	v_mfma_f32_16x16x32_bf16 v[14:17], v[18:21], v[116:119], 0
	v_mfma_f32_16x16x32_bf16 v[194:197], v[22:25], v[120:123], v[14:17]
	v_mfma_f32_16x16x32_bf16 v[14:17], v[26:29], v[116:119], 0
	v_mfma_f32_16x16x32_bf16 v[10:13], v[18:21], v[62:65], 0
	v_mfma_f32_16x16x32_bf16 v[198:201], v[30:33], v[120:123], v[14:17]
	v_mfma_f32_16x16x32_bf16 v[14:17], v[18:21], v[124:127], 0
	v_mfma_f32_16x16x32_bf16 v[10:13], v[22:25], v[94:97], v[10:13]
	v_mfma_f32_16x16x32_bf16 v[202:205], v[22:25], v[128:131], v[14:17]
	v_mfma_f32_16x16x32_bf16 v[14:17], v[26:29], v[124:127], 0
	v_mfma_f32_16x16x32_bf16 v[206:209], v[30:33], v[128:131], v[14:17]
	s_barrier
	s_add_i32 s12, 0, 0x18000
	v_add_u32_e32 v1, s12, v151
	s_add_i32 s13, 0, 0x1c000
	s_nop 1
	ds_read_b128 v[14:17], v1
	ds_read_b128 v[24:27], v1 offset:1024
	ds_read_b128 v[28:31], v1 offset:2048
	ds_read_b128 v[210:213], v1 offset:3072
	v_add_u32_e32 v1, s13, v151
	ds_read_b128 v[214:217], v1
	ds_read_b128 v[218:221], v1 offset:1024
	ds_read_b128 v[222:225], v1 offset:2048
	ds_read_b128 v[226:229], v1 offset:3072
	s_add_u32 s0, s52, 0x2b0100
	s_addc_u32 s1, s53, 0
	s_mov_b32 m0, s21
	v_lshl_add_u64 v[22:23], s[0:1], 0, v[132:133]
	ds_read_b128 v[18:21], v155 offset:32768
	ds_read_b128 v[120:123], v155 offset:33792
	ds_read_b128 v[230:233], v155 offset:34816
	ds_read_b128 v[234:237], v155 offset:35840
	ds_read_b128 v[238:241], v155 offset:36864
	ds_read_b128 v[242:245], v155 offset:37888
	ds_read_b128 v[246:249], v155 offset:38912
	ds_read_b128 v[250:253], v155 offset:39936
	global_load_lds_dwordx4 v[22:23], off
	v_lshl_add_u64 v[22:23], s[0:1], 0, v[136:137]
	s_mov_b32 m0, s24
	s_nop 0
	global_load_lds_dwordx4 v[22:23], off
	s_waitcnt vmcnt(24)
	s_waitcnt lgkmcnt(0)
	s_barrier
	v_mfma_f32_16x16x32_bf16 v[62:65], v[14:17], v[18:21], v[66:69]
	v_mfma_f32_16x16x32_bf16 v[128:131], v[24:27], v[120:123], v[62:65]
	v_mfma_f32_16x16x32_bf16 v[62:65], v[28:31], v[18:21], v[70:73]
	v_mfma_f32_16x16x32_bf16 v[116:119], v[210:213], v[120:123], v[62:65]
	v_mfma_f32_16x16x32_bf16 v[62:65], v[14:17], v[230:233], v[74:77]
	v_mfma_f32_16x16x32_bf16 v[112:115], v[24:27], v[234:237], v[62:65]
	v_mfma_f32_16x16x32_bf16 v[62:65], v[28:31], v[230:233], v[78:81]
	v_mfma_f32_16x16x32_bf16 v[100:103], v[210:213], v[234:237], v[62:65]
	v_mfma_f32_16x16x32_bf16 v[62:65], v[14:17], v[238:241], v[82:85]
	v_mfma_f32_16x16x32_bf16 v[96:99], v[24:27], v[242:245], v[62:65]
	v_mfma_f32_16x16x32_bf16 v[62:65], v[28:31], v[238:241], v[86:89]
	v_mfma_f32_16x16x32_bf16 v[84:87], v[210:213], v[242:245], v[62:65]
	v_mfma_f32_16x16x32_bf16 v[62:65], v[14:17], v[246:249], v[90:93]
	v_mfma_f32_16x16x32_bf16 v[80:83], v[24:27], v[250:253], v[62:65]
	v_mfma_f32_16x16x32_bf16 v[62:65], v[28:31], v[246:249], v[104:107]
	v_mfma_f32_16x16x32_bf16 v[64:67], v[210:213], v[250:253], v[62:65]
	v_mfma_f32_16x16x32_bf16 v[68:71], v[214:217], v[18:21], v[108:111]
	v_mfma_f32_16x16x32_bf16 v[18:21], v[222:225], v[18:21], v[34:37]
	v_mfma_f32_16x16x32_bf16 v[124:127], v[218:221], v[120:123], v[68:71]
	v_mfma_f32_16x16x32_bf16 v[120:123], v[226:229], v[120:123], v[18:21]
	v_mfma_f32_16x16x32_bf16 v[18:21], v[214:217], v[230:233], v[38:41]
	v_mfma_f32_16x16x32_bf16 v[108:111], v[218:221], v[234:237], v[18:21]
	v_mfma_f32_16x16x32_bf16 v[18:21], v[222:225], v[230:233], v[42:45]
	v_mfma_f32_16x16x32_bf16 v[104:107], v[226:229], v[234:237], v[18:21]
	v_mfma_f32_16x16x32_bf16 v[18:21], v[214:217], v[238:241], v[46:49]
	v_mfma_f32_16x16x32_bf16 v[92:95], v[218:221], v[242:245], v[18:21]
	v_mfma_f32_16x16x32_bf16 v[18:21], v[222:225], v[238:241], v[50:53]
	v_mfma_f32_16x16x32_bf16 v[88:91], v[226:229], v[242:245], v[18:21]
	v_mfma_f32_16x16x32_bf16 v[18:21], v[214:217], v[246:249], v[54:57]
	v_mfma_f32_16x16x32_bf16 v[72:75], v[218:221], v[250:253], v[18:21]
	v_mfma_f32_16x16x32_bf16 v[18:21], v[222:225], v[246:249], v[58:61]
	v_mfma_f32_16x16x32_bf16 v[68:71], v[226:229], v[250:253], v[18:21]
	s_barrier
	s_add_u32 s0, s50, 0x18000
	s_addc_u32 s1, s51, 0
	s_add_i32 s12, s12, s2
	s_nop 1
	v_lshl_add_u64 v[18:19], s[0:1], 0, v[134:135]
	s_mov_b32 m0, s12
	ds_read_b128 v[40:43], v155 offset:49152
	ds_read_b128 v[44:47], v155 offset:50176
	ds_read_b128 v[230:233], v155 offset:51200
	ds_read_b128 v[234:237], v155 offset:52224
	ds_read_b128 v[238:241], v155 offset:53248
	ds_read_b128 v[242:245], v155 offset:54272
	ds_read_b128 v[246:249], v155 offset:55296
	ds_read_b128 v[250:253], v155 offset:56320
	global_load_lds_dwordx4 v[18:19], off
	s_add_i32 m0, s12, 0x2000
	v_lshl_add_u64 v[18:19], s[0:1], 0, v[138:139]
	s_add_u32 s0, s50, 0x1c000
	s_addc_u32 s1, s51, 0
	s_add_i32 s12, s13, s2
	global_load_lds_dwordx4 v[18:19], off
	v_lshl_add_u64 v[18:19], s[0:1], 0, v[134:135]
	s_mov_b32 m0, s12
	s_nop 0
	global_load_lds_dwordx4 v[18:19], off
	v_lshl_add_u64 v[18:19], s[0:1], 0, v[138:139]
	s_add_i32 m0, s12, 0x2000
	s_nop 0
	global_load_lds_dwordx4 v[18:19], off
	v_lshl_add_u64 v[18:19], v[148:149], 0, s[46:47]
	s_mov_b32 m0, s33
	s_nop 0
	global_load_lds_dwordx4 v[18:19], off
	v_lshl_add_u64 v[18:19], v[144:145], 0, s[46:47]
	s_mov_b32 m0, s54
	s_nop 0
	global_load_lds_dwordx4 v[18:19], off
	s_waitcnt vmcnt(8)
	s_waitcnt lgkmcnt(0)
	s_barrier
	v_mfma_f32_16x16x32_bf16 v[18:21], v[14:17], v[40:43], v[158:161]
	v_mfma_f32_16x16x32_bf16 v[76:79], v[24:27], v[44:47], v[18:21]
	v_mfma_f32_16x16x32_bf16 v[18:21], v[28:31], v[40:43], v[162:165]
	v_mfma_f32_16x16x32_bf16 v[52:55], v[210:213], v[44:47], v[18:21]
	v_mfma_f32_16x16x32_bf16 v[18:21], v[14:17], v[230:233], v[166:169]
	v_mfma_f32_16x16x32_bf16 v[48:51], v[24:27], v[234:237], v[18:21]
	v_mfma_f32_16x16x32_bf16 v[18:21], v[28:31], v[230:233], v[170:173]
	v_mfma_f32_16x16x32_bf16 v[36:39], v[210:213], v[234:237], v[18:21]
	v_mfma_f32_16x16x32_bf16 v[18:21], v[14:17], v[238:241], v[174:177]
	v_mfma_f32_16x16x32_bf16 v[32:35], v[24:27], v[242:245], v[18:21]
	v_mfma_f32_16x16x32_bf16 v[18:21], v[28:31], v[238:241], v[178:181]
	v_mfma_f32_16x16x32_bf16 v[2:5], v[14:17], v[246:249], v[2:5]
	v_mfma_f32_16x16x32_bf16 v[20:23], v[210:213], v[242:245], v[18:21]
	v_mfma_f32_16x16x32_bf16 v[16:19], v[24:27], v[250:253], v[2:5]
	v_mfma_f32_16x16x32_bf16 v[2:5], v[28:31], v[246:249], v[6:9]
	v_mfma_f32_16x16x32_bf16 v[4:7], v[210:213], v[250:253], v[2:5]
	v_mfma_f32_16x16x32_bf16 v[8:11], v[214:217], v[40:43], v[10:13]
	v_mfma_f32_16x16x32_bf16 v[60:63], v[218:221], v[44:47], v[8:11]
	v_mfma_f32_16x16x32_bf16 v[8:11], v[222:225], v[40:43], v[182:185]
	v_mfma_f32_16x16x32_bf16 v[56:59], v[226:229], v[44:47], v[8:11]
	v_mfma_f32_16x16x32_bf16 v[8:11], v[214:217], v[230:233], v[186:189]
	v_mfma_f32_16x16x32_bf16 v[44:47], v[218:221], v[234:237], v[8:11]
	v_mfma_f32_16x16x32_bf16 v[8:11], v[222:225], v[230:233], v[190:193]
	v_mfma_f32_16x16x32_bf16 v[40:43], v[226:229], v[234:237], v[8:11]
	v_mfma_f32_16x16x32_bf16 v[8:11], v[214:217], v[238:241], v[194:197]
	v_mfma_f32_16x16x32_bf16 v[28:31], v[218:221], v[242:245], v[8:11]
	v_mfma_f32_16x16x32_bf16 v[8:11], v[222:225], v[238:241], v[198:201]
	v_mfma_f32_16x16x32_bf16 v[24:27], v[226:229], v[242:245], v[8:11]
	v_mfma_f32_16x16x32_bf16 v[8:11], v[214:217], v[246:249], v[202:205]
	v_mfma_f32_16x16x32_bf16 v[12:15], v[218:221], v[250:253], v[8:11]
	v_mfma_f32_16x16x32_bf16 v[8:11], v[222:225], v[246:249], v[206:209]
	v_mfma_f32_16x16x32_bf16 v[8:11], v[226:229], v[250:253], v[8:11]
	s_barrier
	s_mov_b32 s22, 2
	s_branch .LBB0_761

.LBB0_762:
	ds_read_b128 v[158:161], v153
	ds_read_b128 v[162:165], v153 offset:1024
	ds_read_b128 v[166:169], v153 offset:2048
	ds_read_b128 v[170:173], v153 offset:3072
	ds_read_b128 v[174:177], v154
	ds_read_b128 v[178:181], v154 offset:1024
	ds_read_b128 v[182:185], v154 offset:2048
	ds_read_b128 v[186:189], v154 offset:3072
	s_add_u32 s12, s65, s30
	s_addc_u32 s13, s66, 0
	s_cmp_eq_u32 s30, s50
	s_cselect_b32 s23, s11, s13
	s_cselect_b32 s22, s10, s12
	s_cselect_b32 s53, s49, s64
	s_cselect_b32 s52, s48, s1
	s_add_i32 s68, s19, 0xc000
	v_lshl_add_u64 v[144:145], v[2:3], 0, s[30:31]
	s_mov_b32 m0, s68
	s_add_i32 s67, s19, 0xe000
	ds_read_b128 v[190:193], v155
	ds_read_b128 v[194:197], v155 offset:1024
	ds_read_b128 v[198:201], v155 offset:2048
	ds_read_b128 v[202:205], v155 offset:3072
	ds_read_b128 v[206:209], v155 offset:4096
	ds_read_b128 v[210:213], v155 offset:5120
	ds_read_b128 v[214:217], v155 offset:6144
	ds_read_b128 v[218:221], v155 offset:7168
	global_load_lds_dwordx4 v[144:145], off
	v_lshl_add_u64 v[144:145], v[148:149], 0, s[30:31]
	s_mov_b32 m0, s67
	s_nop 0
	global_load_lds_dwordx4 v[144:145], off
	s_waitcnt vmcnt(8)
	s_waitcnt lgkmcnt(0)
	s_barrier
	v_mfma_f32_16x16x32_bf16 v[128:131], v[158:161], v[190:193], v[128:131]
	v_mfma_f32_16x16x32_bf16 v[116:119], v[166:169], v[190:193], v[116:119]
	v_mfma_f32_16x16x32_bf16 v[112:115], v[158:161], v[198:201], v[112:115]
	v_mfma_f32_16x16x32_bf16 v[100:103], v[166:169], v[198:201], v[100:103]
	v_mfma_f32_16x16x32_bf16 v[96:99], v[158:161], v[206:209], v[96:99]
	v_mfma_f32_16x16x32_bf16 v[84:87], v[166:169], v[206:209], v[84:87]
	v_mfma_f32_16x16x32_bf16 v[80:83], v[158:161], v[214:217], v[80:83]
	v_mfma_f32_16x16x32_bf16 v[64:67], v[166:169], v[214:217], v[64:67]
	v_mfma_f32_16x16x32_bf16 v[128:131], v[162:165], v[194:197], v[128:131]
	v_mfma_f32_16x16x32_bf16 v[116:119], v[170:173], v[194:197], v[116:119]
	v_mfma_f32_16x16x32_bf16 v[112:115], v[162:165], v[202:205], v[112:115]
	v_mfma_f32_16x16x32_bf16 v[100:103], v[170:173], v[202:205], v[100:103]
	v_mfma_f32_16x16x32_bf16 v[96:99], v[162:165], v[210:213], v[96:99]
	v_mfma_f32_16x16x32_bf16 v[84:87], v[170:173], v[210:213], v[84:87]
	v_mfma_f32_16x16x32_bf16 v[80:83], v[162:165], v[218:221], v[80:83]
	v_mfma_f32_16x16x32_bf16 v[64:67], v[170:173], v[218:221], v[64:67]
	v_mfma_f32_16x16x32_bf16 v[124:127], v[174:177], v[190:193], v[124:127]
	v_mfma_f32_16x16x32_bf16 v[120:123], v[182:185], v[190:193], v[120:123]
	v_mfma_f32_16x16x32_bf16 v[108:111], v[174:177], v[198:201], v[108:111]
	v_mfma_f32_16x16x32_bf16 v[104:107], v[182:185], v[198:201], v[104:107]
	v_mfma_f32_16x16x32_bf16 v[92:95], v[174:177], v[206:209], v[92:95]
	v_mfma_f32_16x16x32_bf16 v[88:91], v[182:185], v[206:209], v[88:91]
	v_mfma_f32_16x16x32_bf16 v[72:75], v[174:177], v[214:217], v[72:75]
	v_mfma_f32_16x16x32_bf16 v[68:71], v[182:185], v[214:217], v[68:71]
	v_mfma_f32_16x16x32_bf16 v[124:127], v[178:181], v[194:197], v[124:127]
	v_mfma_f32_16x16x32_bf16 v[120:123], v[186:189], v[194:197], v[120:123]
	v_mfma_f32_16x16x32_bf16 v[108:111], v[178:181], v[202:205], v[108:111]
	v_mfma_f32_16x16x32_bf16 v[104:107], v[186:189], v[202:205], v[104:107]
	v_mfma_f32_16x16x32_bf16 v[92:95], v[178:181], v[210:213], v[92:95]
	v_mfma_f32_16x16x32_bf16 v[88:91], v[186:189], v[210:213], v[88:91]
	v_mfma_f32_16x16x32_bf16 v[72:75], v[178:181], v[218:221], v[72:75]
	v_mfma_f32_16x16x32_bf16 v[68:71], v[186:189], v[218:221], v[68:71]
	s_barrier
	s_add_i32 s12, s57, s2
	v_lshl_add_u64 v[144:145], s[52:53], 0, v[134:135]
	s_mov_b32 m0, s12
	ds_read_b128 v[190:193], v155 offset:16384
	ds_read_b128 v[194:197], v155 offset:17408
	ds_read_b128 v[198:201], v155 offset:18432
	ds_read_b128 v[202:205], v155 offset:19456
	ds_read_b128 v[206:209], v155 offset:20480
	ds_read_b128 v[210:213], v155 offset:21504
	ds_read_b128 v[214:217], v155 offset:22528
	ds_read_b128 v[218:221], v155 offset:23552
	global_load_lds_dwordx4 v[144:145], off
	s_add_i32 m0, s12, 0x2000
	s_add_u32 s12, s52, 0x4000
	v_lshl_add_u64 v[144:145], s[52:53], 0, v[138:139]
	s_addc_u32 s13, s53, 0
	s_add_i32 s14, s58, s2
	global_load_lds_dwordx4 v[144:145], off
	v_lshl_add_u64 v[144:145], s[12:13], 0, v[134:135]
	s_mov_b32 m0, s14
	v_lshl_add_u64 v[222:223], s[22:23], 0, v[136:137]
	global_load_lds_dwordx4 v[144:145], off
	v_lshl_add_u64 v[144:145], s[12:13], 0, v[138:139]
	s_add_i32 m0, s14, 0x2000
	s_nop 0
	global_load_lds_dwordx4 v[144:145], off
	v_lshl_add_u64 v[144:145], s[22:23], 0, v[132:133]
	s_mov_b32 m0, s19
	s_nop 0
	global_load_lds_dwordx4 v[144:145], off
	s_mov_b32 m0, s20
	s_nop 0
	global_load_lds_dwordx4 v[222:223], off
	s_waitcnt vmcnt(8)
	s_waitcnt lgkmcnt(0)
	s_barrier
	v_mfma_f32_16x16x32_bf16 v[76:79], v[158:161], v[190:193], v[76:79]
	v_mfma_f32_16x16x32_bf16 v[52:55], v[166:169], v[190:193], v[52:55]
	v_mfma_f32_16x16x32_bf16 v[48:51], v[158:161], v[198:201], v[48:51]
	v_mfma_f32_16x16x32_bf16 v[36:39], v[166:169], v[198:201], v[36:39]
	v_mfma_f32_16x16x32_bf16 v[32:35], v[158:161], v[206:209], v[32:35]
	v_mfma_f32_16x16x32_bf16 v[20:23], v[166:169], v[206:209], v[20:23]
	v_mfma_f32_16x16x32_bf16 v[16:19], v[158:161], v[214:217], v[16:19]
	v_mfma_f32_16x16x32_bf16 v[4:7], v[166:169], v[214:217], v[4:7]
	v_mfma_f32_16x16x32_bf16 v[76:79], v[162:165], v[194:197], v[76:79]
	v_mfma_f32_16x16x32_bf16 v[52:55], v[170:173], v[194:197], v[52:55]
	v_mfma_f32_16x16x32_bf16 v[48:51], v[162:165], v[202:205], v[48:51]
	v_mfma_f32_16x16x32_bf16 v[36:39], v[170:173], v[202:205], v[36:39]
	v_mfma_f32_16x16x32_bf16 v[32:35], v[162:165], v[210:213], v[32:35]
	v_mfma_f32_16x16x32_bf16 v[20:23], v[170:173], v[210:213], v[20:23]
	v_mfma_f32_16x16x32_bf16 v[16:19], v[162:165], v[218:221], v[16:19]
	v_mfma_f32_16x16x32_bf16 v[4:7], v[170:173], v[218:221], v[4:7]
	v_mfma_f32_16x16x32_bf16 v[60:63], v[174:177], v[190:193], v[60:63]
	v_mfma_f32_16x16x32_bf16 v[56:59], v[182:185], v[190:193], v[56:59]
	v_mfma_f32_16x16x32_bf16 v[44:47], v[174:177], v[198:201], v[44:47]
	v_mfma_f32_16x16x32_bf16 v[40:43], v[182:185], v[198:201], v[40:43]
	v_mfma_f32_16x16x32_bf16 v[28:31], v[174:177], v[206:209], v[28:31]
	v_mfma_f32_16x16x32_bf16 v[24:27], v[182:185], v[206:209], v[24:27]
	v_mfma_f32_16x16x32_bf16 v[12:15], v[174:177], v[214:217], v[12:15]
	v_mfma_f32_16x16x32_bf16 v[8:11], v[182:185], v[214:217], v[8:11]
	v_mfma_f32_16x16x32_bf16 v[60:63], v[178:181], v[194:197], v[60:63]
	v_mfma_f32_16x16x32_bf16 v[56:59], v[186:189], v[194:197], v[56:59]
	v_mfma_f32_16x16x32_bf16 v[44:47], v[178:181], v[202:205], v[44:47]
	v_mfma_f32_16x16x32_bf16 v[40:43], v[186:189], v[202:205], v[40:43]
	v_mfma_f32_16x16x32_bf16 v[28:31], v[178:181], v[210:213], v[28:31]
	v_mfma_f32_16x16x32_bf16 v[24:27], v[186:189], v[210:213], v[24:27]
	v_mfma_f32_16x16x32_bf16 v[12:15], v[178:181], v[218:221], v[12:15]
	v_mfma_f32_16x16x32_bf16 v[8:11], v[186:189], v[218:221], v[8:11]
	s_barrier
	s_add_i32 s14, 0, 0x18000
	v_add_u32_e32 v1, s14, v151
	s_add_i32 s69, 0, 0x1c000
	ds_read_b128 v[158:161], v1
	ds_read_b128 v[162:165], v1 offset:1024
	ds_read_b128 v[166:169], v1 offset:2048
	ds_read_b128 v[170:173], v1 offset:3072
	v_add_u32_e32 v1, s69, v151
	ds_read_b128 v[174:177], v1
	ds_read_b128 v[178:181], v1 offset:1024
	ds_read_b128 v[182:185], v1 offset:2048
	ds_read_b128 v[186:189], v1 offset:3072
	s_add_u32 s12, s22, 0x2b0000
	s_addc_u32 s13, s23, 0
	s_mov_b32 m0, s21
	v_lshl_add_u64 v[224:225], s[12:13], 0, v[132:133]
	ds_read_b128 v[190:193], v155 offset:32768
	ds_read_b128 v[194:197], v155 offset:33792
	ds_read_b128 v[198:201], v155 offset:34816
	ds_read_b128 v[202:205], v155 offset:35840
	ds_read_b128 v[206:209], v155 offset:36864
	ds_read_b128 v[210:213], v155 offset:37888
	ds_read_b128 v[214:217], v155 offset:38912
	ds_read_b128 v[218:221], v155 offset:39936
	global_load_lds_dwordx4 v[224:225], off
	v_lshl_add_u64 v[224:225], s[12:13], 0, v[136:137]
	s_mov_b32 m0, s24
	s_nop 0
	global_load_lds_dwordx4 v[224:225], off
	s_waitcnt vmcnt(8)
	s_waitcnt lgkmcnt(0)
	s_barrier
	v_mfma_f32_16x16x32_bf16 v[128:131], v[158:161], v[190:193], v[128:131]
	v_mfma_f32_16x16x32_bf16 v[116:119], v[166:169], v[190:193], v[116:119]
	v_mfma_f32_16x16x32_bf16 v[112:115], v[158:161], v[198:201], v[112:115]
	v_mfma_f32_16x16x32_bf16 v[100:103], v[166:169], v[198:201], v[100:103]
	v_mfma_f32_16x16x32_bf16 v[96:99], v[158:161], v[206:209], v[96:99]
	v_mfma_f32_16x16x32_bf16 v[84:87], v[166:169], v[206:209], v[84:87]
	v_mfma_f32_16x16x32_bf16 v[80:83], v[158:161], v[214:217], v[80:83]
	v_mfma_f32_16x16x32_bf16 v[64:67], v[166:169], v[214:217], v[64:67]
	v_mfma_f32_16x16x32_bf16 v[128:131], v[162:165], v[194:197], v[128:131]
	v_mfma_f32_16x16x32_bf16 v[116:119], v[170:173], v[194:197], v[116:119]
	v_mfma_f32_16x16x32_bf16 v[112:115], v[162:165], v[202:205], v[112:115]
	v_mfma_f32_16x16x32_bf16 v[100:103], v[170:173], v[202:205], v[100:103]
	v_mfma_f32_16x16x32_bf16 v[96:99], v[162:165], v[210:213], v[96:99]
	v_mfma_f32_16x16x32_bf16 v[84:87], v[170:173], v[210:213], v[84:87]
	v_mfma_f32_16x16x32_bf16 v[80:83], v[162:165], v[218:221], v[80:83]
	v_mfma_f32_16x16x32_bf16 v[64:67], v[170:173], v[218:221], v[64:67]
	v_mfma_f32_16x16x32_bf16 v[124:127], v[174:177], v[190:193], v[124:127]
	v_mfma_f32_16x16x32_bf16 v[120:123], v[182:185], v[190:193], v[120:123]
	v_mfma_f32_16x16x32_bf16 v[108:111], v[174:177], v[198:201], v[108:111]
	v_mfma_f32_16x16x32_bf16 v[104:107], v[182:185], v[198:201], v[104:107]
	v_mfma_f32_16x16x32_bf16 v[92:95], v[174:177], v[206:209], v[92:95]
	v_mfma_f32_16x16x32_bf16 v[88:91], v[182:185], v[206:209], v[88:91]
	v_mfma_f32_16x16x32_bf16 v[72:75], v[174:177], v[214:217], v[72:75]
	v_mfma_f32_16x16x32_bf16 v[68:71], v[182:185], v[214:217], v[68:71]
	v_mfma_f32_16x16x32_bf16 v[124:127], v[178:181], v[194:197], v[124:127]
	v_mfma_f32_16x16x32_bf16 v[120:123], v[186:189], v[194:197], v[120:123]
	v_mfma_f32_16x16x32_bf16 v[108:111], v[178:181], v[202:205], v[108:111]
	v_mfma_f32_16x16x32_bf16 v[104:107], v[186:189], v[202:205], v[104:107]
	v_mfma_f32_16x16x32_bf16 v[92:95], v[178:181], v[210:213], v[92:95]
	v_mfma_f32_16x16x32_bf16 v[88:91], v[186:189], v[210:213], v[88:91]
	v_mfma_f32_16x16x32_bf16 v[72:75], v[178:181], v[218:221], v[72:75]
	v_mfma_f32_16x16x32_bf16 v[68:71], v[186:189], v[218:221], v[68:71]
	s_barrier
	s_add_u32 s12, s52, 0x8000
	s_addc_u32 s13, s53, 0
	s_add_i32 s14, s14, s2
	v_lshl_add_u64 v[224:225], s[12:13], 0, v[134:135]
	s_mov_b32 m0, s14
	ds_read_b128 v[190:193], v155 offset:49152
	ds_read_b128 v[194:197], v155 offset:50176
	ds_read_b128 v[198:201], v155 offset:51200
	ds_read_b128 v[202:205], v155 offset:52224
	ds_read_b128 v[206:209], v155 offset:53248
	ds_read_b128 v[210:213], v155 offset:54272
	ds_read_b128 v[214:217], v155 offset:55296
	ds_read_b128 v[218:221], v155 offset:56320
	global_load_lds_dwordx4 v[224:225], off
	s_add_i32 m0, s14, 0x2000
	v_lshl_add_u64 v[224:225], s[12:13], 0, v[138:139]
	s_add_u32 s12, s52, 0xc000
	s_addc_u32 s13, s53, 0
	s_add_i32 s14, s69, s2
	global_load_lds_dwordx4 v[224:225], off
	v_lshl_add_u64 v[224:225], s[12:13], 0, v[134:135]
	s_mov_b32 m0, s14
	v_lshl_add_u64 v[144:145], v[144:145], 0, s[40:41]
	global_load_lds_dwordx4 v[224:225], off
	v_lshl_add_u64 v[224:225], s[12:13], 0, v[138:139]
	s_add_i32 m0, s14, 0x2000
	s_nop 0
	global_load_lds_dwordx4 v[224:225], off
	s_mov_b32 m0, s33
	s_nop 0
	global_load_lds_dwordx4 v[144:145], off
	v_lshl_add_u64 v[144:145], v[222:223], 0, s[40:41]
	s_mov_b32 m0, s54
	s_nop 0
	global_load_lds_dwordx4 v[144:145], off
	s_waitcnt vmcnt(8)
	s_waitcnt lgkmcnt(0)
	s_barrier
	v_mfma_f32_16x16x32_bf16 v[76:79], v[158:161], v[190:193], v[76:79]
	v_mfma_f32_16x16x32_bf16 v[52:55], v[166:169], v[190:193], v[52:55]
	v_mfma_f32_16x16x32_bf16 v[48:51], v[158:161], v[198:201], v[48:51]
	v_mfma_f32_16x16x32_bf16 v[36:39], v[166:169], v[198:201], v[36:39]
	v_mfma_f32_16x16x32_bf16 v[32:35], v[158:161], v[206:209], v[32:35]
	v_mfma_f32_16x16x32_bf16 v[20:23], v[166:169], v[206:209], v[20:23]
	v_mfma_f32_16x16x32_bf16 v[16:19], v[158:161], v[214:217], v[16:19]
	v_mfma_f32_16x16x32_bf16 v[4:7], v[166:169], v[214:217], v[4:7]
	v_mfma_f32_16x16x32_bf16 v[76:79], v[162:165], v[194:197], v[76:79]
	v_mfma_f32_16x16x32_bf16 v[52:55], v[170:173], v[194:197], v[52:55]
	v_mfma_f32_16x16x32_bf16 v[48:51], v[162:165], v[202:205], v[48:51]
	v_mfma_f32_16x16x32_bf16 v[36:39], v[170:173], v[202:205], v[36:39]
	v_mfma_f32_16x16x32_bf16 v[32:35], v[162:165], v[210:213], v[32:35]
	v_mfma_f32_16x16x32_bf16 v[20:23], v[170:173], v[210:213], v[20:23]
	v_mfma_f32_16x16x32_bf16 v[16:19], v[162:165], v[218:221], v[16:19]
	v_mfma_f32_16x16x32_bf16 v[4:7], v[170:173], v[218:221], v[4:7]
	v_mfma_f32_16x16x32_bf16 v[60:63], v[174:177], v[190:193], v[60:63]
	v_mfma_f32_16x16x32_bf16 v[56:59], v[182:185], v[190:193], v[56:59]
	v_mfma_f32_16x16x32_bf16 v[44:47], v[174:177], v[198:201], v[44:47]
	v_mfma_f32_16x16x32_bf16 v[40:43], v[182:185], v[198:201], v[40:43]
	v_mfma_f32_16x16x32_bf16 v[28:31], v[174:177], v[206:209], v[28:31]
	v_mfma_f32_16x16x32_bf16 v[24:27], v[182:185], v[206:209], v[24:27]
	v_mfma_f32_16x16x32_bf16 v[12:15], v[174:177], v[214:217], v[12:15]
	v_mfma_f32_16x16x32_bf16 v[8:11], v[182:185], v[214:217], v[8:11]
	v_mfma_f32_16x16x32_bf16 v[60:63], v[178:181], v[194:197], v[60:63]
	v_mfma_f32_16x16x32_bf16 v[56:59], v[186:189], v[194:197], v[56:59]
	v_mfma_f32_16x16x32_bf16 v[44:47], v[178:181], v[202:205], v[44:47]
	v_mfma_f32_16x16x32_bf16 v[40:43], v[186:189], v[202:205], v[40:43]
	v_mfma_f32_16x16x32_bf16 v[28:31], v[178:181], v[210:213], v[28:31]
	v_mfma_f32_16x16x32_bf16 v[24:27], v[186:189], v[210:213], v[24:27]
	v_mfma_f32_16x16x32_bf16 v[12:15], v[178:181], v[218:221], v[12:15]
	v_mfma_f32_16x16x32_bf16 v[8:11], v[186:189], v[218:221], v[8:11]
	s_barrier
	s_add_i32 s0, s0, 2
	s_add_u32 s1, s1, 0x10000
	s_addc_u32 s64, s64, 0
	s_add_u32 s65, s65, 0x100
	s_addc_u32 s66, s66, 0
	s_add_u32 s50, s50, 0xffffff00
	s_addc_u32 s51, s51, -1
	v_lshl_add_u64 v[2:3], v[2:3], 0, s[44:45]
	s_cmpk_gt_u32 s0, 0xa9
	v_lshl_add_u64 v[148:149], v[148:149], 0, s[44:45]
	s_cbranch_scc0 .LBB0_762
	s_and_b64 vcc, exec, s[42:43]
	s_cbranch_vccz .LBB0_765
	s_barrier

.LBB0_797:
	s_cmp_lg_u32 s67, 0
	s_mov_b32 s22, 0
	s_cbranch_scc0 .LBB0_799
	ds_read_b128 v[2:5], v155
	ds_read_b128 v[6:9], v155 offset:1024
	ds_read_b128 v[10:13], v155 offset:2048
	ds_read_b128 v[14:17], v155 offset:3072
	ds_read_b128 v[18:21], v156
	ds_read_b128 v[22:25], v156 offset:1024
	ds_read_b128 v[26:29], v156 offset:2048
	ds_read_b128 v[30:33], v156 offset:3072
	s_add_u32 s0, s56, 0x10000
	s_addc_u32 s1, s57, 0
	ds_read_b128 v[34:37], v157
	ds_read_b128 v[38:41], v157 offset:1024
	ds_read_b128 v[42:45], v157 offset:2048
	ds_read_b128 v[46:49], v157 offset:3072
	ds_read_b128 v[50:53], v157 offset:4096
	ds_read_b128 v[54:57], v157 offset:5120
	ds_read_b128 v[58:61], v157 offset:6144
	ds_read_b128 v[62:65], v157 offset:7168
	s_waitcnt vmcnt(16)
	s_waitcnt lgkmcnt(0)
	s_barrier
	v_mfma_f32_16x16x32_bf16 v[86:89], v[10:13], v[50:53], 0
	v_mfma_f32_16x16x32_bf16 v[92:95], v[14:17], v[54:57], v[86:89]
	v_mfma_f32_16x16x32_bf16 v[86:89], v[2:5], v[58:61], 0
	v_mfma_f32_16x16x32_bf16 v[66:69], v[2:5], v[34:37], 0
	v_mfma_f32_16x16x32_bf16 v[70:73], v[10:13], v[34:37], 0
	v_mfma_f32_16x16x32_bf16 v[74:77], v[2:5], v[42:45], 0
	v_mfma_f32_16x16x32_bf16 v[78:81], v[10:13], v[42:45], 0
	v_mfma_f32_16x16x32_bf16 v[82:85], v[2:5], v[50:53], 0
	v_mfma_f32_16x16x32_bf16 v[96:99], v[6:9], v[62:65], v[86:89]
	v_mfma_f32_16x16x32_bf16 v[86:89], v[10:13], v[58:61], 0
	v_mfma_f32_16x16x32_bf16 v[66:69], v[6:9], v[38:41], v[66:69]
	v_mfma_f32_16x16x32_bf16 v[70:73], v[14:17], v[38:41], v[70:73]
	v_mfma_f32_16x16x32_bf16 v[74:77], v[6:9], v[46:49], v[74:77]
	v_mfma_f32_16x16x32_bf16 v[78:81], v[14:17], v[46:49], v[78:81]
	v_mfma_f32_16x16x32_bf16 v[82:85], v[6:9], v[54:57], v[82:85]
	v_mfma_f32_16x16x32_bf16 v[108:111], v[14:17], v[62:65], v[86:89]
	v_mfma_f32_16x16x32_bf16 v[86:89], v[18:21], v[34:37], 0
	v_mfma_f32_16x16x32_bf16 v[34:37], v[26:29], v[34:37], 0
	v_mfma_f32_16x16x32_bf16 v[112:115], v[22:25], v[38:41], v[86:89]
	v_mfma_f32_16x16x32_bf16 v[34:37], v[30:33], v[38:41], v[34:37]
	v_mfma_f32_16x16x32_bf16 v[38:41], v[18:21], v[42:45], 0
	v_mfma_f32_16x16x32_bf16 v[42:45], v[26:29], v[42:45], 0
	v_mfma_f32_16x16x32_bf16 v[38:41], v[22:25], v[46:49], v[38:41]
	v_mfma_f32_16x16x32_bf16 v[42:45], v[30:33], v[46:49], v[42:45]
	v_mfma_f32_16x16x32_bf16 v[46:49], v[18:21], v[50:53], 0
	v_mfma_f32_16x16x32_bf16 v[50:53], v[26:29], v[50:53], 0
	v_mfma_f32_16x16x32_bf16 v[46:49], v[22:25], v[54:57], v[46:49]
	v_mfma_f32_16x16x32_bf16 v[50:53], v[30:33], v[54:57], v[50:53]
	v_mfma_f32_16x16x32_bf16 v[54:57], v[18:21], v[58:61], 0
	v_mfma_f32_16x16x32_bf16 v[58:61], v[26:29], v[58:61], 0
	v_mfma_f32_16x16x32_bf16 v[54:57], v[22:25], v[62:65], v[54:57]
	v_mfma_f32_16x16x32_bf16 v[58:61], v[30:33], v[62:65], v[58:61]
	s_barrier
	s_add_i32 s12, s60, s2
	v_lshl_add_u64 v[90:91], s[0:1], 0, v[134:135]
	s_mov_b32 m0, s12
	ds_read_b128 v[62:65], v157 offset:16384
	ds_read_b128 v[86:89], v157 offset:17408
	ds_read_b128 v[100:103], v157 offset:18432
	ds_read_b128 v[104:107], v157 offset:19456
	ds_read_b128 v[116:119], v157 offset:20480
	ds_read_b128 v[120:123], v157 offset:21504
	ds_read_b128 v[124:127], v157 offset:22528
	ds_read_b128 v[128:131], v157 offset:23552
	global_load_lds_dwordx4 v[90:91], off
	s_add_i32 m0, s12, 0x2000
	v_lshl_add_u64 v[90:91], s[0:1], 0, v[138:139]
	s_add_u32 s0, s56, 0x14000
	s_addc_u32 s1, s57, 0
	s_add_i32 s12, s61, s2
	global_load_lds_dwordx4 v[90:91], off
	v_lshl_add_u64 v[90:91], s[0:1], 0, v[134:135]
	s_mov_b32 m0, s12
	v_lshl_add_u64 v[148:149], s[8:9], 0, v[132:133]
	global_load_lds_dwordx4 v[90:91], off
	v_lshl_add_u64 v[90:91], s[0:1], 0, v[138:139]
	s_add_i32 m0, s12, 0x2000
	v_lshl_add_u64 v[144:145], s[8:9], 0, v[136:137]
	global_load_lds_dwordx4 v[90:91], off
	v_lshl_add_u64 v[90:91], v[148:149], 0, s[40:41]
	s_mov_b32 m0, s33
	s_nop 0
	global_load_lds_dwordx4 v[90:91], off
	v_lshl_add_u64 v[90:91], v[144:145], 0, s[40:41]
	s_mov_b32 m0, s53
	s_nop 0
	global_load_lds_dwordx4 v[90:91], off
	s_waitcnt vmcnt(16)
	s_waitcnt lgkmcnt(0)
	s_barrier
	v_mfma_f32_16x16x32_bf16 v[158:161], v[2:5], v[62:65], 0
	v_mfma_f32_16x16x32_bf16 v[166:169], v[2:5], v[100:103], 0
	v_mfma_f32_16x16x32_bf16 v[174:177], v[2:5], v[116:119], 0
	v_mfma_f32_16x16x32_bf16 v[2:5], v[2:5], v[124:127], 0
	v_mfma_f32_16x16x32_bf16 v[158:161], v[6:9], v[86:89], v[158:161]
	v_mfma_f32_16x16x32_bf16 v[162:165], v[10:13], v[62:65], 0
	v_mfma_f32_16x16x32_bf16 v[166:169], v[6:9], v[104:107], v[166:169]
	v_mfma_f32_16x16x32_bf16 v[170:173], v[10:13], v[100:103], 0
	v_mfma_f32_16x16x32_bf16 v[174:177], v[6:9], v[120:123], v[174:177]
	v_mfma_f32_16x16x32_bf16 v[178:181], v[10:13], v[116:119], 0
	v_mfma_f32_16x16x32_bf16 v[2:5], v[6:9], v[128:131], v[2:5]
	v_mfma_f32_16x16x32_bf16 v[6:9], v[10:13], v[124:127], 0
	v_mfma_f32_16x16x32_bf16 v[162:165], v[14:17], v[86:89], v[162:165]
	v_mfma_f32_16x16x32_bf16 v[170:173], v[14:17], v[104:107], v[170:173]
	v_mfma_f32_16x16x32_bf16 v[178:181], v[14:17], v[120:123], v[178:181]
	v_mfma_f32_16x16x32_bf16 v[12:15], v[14:17], v[128:131], v[6:9]
	v_mfma_f32_16x16x32_bf16 v[6:9], v[18:21], v[62:65], 0
	v_mfma_f32_16x16x32_bf16 v[182:185], v[22:25], v[86:89], v[6:9]
	v_mfma_f32_16x16x32_bf16 v[6:9], v[26:29], v[62:65], 0
	v_mfma_f32_16x16x32_bf16 v[186:189], v[30:33], v[86:89], v[6:9]
	v_mfma_f32_16x16x32_bf16 v[6:9], v[18:21], v[100:103], 0
	v_mfma_f32_16x16x32_bf16 v[190:193], v[22:25], v[104:107], v[6:9]
	v_mfma_f32_16x16x32_bf16 v[6:9], v[26:29], v[100:103], 0
	v_mfma_f32_16x16x32_bf16 v[194:197], v[30:33], v[104:107], v[6:9]
	v_mfma_f32_16x16x32_bf16 v[6:9], v[18:21], v[116:119], 0
	v_mfma_f32_16x16x32_bf16 v[198:201], v[22:25], v[120:123], v[6:9]
	v_mfma_f32_16x16x32_bf16 v[6:9], v[26:29], v[116:119], 0
	v_mfma_f32_16x16x32_bf16 v[202:205], v[30:33], v[120:123], v[6:9]
	v_mfma_f32_16x16x32_bf16 v[6:9], v[18:21], v[124:127], 0
	v_mfma_f32_16x16x32_bf16 v[16:19], v[22:25], v[128:131], v[6:9]
	v_mfma_f32_16x16x32_bf16 v[6:9], v[26:29], v[124:127], 0
	v_mfma_f32_16x16x32_bf16 v[206:209], v[30:33], v[128:131], v[6:9]
	s_barrier
	s_add_i32 s12, 0, 0x18000
	v_add_u32_e32 v1, s12, v152
	s_add_i32 s13, 0, 0x1c000
	s_nop 1
	ds_read_b128 v[6:9], v1
	ds_read_b128 v[28:31], v1 offset:1024
	ds_read_b128 v[62:65], v1 offset:2048
	ds_read_b128 v[210:213], v1 offset:3072
	v_add_u32_e32 v1, s13, v152
	ds_read_b128 v[214:217], v1
	ds_read_b128 v[218:221], v1 offset:1024
	ds_read_b128 v[222:225], v1 offset:2048
	ds_read_b128 v[226:229], v1 offset:3072
	s_add_u32 s0, s8, 0x100100
	s_addc_u32 s1, s9, 0
	s_mov_b32 m0, s55
	v_lshl_add_u64 v[10:11], s[0:1], 0, v[132:133]
	ds_read_b128 v[20:23], v157 offset:32768
	ds_read_b128 v[24:27], v157 offset:33792
	ds_read_b128 v[230:233], v157 offset:34816
	ds_read_b128 v[234:237], v157 offset:35840
	ds_read_b128 v[238:241], v157 offset:36864
	ds_read_b128 v[242:245], v157 offset:37888
	ds_read_b128 v[246:249], v157 offset:38912
	ds_read_b128 v[250:253], v157 offset:39936
	global_load_lds_dwordx4 v[10:11], off
	v_lshl_add_u64 v[10:11], s[0:1], 0, v[136:137]
	s_mov_b32 m0, s58
	s_nop 0
	global_load_lds_dwordx4 v[10:11], off
	s_waitcnt vmcnt(16)
	s_waitcnt lgkmcnt(0)
	s_barrier
	v_mfma_f32_16x16x32_bf16 v[66:69], v[6:9], v[20:23], v[66:69]
	v_mfma_f32_16x16x32_bf16 v[120:123], v[28:31], v[24:27], v[66:69]
	v_mfma_f32_16x16x32_bf16 v[66:69], v[62:65], v[20:23], v[70:73]
	v_mfma_f32_16x16x32_bf16 v[116:119], v[210:213], v[24:27], v[66:69]
	v_mfma_f32_16x16x32_bf16 v[66:69], v[6:9], v[230:233], v[74:77]
	v_mfma_f32_16x16x32_bf16 v[104:107], v[28:31], v[234:237], v[66:69]
	v_mfma_f32_16x16x32_bf16 v[66:69], v[62:65], v[230:233], v[78:81]
	v_mfma_f32_16x16x32_bf16 v[100:103], v[210:213], v[234:237], v[66:69]
	v_mfma_f32_16x16x32_bf16 v[66:69], v[6:9], v[238:241], v[82:85]
	v_mfma_f32_16x16x32_bf16 v[88:91], v[28:31], v[242:245], v[66:69]
	v_mfma_f32_16x16x32_bf16 v[66:69], v[62:65], v[238:241], v[92:95]
	v_mfma_f32_16x16x32_bf16 v[84:87], v[210:213], v[242:245], v[66:69]
	v_mfma_f32_16x16x32_bf16 v[66:69], v[6:9], v[246:249], v[96:99]
	v_mfma_f32_16x16x32_bf16 v[72:75], v[28:31], v[250:253], v[66:69]
	v_mfma_f32_16x16x32_bf16 v[66:69], v[62:65], v[246:249], v[108:111]
	v_mfma_f32_16x16x32_bf16 v[68:71], v[210:213], v[250:253], v[66:69]
	v_mfma_f32_16x16x32_bf16 v[76:79], v[214:217], v[20:23], v[112:115]
	v_mfma_f32_16x16x32_bf16 v[20:23], v[222:225], v[20:23], v[34:37]
	v_mfma_f32_16x16x32_bf16 v[124:127], v[226:229], v[24:27], v[20:23]
	v_mfma_f32_16x16x32_bf16 v[20:23], v[214:217], v[230:233], v[38:41]
	v_mfma_f32_16x16x32_bf16 v[112:115], v[218:221], v[234:237], v[20:23]
	v_mfma_f32_16x16x32_bf16 v[20:23], v[222:225], v[230:233], v[42:45]
	v_mfma_f32_16x16x32_bf16 v[108:111], v[226:229], v[234:237], v[20:23]
	v_mfma_f32_16x16x32_bf16 v[20:23], v[214:217], v[238:241], v[46:49]
	v_mfma_f32_16x16x32_bf16 v[96:99], v[218:221], v[242:245], v[20:23]
	v_mfma_f32_16x16x32_bf16 v[20:23], v[222:225], v[238:241], v[50:53]
	v_mfma_f32_16x16x32_bf16 v[92:95], v[226:229], v[242:245], v[20:23]
	v_mfma_f32_16x16x32_bf16 v[20:23], v[214:217], v[246:249], v[54:57]
	v_mfma_f32_16x16x32_bf16 v[80:83], v[218:221], v[250:253], v[20:23]
	v_mfma_f32_16x16x32_bf16 v[20:23], v[222:225], v[246:249], v[58:61]
	v_mfma_f32_16x16x32_bf16 v[128:131], v[218:221], v[24:27], v[76:79]
	v_mfma_f32_16x16x32_bf16 v[76:79], v[226:229], v[250:253], v[20:23]
	s_barrier
	s_add_u32 s0, s56, 0x18000
	s_addc_u32 s1, s57, 0
	s_add_i32 s12, s12, s2
	v_lshl_add_u64 v[10:11], s[0:1], 0, v[134:135]
	s_mov_b32 m0, s12
	ds_read_b128 v[32:35], v157 offset:49152
	ds_read_b128 v[44:47], v157 offset:50176
	ds_read_b128 v[230:233], v157 offset:51200
	ds_read_b128 v[234:237], v157 offset:52224
	ds_read_b128 v[238:241], v157 offset:53248
	ds_read_b128 v[242:245], v157 offset:54272
	ds_read_b128 v[246:249], v157 offset:55296
	ds_read_b128 v[250:253], v157 offset:56320
	global_load_lds_dwordx4 v[10:11], off
	s_add_i32 m0, s12, 0x2000
	v_lshl_add_u64 v[10:11], s[0:1], 0, v[138:139]
	s_add_u32 s0, s56, 0x1c000
	s_addc_u32 s1, s57, 0
	s_add_i32 s12, s13, s2
	global_load_lds_dwordx4 v[10:11], off
	v_lshl_add_u64 v[10:11], s[0:1], 0, v[134:135]
	s_mov_b32 m0, s12
	s_nop 0
	global_load_lds_dwordx4 v[10:11], off
	v_lshl_add_u64 v[10:11], s[0:1], 0, v[138:139]
	s_add_i32 m0, s12, 0x2000
	s_nop 0
	global_load_lds_dwordx4 v[10:11], off
	v_lshl_add_u64 v[10:11], v[148:149], 0, s[42:43]
	s_mov_b32 m0, s16
	s_nop 0
	global_load_lds_dwordx4 v[10:11], off
	v_lshl_add_u64 v[10:11], v[144:145], 0, s[42:43]
	s_mov_b32 m0, s59
	s_nop 0
	global_load_lds_dwordx4 v[10:11], off
	s_waitcnt vmcnt(8)
	s_waitcnt lgkmcnt(0)
	s_barrier
	v_mfma_f32_16x16x32_bf16 v[20:23], v[6:9], v[32:35], v[158:161]
	v_mfma_f32_16x16x32_bf16 v[56:59], v[28:31], v[44:47], v[20:23]
	v_mfma_f32_16x16x32_bf16 v[20:23], v[62:65], v[32:35], v[162:165]
	v_mfma_f32_16x16x32_bf16 v[52:55], v[210:213], v[44:47], v[20:23]
	v_mfma_f32_16x16x32_bf16 v[20:23], v[6:9], v[230:233], v[166:169]
	v_mfma_f32_16x16x32_bf16 v[40:43], v[28:31], v[234:237], v[20:23]
	v_mfma_f32_16x16x32_bf16 v[20:23], v[62:65], v[230:233], v[170:173]
	v_mfma_f32_16x16x32_bf16 v[36:39], v[210:213], v[234:237], v[20:23]
	v_mfma_f32_16x16x32_bf16 v[20:23], v[6:9], v[238:241], v[174:177]
	v_mfma_f32_16x16x32_bf16 v[2:5], v[6:9], v[246:249], v[2:5]
	v_mfma_f32_16x16x32_bf16 v[24:27], v[28:31], v[242:245], v[20:23]
	v_mfma_f32_16x16x32_bf16 v[20:23], v[62:65], v[238:241], v[178:181]
	v_mfma_f32_16x16x32_bf16 v[8:11], v[28:31], v[250:253], v[2:5]
	v_mfma_f32_16x16x32_bf16 v[2:5], v[62:65], v[246:249], v[12:15]
	v_mfma_f32_16x16x32_bf16 v[20:23], v[210:213], v[242:245], v[20:23]
	v_mfma_f32_16x16x32_bf16 v[4:7], v[210:213], v[250:253], v[2:5]
	v_mfma_f32_16x16x32_bf16 v[12:15], v[214:217], v[32:35], v[182:185]
	v_mfma_f32_16x16x32_bf16 v[64:67], v[218:221], v[44:47], v[12:15]
	v_mfma_f32_16x16x32_bf16 v[12:15], v[222:225], v[32:35], v[186:189]
	v_mfma_f32_16x16x32_bf16 v[60:63], v[226:229], v[44:47], v[12:15]
	v_mfma_f32_16x16x32_bf16 v[12:15], v[214:217], v[230:233], v[190:193]
	v_mfma_f32_16x16x32_bf16 v[48:51], v[218:221], v[234:237], v[12:15]
	v_mfma_f32_16x16x32_bf16 v[12:15], v[222:225], v[230:233], v[194:197]
	v_mfma_f32_16x16x32_bf16 v[44:47], v[226:229], v[234:237], v[12:15]
	v_mfma_f32_16x16x32_bf16 v[12:15], v[214:217], v[238:241], v[198:201]
	v_mfma_f32_16x16x32_bf16 v[32:35], v[218:221], v[242:245], v[12:15]
	v_mfma_f32_16x16x32_bf16 v[12:15], v[222:225], v[238:241], v[202:205]
	v_mfma_f32_16x16x32_bf16 v[28:31], v[226:229], v[242:245], v[12:15]
	v_mfma_f32_16x16x32_bf16 v[12:15], v[214:217], v[246:249], v[16:19]
	v_mfma_f32_16x16x32_bf16 v[16:19], v[218:221], v[250:253], v[12:15]
	v_mfma_f32_16x16x32_bf16 v[12:15], v[222:225], v[246:249], v[206:209]
	v_mfma_f32_16x16x32_bf16 v[12:15], v[226:229], v[250:253], v[12:15]
	s_barrier
	s_mov_b32 s22, 2
	s_branch .LBB0_800

.LBB0_801:
	ds_read_b128 v[158:161], v155
	ds_read_b128 v[162:165], v155 offset:1024
	ds_read_b128 v[166:169], v155 offset:2048
	ds_read_b128 v[170:173], v155 offset:3072
	ds_read_b128 v[174:177], v156
	ds_read_b128 v[178:181], v156 offset:1024
	ds_read_b128 v[182:185], v156 offset:2048
	ds_read_b128 v[186:189], v156 offset:3072
	s_add_u32 s12, s72, s36
	s_addc_u32 s13, s73, 0
	s_cmp_eq_u32 s36, s8
	s_cselect_b32 s23, s0, s13
	s_cselect_b32 s22, s1, s12
	s_cselect_b32 s57, s45, s71
	s_cselect_b32 s56, s68, s70
	s_add_i32 s75, s33, 0xc000
	v_lshl_add_u64 v[144:145], v[2:3], 0, s[36:37]
	s_mov_b32 m0, s75
	s_add_i32 s74, s33, 0xe000
	ds_read_b128 v[190:193], v157
	ds_read_b128 v[194:197], v157 offset:1024
	ds_read_b128 v[198:201], v157 offset:2048
	ds_read_b128 v[202:205], v157 offset:3072
	ds_read_b128 v[206:209], v157 offset:4096
	ds_read_b128 v[210:213], v157 offset:5120
	ds_read_b128 v[214:217], v157 offset:6144
	ds_read_b128 v[218:221], v157 offset:7168
	global_load_lds_dwordx4 v[144:145], off
	v_lshl_add_u64 v[144:145], v[148:149], 0, s[36:37]
	s_mov_b32 m0, s74
	s_nop 0
	global_load_lds_dwordx4 v[144:145], off
	s_waitcnt vmcnt(8)
	s_waitcnt lgkmcnt(0)
	s_barrier
	v_mfma_f32_16x16x32_bf16 v[120:123], v[158:161], v[190:193], v[120:123]
	v_mfma_f32_16x16x32_bf16 v[116:119], v[166:169], v[190:193], v[116:119]
	v_mfma_f32_16x16x32_bf16 v[104:107], v[158:161], v[198:201], v[104:107]
	v_mfma_f32_16x16x32_bf16 v[100:103], v[166:169], v[198:201], v[100:103]
	v_mfma_f32_16x16x32_bf16 v[88:91], v[158:161], v[206:209], v[88:91]
	v_mfma_f32_16x16x32_bf16 v[84:87], v[166:169], v[206:209], v[84:87]
	v_mfma_f32_16x16x32_bf16 v[72:75], v[158:161], v[214:217], v[72:75]
	v_mfma_f32_16x16x32_bf16 v[68:71], v[166:169], v[214:217], v[68:71]
	v_mfma_f32_16x16x32_bf16 v[120:123], v[162:165], v[194:197], v[120:123]
	v_mfma_f32_16x16x32_bf16 v[116:119], v[170:173], v[194:197], v[116:119]
	v_mfma_f32_16x16x32_bf16 v[104:107], v[162:165], v[202:205], v[104:107]
	v_mfma_f32_16x16x32_bf16 v[100:103], v[170:173], v[202:205], v[100:103]
	v_mfma_f32_16x16x32_bf16 v[88:91], v[162:165], v[210:213], v[88:91]
	v_mfma_f32_16x16x32_bf16 v[84:87], v[170:173], v[210:213], v[84:87]
	v_mfma_f32_16x16x32_bf16 v[72:75], v[162:165], v[218:221], v[72:75]
	v_mfma_f32_16x16x32_bf16 v[68:71], v[170:173], v[218:221], v[68:71]
	v_mfma_f32_16x16x32_bf16 v[128:131], v[174:177], v[190:193], v[128:131]
	v_mfma_f32_16x16x32_bf16 v[124:127], v[182:185], v[190:193], v[124:127]
	v_mfma_f32_16x16x32_bf16 v[112:115], v[174:177], v[198:201], v[112:115]
	v_mfma_f32_16x16x32_bf16 v[108:111], v[182:185], v[198:201], v[108:111]
	v_mfma_f32_16x16x32_bf16 v[96:99], v[174:177], v[206:209], v[96:99]
	v_mfma_f32_16x16x32_bf16 v[92:95], v[182:185], v[206:209], v[92:95]
	v_mfma_f32_16x16x32_bf16 v[80:83], v[174:177], v[214:217], v[80:83]
	v_mfma_f32_16x16x32_bf16 v[76:79], v[182:185], v[214:217], v[76:79]
	v_mfma_f32_16x16x32_bf16 v[128:131], v[178:181], v[194:197], v[128:131]
	v_mfma_f32_16x16x32_bf16 v[124:127], v[186:189], v[194:197], v[124:127]
	v_mfma_f32_16x16x32_bf16 v[112:115], v[178:181], v[202:205], v[112:115]
	v_mfma_f32_16x16x32_bf16 v[108:111], v[186:189], v[202:205], v[108:111]
	v_mfma_f32_16x16x32_bf16 v[96:99], v[178:181], v[210:213], v[96:99]
	v_mfma_f32_16x16x32_bf16 v[92:95], v[186:189], v[210:213], v[92:95]
	v_mfma_f32_16x16x32_bf16 v[80:83], v[178:181], v[218:221], v[80:83]
	v_mfma_f32_16x16x32_bf16 v[76:79], v[186:189], v[218:221], v[76:79]
	s_barrier
	s_add_i32 s12, s60, s2
	v_lshl_add_u64 v[144:145], s[56:57], 0, v[134:135]
	s_mov_b32 m0, s12
	ds_read_b128 v[190:193], v157 offset:16384
	ds_read_b128 v[194:197], v157 offset:17408
	ds_read_b128 v[198:201], v157 offset:18432
	ds_read_b128 v[202:205], v157 offset:19456
	ds_read_b128 v[206:209], v157 offset:20480
	ds_read_b128 v[210:213], v157 offset:21504
	ds_read_b128 v[214:217], v157 offset:22528
	ds_read_b128 v[218:221], v157 offset:23552
	global_load_lds_dwordx4 v[144:145], off
	s_add_i32 m0, s12, 0x2000
	s_add_u32 s12, s56, 0x4000
	v_lshl_add_u64 v[144:145], s[56:57], 0, v[138:139]
	s_addc_u32 s13, s57, 0
	s_add_i32 s14, s61, s2
	global_load_lds_dwordx4 v[144:145], off
	v_lshl_add_u64 v[144:145], s[12:13], 0, v[134:135]
	s_mov_b32 m0, s14
	v_lshl_add_u64 v[222:223], s[22:23], 0, v[136:137]
	global_load_lds_dwordx4 v[144:145], off
	v_lshl_add_u64 v[144:145], s[12:13], 0, v[138:139]
	s_add_i32 m0, s14, 0x2000
	s_nop 0
	global_load_lds_dwordx4 v[144:145], off
	v_lshl_add_u64 v[144:145], s[22:23], 0, v[132:133]
	s_mov_b32 m0, s33
	s_nop 0
	global_load_lds_dwordx4 v[144:145], off
	s_mov_b32 m0, s53
	s_nop 0
	global_load_lds_dwordx4 v[222:223], off
	s_waitcnt vmcnt(8)
	s_waitcnt lgkmcnt(0)
	s_barrier
	v_mfma_f32_16x16x32_bf16 v[56:59], v[158:161], v[190:193], v[56:59]
	v_mfma_f32_16x16x32_bf16 v[52:55], v[166:169], v[190:193], v[52:55]
	v_mfma_f32_16x16x32_bf16 v[40:43], v[158:161], v[198:201], v[40:43]
	v_mfma_f32_16x16x32_bf16 v[36:39], v[166:169], v[198:201], v[36:39]
	v_mfma_f32_16x16x32_bf16 v[24:27], v[158:161], v[206:209], v[24:27]
	v_mfma_f32_16x16x32_bf16 v[20:23], v[166:169], v[206:209], v[20:23]
	v_mfma_f32_16x16x32_bf16 v[8:11], v[158:161], v[214:217], v[8:11]
	v_mfma_f32_16x16x32_bf16 v[4:7], v[166:169], v[214:217], v[4:7]
	v_mfma_f32_16x16x32_bf16 v[56:59], v[162:165], v[194:197], v[56:59]
	v_mfma_f32_16x16x32_bf16 v[52:55], v[170:173], v[194:197], v[52:55]
	v_mfma_f32_16x16x32_bf16 v[40:43], v[162:165], v[202:205], v[40:43]
	v_mfma_f32_16x16x32_bf16 v[36:39], v[170:173], v[202:205], v[36:39]
	v_mfma_f32_16x16x32_bf16 v[24:27], v[162:165], v[210:213], v[24:27]
	v_mfma_f32_16x16x32_bf16 v[20:23], v[170:173], v[210:213], v[20:23]
	v_mfma_f32_16x16x32_bf16 v[8:11], v[162:165], v[218:221], v[8:11]
	v_mfma_f32_16x16x32_bf16 v[4:7], v[170:173], v[218:221], v[4:7]
	v_mfma_f32_16x16x32_bf16 v[64:67], v[174:177], v[190:193], v[64:67]
	v_mfma_f32_16x16x32_bf16 v[60:63], v[182:185], v[190:193], v[60:63]
	v_mfma_f32_16x16x32_bf16 v[48:51], v[174:177], v[198:201], v[48:51]
	v_mfma_f32_16x16x32_bf16 v[44:47], v[182:185], v[198:201], v[44:47]
	v_mfma_f32_16x16x32_bf16 v[32:35], v[174:177], v[206:209], v[32:35]
	v_mfma_f32_16x16x32_bf16 v[28:31], v[182:185], v[206:209], v[28:31]
	v_mfma_f32_16x16x32_bf16 v[16:19], v[174:177], v[214:217], v[16:19]
	v_mfma_f32_16x16x32_bf16 v[12:15], v[182:185], v[214:217], v[12:15]
	v_mfma_f32_16x16x32_bf16 v[64:67], v[178:181], v[194:197], v[64:67]
	v_mfma_f32_16x16x32_bf16 v[60:63], v[186:189], v[194:197], v[60:63]
	v_mfma_f32_16x16x32_bf16 v[48:51], v[178:181], v[202:205], v[48:51]
	v_mfma_f32_16x16x32_bf16 v[44:47], v[186:189], v[202:205], v[44:47]
	v_mfma_f32_16x16x32_bf16 v[32:35], v[178:181], v[210:213], v[32:35]
	v_mfma_f32_16x16x32_bf16 v[28:31], v[186:189], v[210:213], v[28:31]
	v_mfma_f32_16x16x32_bf16 v[16:19], v[178:181], v[218:221], v[16:19]
	v_mfma_f32_16x16x32_bf16 v[12:15], v[186:189], v[218:221], v[12:15]
	s_barrier
	s_add_i32 s14, 0, 0x18000
	v_add_u32_e32 v1, s14, v152
	s_add_i32 s76, 0, 0x1c000
	ds_read_b128 v[158:161], v1
	ds_read_b128 v[162:165], v1 offset:1024
	ds_read_b128 v[166:169], v1 offset:2048
	ds_read_b128 v[170:173], v1 offset:3072
	v_add_u32_e32 v1, s76, v152
	ds_read_b128 v[174:177], v1
	ds_read_b128 v[178:181], v1 offset:1024
	ds_read_b128 v[182:185], v1 offset:2048
	ds_read_b128 v[186:189], v1 offset:3072
	s_add_u32 s12, s22, 0x100000
	s_addc_u32 s13, s23, 0
	s_mov_b32 m0, s55
	v_lshl_add_u64 v[224:225], s[12:13], 0, v[132:133]
	ds_read_b128 v[190:193], v157 offset:32768
	ds_read_b128 v[194:197], v157 offset:33792
	ds_read_b128 v[198:201], v157 offset:34816
	ds_read_b128 v[202:205], v157 offset:35840
	ds_read_b128 v[206:209], v157 offset:36864
	ds_read_b128 v[210:213], v157 offset:37888
	ds_read_b128 v[214:217], v157 offset:38912
	ds_read_b128 v[218:221], v157 offset:39936
	global_load_lds_dwordx4 v[224:225], off
	v_lshl_add_u64 v[224:225], s[12:13], 0, v[136:137]
	s_mov_b32 m0, s58
	s_nop 0
	global_load_lds_dwordx4 v[224:225], off
	s_waitcnt vmcnt(8)
	s_waitcnt lgkmcnt(0)
	s_barrier
	v_mfma_f32_16x16x32_bf16 v[120:123], v[158:161], v[190:193], v[120:123]
	v_mfma_f32_16x16x32_bf16 v[116:119], v[166:169], v[190:193], v[116:119]
	v_mfma_f32_16x16x32_bf16 v[104:107], v[158:161], v[198:201], v[104:107]
	v_mfma_f32_16x16x32_bf16 v[100:103], v[166:169], v[198:201], v[100:103]
	v_mfma_f32_16x16x32_bf16 v[88:91], v[158:161], v[206:209], v[88:91]
	v_mfma_f32_16x16x32_bf16 v[84:87], v[166:169], v[206:209], v[84:87]
	v_mfma_f32_16x16x32_bf16 v[72:75], v[158:161], v[214:217], v[72:75]
	v_mfma_f32_16x16x32_bf16 v[68:71], v[166:169], v[214:217], v[68:71]
	v_mfma_f32_16x16x32_bf16 v[120:123], v[162:165], v[194:197], v[120:123]
	v_mfma_f32_16x16x32_bf16 v[116:119], v[170:173], v[194:197], v[116:119]
	v_mfma_f32_16x16x32_bf16 v[104:107], v[162:165], v[202:205], v[104:107]
	v_mfma_f32_16x16x32_bf16 v[100:103], v[170:173], v[202:205], v[100:103]
	v_mfma_f32_16x16x32_bf16 v[88:91], v[162:165], v[210:213], v[88:91]
	v_mfma_f32_16x16x32_bf16 v[84:87], v[170:173], v[210:213], v[84:87]
	v_mfma_f32_16x16x32_bf16 v[72:75], v[162:165], v[218:221], v[72:75]
	v_mfma_f32_16x16x32_bf16 v[68:71], v[170:173], v[218:221], v[68:71]
	v_mfma_f32_16x16x32_bf16 v[128:131], v[174:177], v[190:193], v[128:131]
	v_mfma_f32_16x16x32_bf16 v[124:127], v[182:185], v[190:193], v[124:127]
	v_mfma_f32_16x16x32_bf16 v[112:115], v[174:177], v[198:201], v[112:115]
	v_mfma_f32_16x16x32_bf16 v[108:111], v[182:185], v[198:201], v[108:111]
	v_mfma_f32_16x16x32_bf16 v[96:99], v[174:177], v[206:209], v[96:99]
	v_mfma_f32_16x16x32_bf16 v[92:95], v[182:185], v[206:209], v[92:95]
	v_mfma_f32_16x16x32_bf16 v[80:83], v[174:177], v[214:217], v[80:83]
	v_mfma_f32_16x16x32_bf16 v[76:79], v[182:185], v[214:217], v[76:79]
	v_mfma_f32_16x16x32_bf16 v[128:131], v[178:181], v[194:197], v[128:131]
	v_mfma_f32_16x16x32_bf16 v[124:127], v[186:189], v[194:197], v[124:127]
	v_mfma_f32_16x16x32_bf16 v[112:115], v[178:181], v[202:205], v[112:115]
	v_mfma_f32_16x16x32_bf16 v[108:111], v[186:189], v[202:205], v[108:111]
	v_mfma_f32_16x16x32_bf16 v[96:99], v[178:181], v[210:213], v[96:99]
	v_mfma_f32_16x16x32_bf16 v[92:95], v[186:189], v[210:213], v[92:95]
	v_mfma_f32_16x16x32_bf16 v[80:83], v[178:181], v[218:221], v[80:83]
	v_mfma_f32_16x16x32_bf16 v[76:79], v[186:189], v[218:221], v[76:79]
	s_barrier
	s_add_u32 s12, s56, 0x8000
	s_addc_u32 s13, s57, 0
	s_add_i32 s14, s14, s2
	v_lshl_add_u64 v[224:225], s[12:13], 0, v[134:135]
	s_mov_b32 m0, s14
	ds_read_b128 v[190:193], v157 offset:49152
	ds_read_b128 v[194:197], v157 offset:50176
	ds_read_b128 v[198:201], v157 offset:51200
	ds_read_b128 v[202:205], v157 offset:52224
	ds_read_b128 v[206:209], v157 offset:53248
	ds_read_b128 v[210:213], v157 offset:54272
	ds_read_b128 v[214:217], v157 offset:55296
	ds_read_b128 v[218:221], v157 offset:56320
	global_load_lds_dwordx4 v[224:225], off
	s_add_i32 m0, s14, 0x2000
	v_lshl_add_u64 v[224:225], s[12:13], 0, v[138:139]
	s_add_u32 s12, s56, 0xc000
	s_addc_u32 s13, s57, 0
	s_add_i32 s14, s76, s2
	global_load_lds_dwordx4 v[224:225], off
	v_lshl_add_u64 v[224:225], s[12:13], 0, v[134:135]
	s_mov_b32 m0, s14
	v_lshl_add_u64 v[144:145], v[144:145], 0, s[34:35]
	global_load_lds_dwordx4 v[224:225], off
	v_lshl_add_u64 v[224:225], s[12:13], 0, v[138:139]
	s_add_i32 m0, s14, 0x2000
	s_nop 0
	global_load_lds_dwordx4 v[224:225], off
	s_mov_b32 m0, s16
	s_nop 0
	global_load_lds_dwordx4 v[144:145], off
	v_lshl_add_u64 v[144:145], v[222:223], 0, s[34:35]
	s_mov_b32 m0, s59
	s_nop 0
	global_load_lds_dwordx4 v[144:145], off
	s_waitcnt vmcnt(8)
	s_waitcnt lgkmcnt(0)
	s_barrier
	v_mfma_f32_16x16x32_bf16 v[56:59], v[158:161], v[190:193], v[56:59]
	v_mfma_f32_16x16x32_bf16 v[52:55], v[166:169], v[190:193], v[52:55]
	v_mfma_f32_16x16x32_bf16 v[40:43], v[158:161], v[198:201], v[40:43]
	v_mfma_f32_16x16x32_bf16 v[36:39], v[166:169], v[198:201], v[36:39]
	v_mfma_f32_16x16x32_bf16 v[24:27], v[158:161], v[206:209], v[24:27]
	v_mfma_f32_16x16x32_bf16 v[20:23], v[166:169], v[206:209], v[20:23]
	v_mfma_f32_16x16x32_bf16 v[8:11], v[158:161], v[214:217], v[8:11]
	v_mfma_f32_16x16x32_bf16 v[4:7], v[166:169], v[214:217], v[4:7]
	v_mfma_f32_16x16x32_bf16 v[56:59], v[162:165], v[194:197], v[56:59]
	v_mfma_f32_16x16x32_bf16 v[52:55], v[170:173], v[194:197], v[52:55]
	v_mfma_f32_16x16x32_bf16 v[40:43], v[162:165], v[202:205], v[40:43]
	v_mfma_f32_16x16x32_bf16 v[36:39], v[170:173], v[202:205], v[36:39]
	v_mfma_f32_16x16x32_bf16 v[24:27], v[162:165], v[210:213], v[24:27]
	v_mfma_f32_16x16x32_bf16 v[20:23], v[170:173], v[210:213], v[20:23]
	v_mfma_f32_16x16x32_bf16 v[8:11], v[162:165], v[218:221], v[8:11]
	v_mfma_f32_16x16x32_bf16 v[4:7], v[170:173], v[218:221], v[4:7]
	v_mfma_f32_16x16x32_bf16 v[64:67], v[174:177], v[190:193], v[64:67]
	v_mfma_f32_16x16x32_bf16 v[60:63], v[182:185], v[190:193], v[60:63]
	v_mfma_f32_16x16x32_bf16 v[48:51], v[174:177], v[198:201], v[48:51]
	v_mfma_f32_16x16x32_bf16 v[44:47], v[182:185], v[198:201], v[44:47]
	v_mfma_f32_16x16x32_bf16 v[32:35], v[174:177], v[206:209], v[32:35]
	v_mfma_f32_16x16x32_bf16 v[28:31], v[182:185], v[206:209], v[28:31]
	v_mfma_f32_16x16x32_bf16 v[16:19], v[174:177], v[214:217], v[16:19]
	v_mfma_f32_16x16x32_bf16 v[12:15], v[182:185], v[214:217], v[12:15]
	v_mfma_f32_16x16x32_bf16 v[64:67], v[178:181], v[194:197], v[64:67]
	v_mfma_f32_16x16x32_bf16 v[60:63], v[186:189], v[194:197], v[60:63]
	v_mfma_f32_16x16x32_bf16 v[48:51], v[178:181], v[202:205], v[48:51]
	v_mfma_f32_16x16x32_bf16 v[44:47], v[186:189], v[202:205], v[44:47]
	v_mfma_f32_16x16x32_bf16 v[32:35], v[178:181], v[210:213], v[32:35]
	v_mfma_f32_16x16x32_bf16 v[28:31], v[186:189], v[210:213], v[28:31]
	v_mfma_f32_16x16x32_bf16 v[16:19], v[178:181], v[218:221], v[16:19]
	v_mfma_f32_16x16x32_bf16 v[12:15], v[186:189], v[218:221], v[12:15]
	s_barrier
	s_add_i32 s69, s69, 2
	s_add_u32 s70, s70, 0x10000
	s_addc_u32 s71, s71, 0
	s_add_u32 s72, s72, 0x100
	s_addc_u32 s73, s73, 0
	s_add_u32 s8, s8, 0xffffff00
	s_addc_u32 s9, s9, -1
	v_lshl_add_u64 v[2:3], v[2:3], 0, s[40:41]
	s_cmp_gt_u32 s69, 61
	v_lshl_add_u64 v[148:149], v[148:149], 0, s[40:41]
	s_cbranch_scc0 .LBB0_801
	s_and_b64 vcc, exec, s[38:39]
	s_cbranch_vccnz .LBB0_809
	s_and_b64 s[0:1], s[10:11], s[6:7]
	s_andn2_b64 vcc, exec, s[0:1]
	s_cbranch_vccz .LBB0_810

.LBB0_891:
	ds_read_b128 v[2:5], v153
	ds_read_b128 v[6:9], v153 offset:1024
	ds_read_b128 v[10:13], v153 offset:2048
	ds_read_b128 v[14:17], v153 offset:3072
	ds_read_b128 v[18:21], v154
	ds_read_b128 v[22:25], v154 offset:1024
	ds_read_b128 v[26:29], v154 offset:2048
	ds_read_b128 v[30:33], v154 offset:3072
	s_add_u32 s0, s46, 0x10000
	s_addc_u32 s1, s47, 0
	ds_read_b128 v[34:37], v155
	ds_read_b128 v[38:41], v155 offset:1024
	ds_read_b128 v[42:45], v155 offset:2048
	ds_read_b128 v[46:49], v155 offset:3072
	ds_read_b128 v[50:53], v155 offset:4096
	ds_read_b128 v[54:57], v155 offset:5120
	ds_read_b128 v[58:61], v155 offset:6144
	ds_read_b128 v[62:65], v155 offset:7168
	s_waitcnt vmcnt(24)
	s_waitcnt lgkmcnt(0)
	s_barrier
	v_mfma_f32_16x16x32_bf16 v[66:69], v[2:5], v[34:37], 0
	v_mfma_f32_16x16x32_bf16 v[70:73], v[10:13], v[34:37], 0
	v_mfma_f32_16x16x32_bf16 v[74:77], v[2:5], v[42:45], 0
	v_mfma_f32_16x16x32_bf16 v[78:81], v[10:13], v[42:45], 0
	v_mfma_f32_16x16x32_bf16 v[82:85], v[2:5], v[50:53], 0
	v_mfma_f32_16x16x32_bf16 v[86:89], v[10:13], v[50:53], 0
	v_mfma_f32_16x16x32_bf16 v[90:93], v[2:5], v[58:61], 0
	v_mfma_f32_16x16x32_bf16 v[94:97], v[10:13], v[58:61], 0
	v_mfma_f32_16x16x32_bf16 v[66:69], v[6:9], v[38:41], v[66:69]
	v_mfma_f32_16x16x32_bf16 v[70:73], v[14:17], v[38:41], v[70:73]
	v_mfma_f32_16x16x32_bf16 v[74:77], v[6:9], v[46:49], v[74:77]
	v_mfma_f32_16x16x32_bf16 v[78:81], v[14:17], v[46:49], v[78:81]
	v_mfma_f32_16x16x32_bf16 v[82:85], v[6:9], v[54:57], v[82:85]
	v_mfma_f32_16x16x32_bf16 v[86:89], v[14:17], v[54:57], v[86:89]
	v_mfma_f32_16x16x32_bf16 v[90:93], v[6:9], v[62:65], v[90:93]
	v_mfma_f32_16x16x32_bf16 v[104:107], v[14:17], v[62:65], v[94:97]
	v_mfma_f32_16x16x32_bf16 v[94:97], v[18:21], v[34:37], 0
	v_mfma_f32_16x16x32_bf16 v[34:37], v[26:29], v[34:37], 0
	v_mfma_f32_16x16x32_bf16 v[108:111], v[22:25], v[38:41], v[94:97]
	v_mfma_f32_16x16x32_bf16 v[34:37], v[30:33], v[38:41], v[34:37]
	v_mfma_f32_16x16x32_bf16 v[38:41], v[18:21], v[42:45], 0
	v_mfma_f32_16x16x32_bf16 v[42:45], v[26:29], v[42:45], 0
	v_mfma_f32_16x16x32_bf16 v[38:41], v[22:25], v[46:49], v[38:41]
	v_mfma_f32_16x16x32_bf16 v[42:45], v[30:33], v[46:49], v[42:45]
	v_mfma_f32_16x16x32_bf16 v[46:49], v[18:21], v[50:53], 0
	v_mfma_f32_16x16x32_bf16 v[50:53], v[26:29], v[50:53], 0
	v_mfma_f32_16x16x32_bf16 v[46:49], v[22:25], v[54:57], v[46:49]
	v_mfma_f32_16x16x32_bf16 v[50:53], v[30:33], v[54:57], v[50:53]
	v_mfma_f32_16x16x32_bf16 v[54:57], v[18:21], v[58:61], 0
	v_mfma_f32_16x16x32_bf16 v[58:61], v[26:29], v[58:61], 0
	v_mfma_f32_16x16x32_bf16 v[54:57], v[22:25], v[62:65], v[54:57]
	v_mfma_f32_16x16x32_bf16 v[58:61], v[30:33], v[62:65], v[58:61]
	s_barrier
	s_add_i32 s12, s52, s17
	v_lshl_add_u64 v[102:103], s[0:1], 0, v[134:135]
	s_mov_b32 m0, s12
	ds_read_b128 v[62:65], v155 offset:16384
	ds_read_b128 v[94:97], v155 offset:17408
	ds_read_b128 v[98:101], v155 offset:18432
	ds_read_b128 v[112:115], v155 offset:19456
	ds_read_b128 v[116:119], v155 offset:20480
	ds_read_b128 v[120:123], v155 offset:21504
	ds_read_b128 v[124:127], v155 offset:22528
	ds_read_b128 v[128:131], v155 offset:23552
	global_load_lds_dwordx4 v[102:103], off
	s_add_i32 m0, s12, 0x2000
	v_lshl_add_u64 v[102:103], s[0:1], 0, v[138:139]
	s_add_u32 s0, s46, 0x14000
	s_addc_u32 s1, s47, 0
	s_add_i32 s12, s53, s17
	global_load_lds_dwordx4 v[102:103], off
	v_lshl_add_u64 v[102:103], s[0:1], 0, v[134:135]
	s_mov_b32 m0, s12
	v_lshl_add_u64 v[148:149], s[48:49], 0, v[132:133]
	global_load_lds_dwordx4 v[102:103], off
	v_lshl_add_u64 v[102:103], s[0:1], 0, v[138:139]
	s_add_i32 m0, s12, 0x2000
	v_lshl_add_u64 v[144:145], s[48:49], 0, v[136:137]
	global_load_lds_dwordx4 v[102:103], off
	v_lshl_add_u64 v[102:103], v[148:149], 0, s[40:41]
	s_mov_b32 m0, s18
	s_nop 0
	global_load_lds_dwordx4 v[102:103], off
	v_lshl_add_u64 v[102:103], v[144:145], 0, s[40:41]
	s_mov_b32 m0, s19
	s_nop 0
	global_load_lds_dwordx4 v[102:103], off
	s_waitcnt vmcnt(24)
	s_waitcnt lgkmcnt(0)
	s_barrier
	v_mfma_f32_16x16x32_bf16 v[158:161], v[2:5], v[62:65], 0
	v_mfma_f32_16x16x32_bf16 v[166:169], v[2:5], v[98:101], 0
	v_mfma_f32_16x16x32_bf16 v[174:177], v[2:5], v[116:119], 0
	v_mfma_f32_16x16x32_bf16 v[2:5], v[2:5], v[124:127], 0
	v_mfma_f32_16x16x32_bf16 v[158:161], v[6:9], v[94:97], v[158:161]
	v_mfma_f32_16x16x32_bf16 v[166:169], v[6:9], v[112:115], v[166:169]
	v_mfma_f32_16x16x32_bf16 v[174:177], v[6:9], v[120:123], v[174:177]
	v_mfma_f32_16x16x32_bf16 v[2:5], v[6:9], v[128:131], v[2:5]
	v_mfma_f32_16x16x32_bf16 v[6:9], v[10:13], v[124:127], 0
	v_mfma_f32_16x16x32_bf16 v[162:165], v[10:13], v[62:65], 0
	v_mfma_f32_16x16x32_bf16 v[170:173], v[10:13], v[98:101], 0
	v_mfma_f32_16x16x32_bf16 v[178:181], v[10:13], v[116:119], 0
	v_mfma_f32_16x16x32_bf16 v[6:9], v[14:17], v[128:131], v[6:9]
	v_mfma_f32_16x16x32_bf16 v[162:165], v[14:17], v[94:97], v[162:165]
	v_mfma_f32_16x16x32_bf16 v[170:173], v[14:17], v[112:115], v[170:173]
	v_mfma_f32_16x16x32_bf16 v[178:181], v[14:17], v[120:123], v[178:181]
	v_mfma_f32_16x16x32_bf16 v[14:17], v[26:29], v[62:65], 0
	v_mfma_f32_16x16x32_bf16 v[182:185], v[30:33], v[94:97], v[14:17]
	v_mfma_f32_16x16x32_bf16 v[14:17], v[18:21], v[98:101], 0
	v_mfma_f32_16x16x32_bf16 v[186:189], v[22:25], v[112:115], v[14:17]
	v_mfma_f32_16x16x32_bf16 v[14:17], v[26:29], v[98:101], 0
	v_mfma_f32_16x16x32_bf16 v[190:193], v[30:33], v[112:115], v[14:17]
	v_mfma_f32_16x16x32_bf16 v[14:17], v[18:21], v[116:119], 0
	v_mfma_f32_16x16x32_bf16 v[194:197], v[22:25], v[120:123], v[14:17]
	v_mfma_f32_16x16x32_bf16 v[14:17], v[26:29], v[116:119], 0
	v_mfma_f32_16x16x32_bf16 v[10:13], v[18:21], v[62:65], 0
	v_mfma_f32_16x16x32_bf16 v[198:201], v[30:33], v[120:123], v[14:17]
	v_mfma_f32_16x16x32_bf16 v[14:17], v[18:21], v[124:127], 0
	v_mfma_f32_16x16x32_bf16 v[10:13], v[22:25], v[94:97], v[10:13]
	v_mfma_f32_16x16x32_bf16 v[202:205], v[22:25], v[128:131], v[14:17]
	v_mfma_f32_16x16x32_bf16 v[14:17], v[26:29], v[124:127], 0
	v_mfma_f32_16x16x32_bf16 v[206:209], v[30:33], v[128:131], v[14:17]
	s_barrier
	s_add_i32 s12, 0, 0x18000
	v_add_u32_e32 v1, s12, v151
	s_add_i32 s13, 0, 0x1c000
	s_nop 1
	ds_read_b128 v[14:17], v1
	ds_read_b128 v[24:27], v1 offset:1024
	ds_read_b128 v[28:31], v1 offset:2048
	ds_read_b128 v[210:213], v1 offset:3072
	v_add_u32_e32 v1, s13, v151
	ds_read_b128 v[214:217], v1
	ds_read_b128 v[218:221], v1 offset:1024
	ds_read_b128 v[222:225], v1 offset:2048
	ds_read_b128 v[226:229], v1 offset:3072
	s_add_u32 s0, s48, 0x2b0100
	s_addc_u32 s1, s49, 0
	s_mov_b32 m0, s20
	v_lshl_add_u64 v[22:23], s[0:1], 0, v[132:133]
	ds_read_b128 v[18:21], v155 offset:32768
	ds_read_b128 v[120:123], v155 offset:33792
	ds_read_b128 v[230:233], v155 offset:34816
	ds_read_b128 v[234:237], v155 offset:35840
	ds_read_b128 v[238:241], v155 offset:36864
	ds_read_b128 v[242:245], v155 offset:37888
	ds_read_b128 v[246:249], v155 offset:38912
	ds_read_b128 v[250:253], v155 offset:39936
	global_load_lds_dwordx4 v[22:23], off
	v_lshl_add_u64 v[22:23], s[0:1], 0, v[136:137]
	s_mov_b32 m0, s21
	s_nop 0
	global_load_lds_dwordx4 v[22:23], off
	s_waitcnt vmcnt(24)
	s_waitcnt lgkmcnt(0)
	s_barrier
	v_mfma_f32_16x16x32_bf16 v[62:65], v[14:17], v[18:21], v[66:69]
	v_mfma_f32_16x16x32_bf16 v[128:131], v[24:27], v[120:123], v[62:65]
	v_mfma_f32_16x16x32_bf16 v[62:65], v[28:31], v[18:21], v[70:73]
	v_mfma_f32_16x16x32_bf16 v[116:119], v[210:213], v[120:123], v[62:65]
	v_mfma_f32_16x16x32_bf16 v[62:65], v[14:17], v[230:233], v[74:77]
	v_mfma_f32_16x16x32_bf16 v[112:115], v[24:27], v[234:237], v[62:65]
	v_mfma_f32_16x16x32_bf16 v[62:65], v[28:31], v[230:233], v[78:81]
	v_mfma_f32_16x16x32_bf16 v[100:103], v[210:213], v[234:237], v[62:65]
	v_mfma_f32_16x16x32_bf16 v[62:65], v[14:17], v[238:241], v[82:85]
	v_mfma_f32_16x16x32_bf16 v[96:99], v[24:27], v[242:245], v[62:65]
	v_mfma_f32_16x16x32_bf16 v[62:65], v[28:31], v[238:241], v[86:89]
	v_mfma_f32_16x16x32_bf16 v[84:87], v[210:213], v[242:245], v[62:65]
	v_mfma_f32_16x16x32_bf16 v[62:65], v[14:17], v[246:249], v[90:93]
	v_mfma_f32_16x16x32_bf16 v[80:83], v[24:27], v[250:253], v[62:65]
	v_mfma_f32_16x16x32_bf16 v[62:65], v[28:31], v[246:249], v[104:107]
	v_mfma_f32_16x16x32_bf16 v[64:67], v[210:213], v[250:253], v[62:65]
	v_mfma_f32_16x16x32_bf16 v[68:71], v[214:217], v[18:21], v[108:111]
	v_mfma_f32_16x16x32_bf16 v[18:21], v[222:225], v[18:21], v[34:37]
	v_mfma_f32_16x16x32_bf16 v[124:127], v[218:221], v[120:123], v[68:71]
	v_mfma_f32_16x16x32_bf16 v[120:123], v[226:229], v[120:123], v[18:21]
	v_mfma_f32_16x16x32_bf16 v[18:21], v[214:217], v[230:233], v[38:41]
	v_mfma_f32_16x16x32_bf16 v[108:111], v[218:221], v[234:237], v[18:21]
	v_mfma_f32_16x16x32_bf16 v[18:21], v[222:225], v[230:233], v[42:45]
	v_mfma_f32_16x16x32_bf16 v[104:107], v[226:229], v[234:237], v[18:21]
	v_mfma_f32_16x16x32_bf16 v[18:21], v[214:217], v[238:241], v[46:49]
	v_mfma_f32_16x16x32_bf16 v[92:95], v[218:221], v[242:245], v[18:21]
	v_mfma_f32_16x16x32_bf16 v[18:21], v[222:225], v[238:241], v[50:53]
	v_mfma_f32_16x16x32_bf16 v[88:91], v[226:229], v[242:245], v[18:21]
	v_mfma_f32_16x16x32_bf16 v[18:21], v[214:217], v[246:249], v[54:57]
	v_mfma_f32_16x16x32_bf16 v[72:75], v[218:221], v[250:253], v[18:21]
	v_mfma_f32_16x16x32_bf16 v[18:21], v[222:225], v[246:249], v[58:61]
	v_mfma_f32_16x16x32_bf16 v[68:71], v[226:229], v[250:253], v[18:21]
	s_barrier
	s_add_u32 s0, s46, 0x18000
	s_addc_u32 s1, s47, 0
	s_add_i32 s12, s12, s17
	s_nop 1
	v_lshl_add_u64 v[18:19], s[0:1], 0, v[134:135]
	s_mov_b32 m0, s12
	ds_read_b128 v[40:43], v155 offset:49152
	ds_read_b128 v[44:47], v155 offset:50176
	ds_read_b128 v[230:233], v155 offset:51200
	ds_read_b128 v[234:237], v155 offset:52224
	ds_read_b128 v[238:241], v155 offset:53248
	ds_read_b128 v[242:245], v155 offset:54272
	ds_read_b128 v[246:249], v155 offset:55296
	ds_read_b128 v[250:253], v155 offset:56320
	global_load_lds_dwordx4 v[18:19], off
	s_add_i32 m0, s12, 0x2000
	v_lshl_add_u64 v[18:19], s[0:1], 0, v[138:139]
	s_add_u32 s0, s46, 0x1c000
	s_addc_u32 s1, s47, 0
	s_add_i32 s12, s13, s17
	global_load_lds_dwordx4 v[18:19], off
	v_lshl_add_u64 v[18:19], s[0:1], 0, v[134:135]
	s_mov_b32 m0, s12
	s_nop 0
	global_load_lds_dwordx4 v[18:19], off
	v_lshl_add_u64 v[18:19], s[0:1], 0, v[138:139]
	s_add_i32 m0, s12, 0x2000
	s_nop 0
	global_load_lds_dwordx4 v[18:19], off
	v_lshl_add_u64 v[18:19], v[148:149], 0, s[42:43]
	s_mov_b32 m0, s25
	s_nop 0
	global_load_lds_dwordx4 v[18:19], off
	v_lshl_add_u64 v[18:19], v[144:145], 0, s[42:43]
	s_mov_b32 m0, s33
	s_nop 0
	global_load_lds_dwordx4 v[18:19], off
	s_waitcnt vmcnt(8)
	s_waitcnt lgkmcnt(0)
	s_barrier
	v_mfma_f32_16x16x32_bf16 v[18:21], v[14:17], v[40:43], v[158:161]
	v_mfma_f32_16x16x32_bf16 v[76:79], v[24:27], v[44:47], v[18:21]
	v_mfma_f32_16x16x32_bf16 v[18:21], v[28:31], v[40:43], v[162:165]
	v_mfma_f32_16x16x32_bf16 v[52:55], v[210:213], v[44:47], v[18:21]
	v_mfma_f32_16x16x32_bf16 v[18:21], v[14:17], v[230:233], v[166:169]
	v_mfma_f32_16x16x32_bf16 v[48:51], v[24:27], v[234:237], v[18:21]
	v_mfma_f32_16x16x32_bf16 v[18:21], v[28:31], v[230:233], v[170:173]
	v_mfma_f32_16x16x32_bf16 v[36:39], v[210:213], v[234:237], v[18:21]
	v_mfma_f32_16x16x32_bf16 v[18:21], v[14:17], v[238:241], v[174:177]
	v_mfma_f32_16x16x32_bf16 v[32:35], v[24:27], v[242:245], v[18:21]
	v_mfma_f32_16x16x32_bf16 v[18:21], v[28:31], v[238:241], v[178:181]
	v_mfma_f32_16x16x32_bf16 v[2:5], v[14:17], v[246:249], v[2:5]
	v_mfma_f32_16x16x32_bf16 v[20:23], v[210:213], v[242:245], v[18:21]
	v_mfma_f32_16x16x32_bf16 v[16:19], v[24:27], v[250:253], v[2:5]
	v_mfma_f32_16x16x32_bf16 v[2:5], v[28:31], v[246:249], v[6:9]
	v_mfma_f32_16x16x32_bf16 v[4:7], v[210:213], v[250:253], v[2:5]
	v_mfma_f32_16x16x32_bf16 v[8:11], v[214:217], v[40:43], v[10:13]
	v_mfma_f32_16x16x32_bf16 v[60:63], v[218:221], v[44:47], v[8:11]
	v_mfma_f32_16x16x32_bf16 v[8:11], v[222:225], v[40:43], v[182:185]
	v_mfma_f32_16x16x32_bf16 v[56:59], v[226:229], v[44:47], v[8:11]
	v_mfma_f32_16x16x32_bf16 v[8:11], v[214:217], v[230:233], v[186:189]
	v_mfma_f32_16x16x32_bf16 v[44:47], v[218:221], v[234:237], v[8:11]
	v_mfma_f32_16x16x32_bf16 v[8:11], v[222:225], v[230:233], v[190:193]
	v_mfma_f32_16x16x32_bf16 v[40:43], v[226:229], v[234:237], v[8:11]
	v_mfma_f32_16x16x32_bf16 v[8:11], v[214:217], v[238:241], v[194:197]
	v_mfma_f32_16x16x32_bf16 v[28:31], v[218:221], v[242:245], v[8:11]
	v_mfma_f32_16x16x32_bf16 v[8:11], v[222:225], v[238:241], v[198:201]
	v_mfma_f32_16x16x32_bf16 v[24:27], v[226:229], v[242:245], v[8:11]
	v_mfma_f32_16x16x32_bf16 v[8:11], v[214:217], v[246:249], v[202:205]
	v_mfma_f32_16x16x32_bf16 v[12:15], v[218:221], v[250:253], v[8:11]
	v_mfma_f32_16x16x32_bf16 v[8:11], v[222:225], v[246:249], v[206:209]
	v_mfma_f32_16x16x32_bf16 v[8:11], v[226:229], v[250:253], v[8:11]
	s_barrier
	s_mov_b32 s22, 2
	s_branch .LBB0_895

.LBB0_896:
	ds_read_b128 v[158:161], v153
	ds_read_b128 v[162:165], v153 offset:1024
	ds_read_b128 v[166:169], v153 offset:2048
	ds_read_b128 v[170:173], v153 offset:3072
	ds_read_b128 v[174:177], v154
	ds_read_b128 v[178:181], v154 offset:1024
	ds_read_b128 v[182:185], v154 offset:2048
	ds_read_b128 v[186:189], v154 offset:3072
	s_add_u32 s12, s60, s26
	s_addc_u32 s13, s61, 0
	s_cmp_eq_u32 s26, s46
	s_cselect_b32 s23, s9, s13
	s_cselect_b32 s22, s8, s12
	s_cselect_b32 s49, s45, s59
	s_cselect_b32 s48, s44, s1
	s_add_i32 s63, s18, 0xc000
	v_lshl_add_u64 v[144:145], v[2:3], 0, s[26:27]
	s_mov_b32 m0, s63
	s_add_i32 s62, s18, 0xe000
	ds_read_b128 v[190:193], v155
	ds_read_b128 v[194:197], v155 offset:1024
	ds_read_b128 v[198:201], v155 offset:2048
	ds_read_b128 v[202:205], v155 offset:3072
	ds_read_b128 v[206:209], v155 offset:4096
	ds_read_b128 v[210:213], v155 offset:5120
	ds_read_b128 v[214:217], v155 offset:6144
	ds_read_b128 v[218:221], v155 offset:7168
	global_load_lds_dwordx4 v[144:145], off
	v_lshl_add_u64 v[144:145], v[148:149], 0, s[26:27]
	s_mov_b32 m0, s62
	s_nop 0
	global_load_lds_dwordx4 v[144:145], off
	s_waitcnt vmcnt(8)
	s_waitcnt lgkmcnt(0)
	s_barrier
	v_mfma_f32_16x16x32_bf16 v[128:131], v[158:161], v[190:193], v[128:131]
	v_mfma_f32_16x16x32_bf16 v[116:119], v[166:169], v[190:193], v[116:119]
	v_mfma_f32_16x16x32_bf16 v[112:115], v[158:161], v[198:201], v[112:115]
	v_mfma_f32_16x16x32_bf16 v[100:103], v[166:169], v[198:201], v[100:103]
	v_mfma_f32_16x16x32_bf16 v[96:99], v[158:161], v[206:209], v[96:99]
	v_mfma_f32_16x16x32_bf16 v[84:87], v[166:169], v[206:209], v[84:87]
	v_mfma_f32_16x16x32_bf16 v[80:83], v[158:161], v[214:217], v[80:83]
	v_mfma_f32_16x16x32_bf16 v[64:67], v[166:169], v[214:217], v[64:67]
	v_mfma_f32_16x16x32_bf16 v[128:131], v[162:165], v[194:197], v[128:131]
	v_mfma_f32_16x16x32_bf16 v[116:119], v[170:173], v[194:197], v[116:119]
	v_mfma_f32_16x16x32_bf16 v[112:115], v[162:165], v[202:205], v[112:115]
	v_mfma_f32_16x16x32_bf16 v[100:103], v[170:173], v[202:205], v[100:103]
	v_mfma_f32_16x16x32_bf16 v[96:99], v[162:165], v[210:213], v[96:99]
	v_mfma_f32_16x16x32_bf16 v[84:87], v[170:173], v[210:213], v[84:87]
	v_mfma_f32_16x16x32_bf16 v[80:83], v[162:165], v[218:221], v[80:83]
	v_mfma_f32_16x16x32_bf16 v[64:67], v[170:173], v[218:221], v[64:67]
	v_mfma_f32_16x16x32_bf16 v[124:127], v[174:177], v[190:193], v[124:127]
	v_mfma_f32_16x16x32_bf16 v[120:123], v[182:185], v[190:193], v[120:123]
	v_mfma_f32_16x16x32_bf16 v[108:111], v[174:177], v[198:201], v[108:111]
	v_mfma_f32_16x16x32_bf16 v[104:107], v[182:185], v[198:201], v[104:107]
	v_mfma_f32_16x16x32_bf16 v[92:95], v[174:177], v[206:209], v[92:95]
	v_mfma_f32_16x16x32_bf16 v[88:91], v[182:185], v[206:209], v[88:91]
	v_mfma_f32_16x16x32_bf16 v[72:75], v[174:177], v[214:217], v[72:75]
	v_mfma_f32_16x16x32_bf16 v[68:71], v[182:185], v[214:217], v[68:71]
	v_mfma_f32_16x16x32_bf16 v[124:127], v[178:181], v[194:197], v[124:127]
	v_mfma_f32_16x16x32_bf16 v[120:123], v[186:189], v[194:197], v[120:123]
	v_mfma_f32_16x16x32_bf16 v[108:111], v[178:181], v[202:205], v[108:111]
	v_mfma_f32_16x16x32_bf16 v[104:107], v[186:189], v[202:205], v[104:107]
	v_mfma_f32_16x16x32_bf16 v[92:95], v[178:181], v[210:213], v[92:95]
	v_mfma_f32_16x16x32_bf16 v[88:91], v[186:189], v[210:213], v[88:91]
	v_mfma_f32_16x16x32_bf16 v[72:75], v[178:181], v[218:221], v[72:75]
	v_mfma_f32_16x16x32_bf16 v[68:71], v[186:189], v[218:221], v[68:71]
	s_barrier
	s_add_i32 s12, s52, s17
	v_lshl_add_u64 v[144:145], s[48:49], 0, v[134:135]
	s_mov_b32 m0, s12
	ds_read_b128 v[190:193], v155 offset:16384
	ds_read_b128 v[194:197], v155 offset:17408
	ds_read_b128 v[198:201], v155 offset:18432
	ds_read_b128 v[202:205], v155 offset:19456
	ds_read_b128 v[206:209], v155 offset:20480
	ds_read_b128 v[210:213], v155 offset:21504
	ds_read_b128 v[214:217], v155 offset:22528
	ds_read_b128 v[218:221], v155 offset:23552
	global_load_lds_dwordx4 v[144:145], off
	s_add_i32 m0, s12, 0x2000
	s_add_u32 s12, s48, 0x4000
	v_lshl_add_u64 v[144:145], s[48:49], 0, v[138:139]
	s_addc_u32 s13, s49, 0
	s_add_i32 s14, s53, s17
	global_load_lds_dwordx4 v[144:145], off
	v_lshl_add_u64 v[144:145], s[12:13], 0, v[134:135]
	s_mov_b32 m0, s14
	v_lshl_add_u64 v[222:223], s[22:23], 0, v[136:137]
	global_load_lds_dwordx4 v[144:145], off
	v_lshl_add_u64 v[144:145], s[12:13], 0, v[138:139]
	s_add_i32 m0, s14, 0x2000
	s_nop 0
	global_load_lds_dwordx4 v[144:145], off
	v_lshl_add_u64 v[144:145], s[22:23], 0, v[132:133]
	s_mov_b32 m0, s18
	s_nop 0
	global_load_lds_dwordx4 v[144:145], off
	s_mov_b32 m0, s19
	s_nop 0
	global_load_lds_dwordx4 v[222:223], off
	s_waitcnt vmcnt(8)
	s_waitcnt lgkmcnt(0)
	s_barrier
	v_mfma_f32_16x16x32_bf16 v[76:79], v[158:161], v[190:193], v[76:79]
	v_mfma_f32_16x16x32_bf16 v[52:55], v[166:169], v[190:193], v[52:55]
	v_mfma_f32_16x16x32_bf16 v[48:51], v[158:161], v[198:201], v[48:51]
	v_mfma_f32_16x16x32_bf16 v[36:39], v[166:169], v[198:201], v[36:39]
	v_mfma_f32_16x16x32_bf16 v[32:35], v[158:161], v[206:209], v[32:35]
	v_mfma_f32_16x16x32_bf16 v[20:23], v[166:169], v[206:209], v[20:23]
	v_mfma_f32_16x16x32_bf16 v[16:19], v[158:161], v[214:217], v[16:19]
	v_mfma_f32_16x16x32_bf16 v[4:7], v[166:169], v[214:217], v[4:7]
	v_mfma_f32_16x16x32_bf16 v[76:79], v[162:165], v[194:197], v[76:79]
	v_mfma_f32_16x16x32_bf16 v[52:55], v[170:173], v[194:197], v[52:55]
	v_mfma_f32_16x16x32_bf16 v[48:51], v[162:165], v[202:205], v[48:51]
	v_mfma_f32_16x16x32_bf16 v[36:39], v[170:173], v[202:205], v[36:39]
	v_mfma_f32_16x16x32_bf16 v[32:35], v[162:165], v[210:213], v[32:35]
	v_mfma_f32_16x16x32_bf16 v[20:23], v[170:173], v[210:213], v[20:23]
	v_mfma_f32_16x16x32_bf16 v[16:19], v[162:165], v[218:221], v[16:19]
	v_mfma_f32_16x16x32_bf16 v[4:7], v[170:173], v[218:221], v[4:7]
	v_mfma_f32_16x16x32_bf16 v[60:63], v[174:177], v[190:193], v[60:63]
	v_mfma_f32_16x16x32_bf16 v[56:59], v[182:185], v[190:193], v[56:59]
	v_mfma_f32_16x16x32_bf16 v[44:47], v[174:177], v[198:201], v[44:47]
	v_mfma_f32_16x16x32_bf16 v[40:43], v[182:185], v[198:201], v[40:43]
	v_mfma_f32_16x16x32_bf16 v[28:31], v[174:177], v[206:209], v[28:31]
	v_mfma_f32_16x16x32_bf16 v[24:27], v[182:185], v[206:209], v[24:27]
	v_mfma_f32_16x16x32_bf16 v[12:15], v[174:177], v[214:217], v[12:15]
	v_mfma_f32_16x16x32_bf16 v[8:11], v[182:185], v[214:217], v[8:11]
	v_mfma_f32_16x16x32_bf16 v[60:63], v[178:181], v[194:197], v[60:63]
	v_mfma_f32_16x16x32_bf16 v[56:59], v[186:189], v[194:197], v[56:59]
	v_mfma_f32_16x16x32_bf16 v[44:47], v[178:181], v[202:205], v[44:47]
	v_mfma_f32_16x16x32_bf16 v[40:43], v[186:189], v[202:205], v[40:43]
	v_mfma_f32_16x16x32_bf16 v[28:31], v[178:181], v[210:213], v[28:31]
	v_mfma_f32_16x16x32_bf16 v[24:27], v[186:189], v[210:213], v[24:27]
	v_mfma_f32_16x16x32_bf16 v[12:15], v[178:181], v[218:221], v[12:15]
	v_mfma_f32_16x16x32_bf16 v[8:11], v[186:189], v[218:221], v[8:11]
	s_barrier
	s_add_i32 s14, 0, 0x18000
	v_add_u32_e32 v1, s14, v151
	s_add_i32 s64, 0, 0x1c000
	ds_read_b128 v[158:161], v1
	ds_read_b128 v[162:165], v1 offset:1024
	ds_read_b128 v[166:169], v1 offset:2048
	ds_read_b128 v[170:173], v1 offset:3072
	v_add_u32_e32 v1, s64, v151
	ds_read_b128 v[174:177], v1
	ds_read_b128 v[178:181], v1 offset:1024
	ds_read_b128 v[182:185], v1 offset:2048
	ds_read_b128 v[186:189], v1 offset:3072
	s_add_u32 s12, s22, 0x2b0000
	s_addc_u32 s13, s23, 0
	s_mov_b32 m0, s20
	v_lshl_add_u64 v[224:225], s[12:13], 0, v[132:133]
	ds_read_b128 v[190:193], v155 offset:32768
	ds_read_b128 v[194:197], v155 offset:33792
	ds_read_b128 v[198:201], v155 offset:34816
	ds_read_b128 v[202:205], v155 offset:35840
	ds_read_b128 v[206:209], v155 offset:36864
	ds_read_b128 v[210:213], v155 offset:37888
	ds_read_b128 v[214:217], v155 offset:38912
	ds_read_b128 v[218:221], v155 offset:39936
	global_load_lds_dwordx4 v[224:225], off
	v_lshl_add_u64 v[224:225], s[12:13], 0, v[136:137]
	s_mov_b32 m0, s21
	s_nop 0
	global_load_lds_dwordx4 v[224:225], off
	s_waitcnt vmcnt(8)
	s_waitcnt lgkmcnt(0)
	s_barrier
	v_mfma_f32_16x16x32_bf16 v[128:131], v[158:161], v[190:193], v[128:131]
	v_mfma_f32_16x16x32_bf16 v[116:119], v[166:169], v[190:193], v[116:119]
	v_mfma_f32_16x16x32_bf16 v[112:115], v[158:161], v[198:201], v[112:115]
	v_mfma_f32_16x16x32_bf16 v[100:103], v[166:169], v[198:201], v[100:103]
	v_mfma_f32_16x16x32_bf16 v[96:99], v[158:161], v[206:209], v[96:99]
	v_mfma_f32_16x16x32_bf16 v[84:87], v[166:169], v[206:209], v[84:87]
	v_mfma_f32_16x16x32_bf16 v[80:83], v[158:161], v[214:217], v[80:83]
	v_mfma_f32_16x16x32_bf16 v[64:67], v[166:169], v[214:217], v[64:67]
	v_mfma_f32_16x16x32_bf16 v[128:131], v[162:165], v[194:197], v[128:131]
	v_mfma_f32_16x16x32_bf16 v[116:119], v[170:173], v[194:197], v[116:119]
	v_mfma_f32_16x16x32_bf16 v[112:115], v[162:165], v[202:205], v[112:115]
	v_mfma_f32_16x16x32_bf16 v[100:103], v[170:173], v[202:205], v[100:103]
	v_mfma_f32_16x16x32_bf16 v[96:99], v[162:165], v[210:213], v[96:99]
	v_mfma_f32_16x16x32_bf16 v[84:87], v[170:173], v[210:213], v[84:87]
	v_mfma_f32_16x16x32_bf16 v[80:83], v[162:165], v[218:221], v[80:83]
	v_mfma_f32_16x16x32_bf16 v[64:67], v[170:173], v[218:221], v[64:67]
	v_mfma_f32_16x16x32_bf16 v[124:127], v[174:177], v[190:193], v[124:127]
	v_mfma_f32_16x16x32_bf16 v[120:123], v[182:185], v[190:193], v[120:123]
	v_mfma_f32_16x16x32_bf16 v[108:111], v[174:177], v[198:201], v[108:111]
	v_mfma_f32_16x16x32_bf16 v[104:107], v[182:185], v[198:201], v[104:107]
	v_mfma_f32_16x16x32_bf16 v[92:95], v[174:177], v[206:209], v[92:95]
	v_mfma_f32_16x16x32_bf16 v[88:91], v[182:185], v[206:209], v[88:91]
	v_mfma_f32_16x16x32_bf16 v[72:75], v[174:177], v[214:217], v[72:75]
	v_mfma_f32_16x16x32_bf16 v[68:71], v[182:185], v[214:217], v[68:71]
	v_mfma_f32_16x16x32_bf16 v[124:127], v[178:181], v[194:197], v[124:127]
	v_mfma_f32_16x16x32_bf16 v[120:123], v[186:189], v[194:197], v[120:123]
	v_mfma_f32_16x16x32_bf16 v[108:111], v[178:181], v[202:205], v[108:111]
	v_mfma_f32_16x16x32_bf16 v[104:107], v[186:189], v[202:205], v[104:107]
	v_mfma_f32_16x16x32_bf16 v[92:95], v[178:181], v[210:213], v[92:95]
	v_mfma_f32_16x16x32_bf16 v[88:91], v[186:189], v[210:213], v[88:91]
	v_mfma_f32_16x16x32_bf16 v[72:75], v[178:181], v[218:221], v[72:75]
	v_mfma_f32_16x16x32_bf16 v[68:71], v[186:189], v[218:221], v[68:71]
	s_barrier
	s_add_u32 s12, s48, 0x8000
	s_addc_u32 s13, s49, 0
	s_add_i32 s14, s14, s17
	v_lshl_add_u64 v[224:225], s[12:13], 0, v[134:135]
	s_mov_b32 m0, s14
	ds_read_b128 v[190:193], v155 offset:49152
	ds_read_b128 v[194:197], v155 offset:50176
	ds_read_b128 v[198:201], v155 offset:51200
	ds_read_b128 v[202:205], v155 offset:52224
	ds_read_b128 v[206:209], v155 offset:53248
	ds_read_b128 v[210:213], v155 offset:54272
	ds_read_b128 v[214:217], v155 offset:55296
	ds_read_b128 v[218:221], v155 offset:56320
	global_load_lds_dwordx4 v[224:225], off
	s_add_i32 m0, s14, 0x2000
	v_lshl_add_u64 v[224:225], s[12:13], 0, v[138:139]
	s_add_u32 s12, s48, 0xc000
	s_addc_u32 s13, s49, 0
	s_add_i32 s14, s64, s17
	global_load_lds_dwordx4 v[224:225], off
	v_lshl_add_u64 v[224:225], s[12:13], 0, v[134:135]
	s_mov_b32 m0, s14
	v_lshl_add_u64 v[144:145], v[144:145], 0, s[36:37]
	global_load_lds_dwordx4 v[224:225], off
	v_lshl_add_u64 v[224:225], s[12:13], 0, v[138:139]
	s_add_i32 m0, s14, 0x2000
	s_nop 0
	global_load_lds_dwordx4 v[224:225], off
	s_mov_b32 m0, s25
	s_nop 0
	global_load_lds_dwordx4 v[144:145], off
	v_lshl_add_u64 v[144:145], v[222:223], 0, s[36:37]
	s_mov_b32 m0, s33
	s_nop 0
	global_load_lds_dwordx4 v[144:145], off
	s_waitcnt vmcnt(8)
	s_waitcnt lgkmcnt(0)
	s_barrier
	v_mfma_f32_16x16x32_bf16 v[76:79], v[158:161], v[190:193], v[76:79]
	v_mfma_f32_16x16x32_bf16 v[52:55], v[166:169], v[190:193], v[52:55]
	v_mfma_f32_16x16x32_bf16 v[48:51], v[158:161], v[198:201], v[48:51]
	v_mfma_f32_16x16x32_bf16 v[36:39], v[166:169], v[198:201], v[36:39]
	v_mfma_f32_16x16x32_bf16 v[32:35], v[158:161], v[206:209], v[32:35]
	v_mfma_f32_16x16x32_bf16 v[20:23], v[166:169], v[206:209], v[20:23]
	v_mfma_f32_16x16x32_bf16 v[16:19], v[158:161], v[214:217], v[16:19]
	v_mfma_f32_16x16x32_bf16 v[4:7], v[166:169], v[214:217], v[4:7]
	v_mfma_f32_16x16x32_bf16 v[76:79], v[162:165], v[194:197], v[76:79]
	v_mfma_f32_16x16x32_bf16 v[52:55], v[170:173], v[194:197], v[52:55]
	v_mfma_f32_16x16x32_bf16 v[48:51], v[162:165], v[202:205], v[48:51]
	v_mfma_f32_16x16x32_bf16 v[36:39], v[170:173], v[202:205], v[36:39]
	v_mfma_f32_16x16x32_bf16 v[32:35], v[162:165], v[210:213], v[32:35]
	v_mfma_f32_16x16x32_bf16 v[20:23], v[170:173], v[210:213], v[20:23]
	v_mfma_f32_16x16x32_bf16 v[16:19], v[162:165], v[218:221], v[16:19]
	v_mfma_f32_16x16x32_bf16 v[4:7], v[170:173], v[218:221], v[4:7]
	v_mfma_f32_16x16x32_bf16 v[60:63], v[174:177], v[190:193], v[60:63]
	v_mfma_f32_16x16x32_bf16 v[56:59], v[182:185], v[190:193], v[56:59]
	v_mfma_f32_16x16x32_bf16 v[44:47], v[174:177], v[198:201], v[44:47]
	v_mfma_f32_16x16x32_bf16 v[40:43], v[182:185], v[198:201], v[40:43]
	v_mfma_f32_16x16x32_bf16 v[28:31], v[174:177], v[206:209], v[28:31]
	v_mfma_f32_16x16x32_bf16 v[24:27], v[182:185], v[206:209], v[24:27]
	v_mfma_f32_16x16x32_bf16 v[12:15], v[174:177], v[214:217], v[12:15]
	v_mfma_f32_16x16x32_bf16 v[8:11], v[182:185], v[214:217], v[8:11]
	v_mfma_f32_16x16x32_bf16 v[60:63], v[178:181], v[194:197], v[60:63]
	v_mfma_f32_16x16x32_bf16 v[56:59], v[186:189], v[194:197], v[56:59]
	v_mfma_f32_16x16x32_bf16 v[44:47], v[178:181], v[202:205], v[44:47]
	v_mfma_f32_16x16x32_bf16 v[40:43], v[186:189], v[202:205], v[40:43]
	v_mfma_f32_16x16x32_bf16 v[28:31], v[178:181], v[210:213], v[28:31]
	v_mfma_f32_16x16x32_bf16 v[24:27], v[186:189], v[210:213], v[24:27]
	v_mfma_f32_16x16x32_bf16 v[12:15], v[178:181], v[218:221], v[12:15]
	v_mfma_f32_16x16x32_bf16 v[8:11], v[186:189], v[218:221], v[8:11]
	s_barrier
	s_add_i32 s0, s0, 2
	s_add_u32 s1, s1, 0x10000
	s_addc_u32 s59, s59, 0
	s_add_u32 s60, s60, 0x100
	s_addc_u32 s61, s61, 0
	s_add_u32 s46, s46, 0xffffff00
	s_addc_u32 s47, s47, -1
	v_lshl_add_u64 v[2:3], v[2:3], 0, s[40:41]
	s_cmpk_gt_u32 s0, 0xa9
	v_lshl_add_u64 v[148:149], v[148:149], 0, s[40:41]
	s_cbranch_scc0 .LBB0_896
	s_and_b64 vcc, exec, s[38:39]
	s_cbranch_vccz .LBB0_899
	s_barrier

.LBB0_1049:
	s_cmp_lg_u32 s45, 0
	s_mov_b32 s22, 0
	s_cbranch_scc0 .LBB0_1051
	ds_read_b128 v[2:5], v155
	ds_read_b128 v[6:9], v155 offset:1024
	ds_read_b128 v[10:13], v155 offset:2048
	ds_read_b128 v[14:17], v155 offset:3072
	ds_read_b128 v[18:21], v156
	ds_read_b128 v[22:25], v156 offset:1024
	ds_read_b128 v[26:29], v156 offset:2048
	ds_read_b128 v[30:33], v156 offset:3072
	s_add_u32 s0, s52, 0x10000
	s_addc_u32 s1, s53, 0
	ds_read_b128 v[34:37], v157
	ds_read_b128 v[38:41], v157 offset:1024
	ds_read_b128 v[42:45], v157 offset:2048
	ds_read_b128 v[46:49], v157 offset:3072
	ds_read_b128 v[50:53], v157 offset:4096
	ds_read_b128 v[54:57], v157 offset:5120
	ds_read_b128 v[58:61], v157 offset:6144
	ds_read_b128 v[62:65], v157 offset:7168
	s_waitcnt vmcnt(24)
	s_waitcnt lgkmcnt(0)
	s_barrier
	v_mfma_f32_16x16x32_bf16 v[90:93], v[2:5], v[58:61], 0
	v_mfma_f32_16x16x32_bf16 v[66:69], v[2:5], v[34:37], 0
	v_mfma_f32_16x16x32_bf16 v[70:73], v[10:13], v[34:37], 0
	v_mfma_f32_16x16x32_bf16 v[74:77], v[2:5], v[42:45], 0
	v_mfma_f32_16x16x32_bf16 v[78:81], v[10:13], v[42:45], 0
	v_mfma_f32_16x16x32_bf16 v[82:85], v[2:5], v[50:53], 0
	v_mfma_f32_16x16x32_bf16 v[86:89], v[10:13], v[50:53], 0
	v_mfma_f32_16x16x32_bf16 v[100:103], v[6:9], v[62:65], v[90:93]
	v_mfma_f32_16x16x32_bf16 v[90:93], v[10:13], v[58:61], 0
	v_mfma_f32_16x16x32_bf16 v[66:69], v[6:9], v[38:41], v[66:69]
	v_mfma_f32_16x16x32_bf16 v[70:73], v[14:17], v[38:41], v[70:73]
	v_mfma_f32_16x16x32_bf16 v[74:77], v[6:9], v[46:49], v[74:77]
	v_mfma_f32_16x16x32_bf16 v[78:81], v[14:17], v[46:49], v[78:81]
	v_mfma_f32_16x16x32_bf16 v[82:85], v[6:9], v[54:57], v[82:85]
	v_mfma_f32_16x16x32_bf16 v[86:89], v[14:17], v[54:57], v[86:89]
	v_mfma_f32_16x16x32_bf16 v[104:107], v[14:17], v[62:65], v[90:93]
	v_mfma_f32_16x16x32_bf16 v[90:93], v[18:21], v[34:37], 0
	v_mfma_f32_16x16x32_bf16 v[34:37], v[26:29], v[34:37], 0
	v_mfma_f32_16x16x32_bf16 v[116:119], v[22:25], v[38:41], v[90:93]
	v_mfma_f32_16x16x32_bf16 v[34:37], v[30:33], v[38:41], v[34:37]
	v_mfma_f32_16x16x32_bf16 v[38:41], v[18:21], v[42:45], 0
	v_mfma_f32_16x16x32_bf16 v[42:45], v[26:29], v[42:45], 0
	v_mfma_f32_16x16x32_bf16 v[38:41], v[22:25], v[46:49], v[38:41]
	v_mfma_f32_16x16x32_bf16 v[42:45], v[30:33], v[46:49], v[42:45]
	v_mfma_f32_16x16x32_bf16 v[46:49], v[18:21], v[50:53], 0
	v_mfma_f32_16x16x32_bf16 v[50:53], v[26:29], v[50:53], 0
	v_mfma_f32_16x16x32_bf16 v[46:49], v[22:25], v[54:57], v[46:49]
	v_mfma_f32_16x16x32_bf16 v[50:53], v[30:33], v[54:57], v[50:53]
	v_mfma_f32_16x16x32_bf16 v[54:57], v[18:21], v[58:61], 0
	v_mfma_f32_16x16x32_bf16 v[58:61], v[26:29], v[58:61], 0
	v_mfma_f32_16x16x32_bf16 v[54:57], v[22:25], v[62:65], v[54:57]
	v_mfma_f32_16x16x32_bf16 v[58:61], v[30:33], v[62:65], v[58:61]
	s_barrier
	s_add_i32 s12, s58, s20
	v_lshl_add_u64 v[98:99], s[0:1], 0, v[134:135]
	s_mov_b32 m0, s12
	ds_read_b128 v[62:65], v157 offset:16384
	ds_read_b128 v[90:93], v157 offset:17408
	ds_read_b128 v[94:97], v157 offset:18432
	ds_read_b128 v[108:111], v157 offset:19456
	ds_read_b128 v[112:115], v157 offset:20480
	ds_read_b128 v[120:123], v157 offset:21504
	ds_read_b128 v[124:127], v157 offset:22528
	ds_read_b128 v[128:131], v157 offset:23552
	global_load_lds_dwordx4 v[98:99], off
	s_add_i32 m0, s12, 0x2000
	v_lshl_add_u64 v[98:99], s[0:1], 0, v[138:139]
	s_add_u32 s0, s52, 0x14000
	s_addc_u32 s1, s53, 0
	s_add_i32 s12, s59, s20
	global_load_lds_dwordx4 v[98:99], off
	v_lshl_add_u64 v[98:99], s[0:1], 0, v[134:135]
	s_mov_b32 m0, s12
	v_lshl_add_u64 v[150:151], s[6:7], 0, v[132:133]
	global_load_lds_dwordx4 v[98:99], off
	v_lshl_add_u64 v[98:99], s[0:1], 0, v[138:139]
	s_add_i32 m0, s12, 0x2000
	v_lshl_add_u64 v[252:253], s[6:7], 0, v[136:137]
	global_load_lds_dwordx4 v[98:99], off
	v_lshl_add_u64 v[98:99], v[150:151], 0, s[36:37]
	s_mov_b32 m0, s21
	s_nop 0
	global_load_lds_dwordx4 v[98:99], off
	v_lshl_add_u64 v[98:99], v[252:253], 0, s[36:37]
	s_mov_b32 m0, s24
	s_nop 0
	global_load_lds_dwordx4 v[98:99], off
	s_waitcnt vmcnt(24)
	s_waitcnt lgkmcnt(0)
	s_barrier
	v_mfma_f32_16x16x32_bf16 v[160:163], v[2:5], v[62:65], 0
	v_mfma_f32_16x16x32_bf16 v[168:171], v[2:5], v[94:97], 0
	v_mfma_f32_16x16x32_bf16 v[176:179], v[2:5], v[112:115], 0
	v_mfma_f32_16x16x32_bf16 v[2:5], v[2:5], v[124:127], 0
	v_mfma_f32_16x16x32_bf16 v[160:163], v[6:9], v[90:93], v[160:163]
	v_mfma_f32_16x16x32_bf16 v[168:171], v[6:9], v[108:111], v[168:171]
	v_mfma_f32_16x16x32_bf16 v[176:179], v[6:9], v[120:123], v[176:179]
	v_mfma_f32_16x16x32_bf16 v[2:5], v[6:9], v[128:131], v[2:5]
	v_mfma_f32_16x16x32_bf16 v[6:9], v[10:13], v[124:127], 0
	v_mfma_f32_16x16x32_bf16 v[164:167], v[10:13], v[62:65], 0
	v_mfma_f32_16x16x32_bf16 v[172:175], v[10:13], v[94:97], 0
	v_mfma_f32_16x16x32_bf16 v[180:183], v[10:13], v[112:115], 0
	v_mfma_f32_16x16x32_bf16 v[6:9], v[14:17], v[128:131], v[6:9]
	v_mfma_f32_16x16x32_bf16 v[164:167], v[14:17], v[90:93], v[164:167]
	v_mfma_f32_16x16x32_bf16 v[172:175], v[14:17], v[108:111], v[172:175]
	v_mfma_f32_16x16x32_bf16 v[180:183], v[14:17], v[120:123], v[180:183]
	v_mfma_f32_16x16x32_bf16 v[10:13], v[18:21], v[62:65], 0
	v_mfma_f32_16x16x32_bf16 v[184:187], v[22:25], v[90:93], v[10:13]
	v_mfma_f32_16x16x32_bf16 v[10:13], v[26:29], v[62:65], 0
	v_mfma_f32_16x16x32_bf16 v[188:191], v[30:33], v[90:93], v[10:13]
	v_mfma_f32_16x16x32_bf16 v[10:13], v[18:21], v[94:97], 0
	v_mfma_f32_16x16x32_bf16 v[192:195], v[22:25], v[108:111], v[10:13]
	v_mfma_f32_16x16x32_bf16 v[10:13], v[26:29], v[94:97], 0
	v_mfma_f32_16x16x32_bf16 v[196:199], v[30:33], v[108:111], v[10:13]
	v_mfma_f32_16x16x32_bf16 v[10:13], v[18:21], v[112:115], 0
	v_mfma_f32_16x16x32_bf16 v[200:203], v[22:25], v[120:123], v[10:13]
	v_mfma_f32_16x16x32_bf16 v[10:13], v[26:29], v[112:115], 0
	v_mfma_f32_16x16x32_bf16 v[204:207], v[30:33], v[120:123], v[10:13]
	v_mfma_f32_16x16x32_bf16 v[10:13], v[18:21], v[124:127], 0
	v_mfma_f32_16x16x32_bf16 v[208:211], v[22:25], v[128:131], v[10:13]
	v_mfma_f32_16x16x32_bf16 v[10:13], v[26:29], v[124:127], 0
	v_mfma_f32_16x16x32_bf16 v[212:215], v[30:33], v[128:131], v[10:13]
	s_barrier
	s_add_i32 s12, 0, 0x18000
	v_add_u32_e32 v0, s12, v154
	s_add_i32 s13, 0, 0x1c000
	s_nop 1
	ds_read_b128 v[10:13], v0
	ds_read_b128 v[14:17], v0 offset:1024
	ds_read_b128 v[20:23], v0 offset:2048
	ds_read_b128 v[24:27], v0 offset:3072
	v_add_u32_e32 v0, s13, v154
	ds_read_b128 v[216:219], v0
	ds_read_b128 v[220:223], v0 offset:1024
	ds_read_b128 v[224:227], v0 offset:2048
	ds_read_b128 v[228:231], v0 offset:3072
	s_add_u32 s0, s6, 0x100100
	s_addc_u32 s1, s7, 0
	s_mov_b32 m0, s25
	v_lshl_add_u64 v[18:19], s[0:1], 0, v[132:133]
	ds_read_b128 v[28:31], v157 offset:32768
	ds_read_b128 v[62:65], v157 offset:33792
	ds_read_b128 v[232:235], v157 offset:34816
	ds_read_b128 v[236:239], v157 offset:35840
	ds_read_b128 v[240:243], v157 offset:36864
	ds_read_b128 v[244:247], v157 offset:37888
	ds_read_b128 v[248:251], v157 offset:38912
	ds_read_b128 v[146:149], v157 offset:39936
	global_load_lds_dwordx4 v[18:19], off
	v_lshl_add_u64 v[18:19], s[0:1], 0, v[136:137]
	s_mov_b32 m0, s33
	s_nop 0
	global_load_lds_dwordx4 v[18:19], off
	s_waitcnt vmcnt(24)
	s_waitcnt lgkmcnt(0)
	s_barrier
	v_mfma_f32_16x16x32_bf16 v[66:69], v[10:13], v[28:31], v[66:69]
	v_mfma_f32_16x16x32_bf16 v[128:131], v[14:17], v[62:65], v[66:69]
	v_mfma_f32_16x16x32_bf16 v[66:69], v[20:23], v[28:31], v[70:73]
	v_mfma_f32_16x16x32_bf16 v[124:127], v[24:27], v[62:65], v[66:69]
	v_mfma_f32_16x16x32_bf16 v[66:69], v[10:13], v[232:235], v[74:77]
	v_mfma_f32_16x16x32_bf16 v[112:115], v[14:17], v[236:239], v[66:69]
	v_mfma_f32_16x16x32_bf16 v[66:69], v[20:23], v[232:235], v[78:81]
	v_mfma_f32_16x16x32_bf16 v[108:111], v[24:27], v[236:239], v[66:69]
	v_mfma_f32_16x16x32_bf16 v[66:69], v[10:13], v[240:243], v[82:85]
	v_mfma_f32_16x16x32_bf16 v[96:99], v[14:17], v[244:247], v[66:69]
	v_mfma_f32_16x16x32_bf16 v[66:69], v[20:23], v[240:243], v[86:89]
	v_mfma_f32_16x16x32_bf16 v[92:95], v[24:27], v[244:247], v[66:69]
	v_mfma_f32_16x16x32_bf16 v[66:69], v[10:13], v[248:251], v[100:103]
	v_mfma_f32_16x16x32_bf16 v[80:83], v[14:17], v[146:149], v[66:69]
	v_mfma_f32_16x16x32_bf16 v[66:69], v[20:23], v[248:251], v[104:107]
	v_mfma_f32_16x16x32_bf16 v[76:79], v[24:27], v[146:149], v[66:69]
	v_mfma_f32_16x16x32_bf16 v[66:69], v[216:219], v[28:31], v[116:119]
	v_mfma_f32_16x16x32_bf16 v[28:31], v[224:227], v[28:31], v[34:37]
	v_mfma_f32_16x16x32_bf16 v[116:119], v[228:231], v[62:65], v[28:31]
	v_mfma_f32_16x16x32_bf16 v[28:31], v[216:219], v[232:235], v[38:41]
	v_mfma_f32_16x16x32_bf16 v[104:107], v[220:223], v[236:239], v[28:31]
	v_mfma_f32_16x16x32_bf16 v[28:31], v[224:227], v[232:235], v[42:45]
	v_mfma_f32_16x16x32_bf16 v[100:103], v[228:231], v[236:239], v[28:31]
	v_mfma_f32_16x16x32_bf16 v[28:31], v[216:219], v[240:243], v[46:49]
	v_mfma_f32_16x16x32_bf16 v[88:91], v[220:223], v[244:247], v[28:31]
	v_mfma_f32_16x16x32_bf16 v[28:31], v[224:227], v[240:243], v[50:53]
	v_mfma_f32_16x16x32_bf16 v[84:87], v[228:231], v[244:247], v[28:31]
	v_mfma_f32_16x16x32_bf16 v[28:31], v[216:219], v[248:251], v[54:57]
	v_mfma_f32_16x16x32_bf16 v[120:123], v[220:223], v[62:65], v[66:69]
	v_mfma_f32_16x16x32_bf16 v[64:67], v[220:223], v[146:149], v[28:31]
	v_mfma_f32_16x16x32_bf16 v[28:31], v[224:227], v[248:251], v[58:61]
	v_mfma_f32_16x16x32_bf16 v[60:63], v[228:231], v[146:149], v[28:31]
	s_barrier
	s_add_u32 s0, s52, 0x18000
	s_addc_u32 s1, s53, 0
	s_add_i32 s12, s12, s20
	v_lshl_add_u64 v[18:19], s[0:1], 0, v[134:135]
	s_mov_b32 m0, s12
	ds_read_b128 v[36:39], v157 offset:49152
	ds_read_b128 v[40:43], v157 offset:50176
	ds_read_b128 v[146:149], v157 offset:51200
	ds_read_b128 v[232:235], v157 offset:52224
	ds_read_b128 v[236:239], v157 offset:53248
	ds_read_b128 v[240:243], v157 offset:54272
	ds_read_b128 v[244:247], v157 offset:55296
	ds_read_b128 v[248:251], v157 offset:56320
	global_load_lds_dwordx4 v[18:19], off
	s_add_i32 m0, s12, 0x2000
	v_lshl_add_u64 v[18:19], s[0:1], 0, v[138:139]
	s_add_u32 s0, s52, 0x1c000
	s_addc_u32 s1, s53, 0
	s_add_i32 s12, s13, s20
	global_load_lds_dwordx4 v[18:19], off
	v_lshl_add_u64 v[18:19], s[0:1], 0, v[134:135]
	s_mov_b32 m0, s12
	s_nop 0
	global_load_lds_dwordx4 v[18:19], off
	v_lshl_add_u64 v[18:19], s[0:1], 0, v[138:139]
	s_add_i32 m0, s12, 0x2000
	s_nop 0
	global_load_lds_dwordx4 v[18:19], off
	v_lshl_add_u64 v[18:19], v[150:151], 0, s[38:39]
	s_mov_b32 m0, s54
	s_nop 0
	global_load_lds_dwordx4 v[18:19], off
	v_lshl_add_u64 v[18:19], v[252:253], 0, s[38:39]
	s_mov_b32 m0, s55
	s_nop 0
	global_load_lds_dwordx4 v[18:19], off
	s_waitcnt vmcnt(8)
	s_waitcnt lgkmcnt(0)
	s_barrier
	v_mfma_f32_16x16x32_bf16 v[28:31], v[10:13], v[36:39], v[160:163]
	v_mfma_f32_16x16x32_bf16 v[72:75], v[14:17], v[40:43], v[28:31]
	v_mfma_f32_16x16x32_bf16 v[28:31], v[20:23], v[36:39], v[164:167]
	v_mfma_f32_16x16x32_bf16 v[68:71], v[24:27], v[40:43], v[28:31]
	v_mfma_f32_16x16x32_bf16 v[28:31], v[10:13], v[146:149], v[168:171]
	v_mfma_f32_16x16x32_bf16 v[48:51], v[14:17], v[232:235], v[28:31]
	v_mfma_f32_16x16x32_bf16 v[28:31], v[20:23], v[146:149], v[172:175]
	v_mfma_f32_16x16x32_bf16 v[44:47], v[24:27], v[232:235], v[28:31]
	v_mfma_f32_16x16x32_bf16 v[28:31], v[10:13], v[236:239], v[176:179]
	v_mfma_f32_16x16x32_bf16 v[2:5], v[10:13], v[244:247], v[2:5]
	v_mfma_f32_16x16x32_bf16 v[32:35], v[14:17], v[240:243], v[28:31]
	v_mfma_f32_16x16x32_bf16 v[28:31], v[20:23], v[236:239], v[180:183]
	v_mfma_f32_16x16x32_bf16 v[16:19], v[14:17], v[248:251], v[2:5]
	v_mfma_f32_16x16x32_bf16 v[2:5], v[20:23], v[244:247], v[6:9]
	v_mfma_f32_16x16x32_bf16 v[28:31], v[24:27], v[240:243], v[28:31]
	v_mfma_f32_16x16x32_bf16 v[12:15], v[24:27], v[248:251], v[2:5]
	v_mfma_f32_16x16x32_bf16 v[2:5], v[216:219], v[36:39], v[184:187]
	v_mfma_f32_16x16x32_bf16 v[56:59], v[220:223], v[40:43], v[2:5]
	v_mfma_f32_16x16x32_bf16 v[2:5], v[224:227], v[36:39], v[188:191]
	v_mfma_f32_16x16x32_bf16 v[52:55], v[228:231], v[40:43], v[2:5]
	v_mfma_f32_16x16x32_bf16 v[2:5], v[216:219], v[146:149], v[192:195]
	v_mfma_f32_16x16x32_bf16 v[40:43], v[220:223], v[232:235], v[2:5]
	v_mfma_f32_16x16x32_bf16 v[2:5], v[224:227], v[146:149], v[196:199]
	v_mfma_f32_16x16x32_bf16 v[36:39], v[228:231], v[232:235], v[2:5]
	v_mfma_f32_16x16x32_bf16 v[2:5], v[216:219], v[236:239], v[200:203]
	v_mfma_f32_16x16x32_bf16 v[24:27], v[220:223], v[240:243], v[2:5]
	v_mfma_f32_16x16x32_bf16 v[2:5], v[224:227], v[236:239], v[204:207]
	v_mfma_f32_16x16x32_bf16 v[20:23], v[228:231], v[240:243], v[2:5]
	v_mfma_f32_16x16x32_bf16 v[2:5], v[216:219], v[244:247], v[208:211]
	v_mfma_f32_16x16x32_bf16 v[8:11], v[220:223], v[248:251], v[2:5]
	v_mfma_f32_16x16x32_bf16 v[2:5], v[224:227], v[244:247], v[212:215]
	v_mfma_f32_16x16x32_bf16 v[4:7], v[228:231], v[248:251], v[2:5]
	s_barrier
	s_mov_b32 s22, 2
	s_branch .LBB0_1052

.LBB0_1053:
	ds_read_b128 v[146:149], v155
	ds_read_b128 v[160:163], v155 offset:1024
	ds_read_b128 v[164:167], v155 offset:2048
	ds_read_b128 v[168:171], v155 offset:3072
	ds_read_b128 v[172:175], v156
	ds_read_b128 v[176:179], v156 offset:1024
	ds_read_b128 v[180:183], v156 offset:2048
	ds_read_b128 v[184:187], v156 offset:3072
	s_add_u32 s12, s68, s30
	s_addc_u32 s13, s69, 0
	s_cmp_eq_u32 s30, s6
	s_cselect_b32 s23, s0, s13
	s_cselect_b32 s22, s1, s12
	s_cselect_b32 s53, s41, s67
	s_cselect_b32 s52, s64, s66
	s_add_i32 s71, s21, 0xc000
	v_lshl_add_u64 v[220:221], v[2:3], 0, s[30:31]
	s_mov_b32 m0, s71
	s_add_i32 s70, s21, 0xe000
	ds_read_b128 v[188:191], v157
	ds_read_b128 v[192:195], v157 offset:1024
	ds_read_b128 v[196:199], v157 offset:2048
	ds_read_b128 v[200:203], v157 offset:3072
	ds_read_b128 v[204:207], v157 offset:4096
	ds_read_b128 v[208:211], v157 offset:5120
	ds_read_b128 v[212:215], v157 offset:6144
	ds_read_b128 v[216:219], v157 offset:7168
	global_load_lds_dwordx4 v[220:221], off
	v_lshl_add_u64 v[220:221], v[150:151], 0, s[30:31]
	s_mov_b32 m0, s70
	s_nop 0
	global_load_lds_dwordx4 v[220:221], off
	s_waitcnt vmcnt(8)
	s_waitcnt lgkmcnt(0)
	s_barrier
	v_mfma_f32_16x16x32_bf16 v[128:131], v[146:149], v[188:191], v[128:131]
	v_mfma_f32_16x16x32_bf16 v[124:127], v[164:167], v[188:191], v[124:127]
	v_mfma_f32_16x16x32_bf16 v[112:115], v[146:149], v[196:199], v[112:115]
	v_mfma_f32_16x16x32_bf16 v[108:111], v[164:167], v[196:199], v[108:111]
	v_mfma_f32_16x16x32_bf16 v[96:99], v[146:149], v[204:207], v[96:99]
	v_mfma_f32_16x16x32_bf16 v[92:95], v[164:167], v[204:207], v[92:95]
	v_mfma_f32_16x16x32_bf16 v[80:83], v[146:149], v[212:215], v[80:83]
	v_mfma_f32_16x16x32_bf16 v[76:79], v[164:167], v[212:215], v[76:79]
	v_mfma_f32_16x16x32_bf16 v[128:131], v[160:163], v[192:195], v[128:131]
	v_mfma_f32_16x16x32_bf16 v[124:127], v[168:171], v[192:195], v[124:127]
	v_mfma_f32_16x16x32_bf16 v[112:115], v[160:163], v[200:203], v[112:115]
	v_mfma_f32_16x16x32_bf16 v[108:111], v[168:171], v[200:203], v[108:111]
	v_mfma_f32_16x16x32_bf16 v[96:99], v[160:163], v[208:211], v[96:99]
	v_mfma_f32_16x16x32_bf16 v[92:95], v[168:171], v[208:211], v[92:95]
	v_mfma_f32_16x16x32_bf16 v[80:83], v[160:163], v[216:219], v[80:83]
	v_mfma_f32_16x16x32_bf16 v[76:79], v[168:171], v[216:219], v[76:79]
	v_mfma_f32_16x16x32_bf16 v[120:123], v[172:175], v[188:191], v[120:123]
	v_mfma_f32_16x16x32_bf16 v[116:119], v[180:183], v[188:191], v[116:119]
	v_mfma_f32_16x16x32_bf16 v[104:107], v[172:175], v[196:199], v[104:107]
	v_mfma_f32_16x16x32_bf16 v[100:103], v[180:183], v[196:199], v[100:103]
	v_mfma_f32_16x16x32_bf16 v[88:91], v[172:175], v[204:207], v[88:91]
	v_mfma_f32_16x16x32_bf16 v[84:87], v[180:183], v[204:207], v[84:87]
	v_mfma_f32_16x16x32_bf16 v[64:67], v[172:175], v[212:215], v[64:67]
	v_mfma_f32_16x16x32_bf16 v[60:63], v[180:183], v[212:215], v[60:63]
	v_mfma_f32_16x16x32_bf16 v[120:123], v[176:179], v[192:195], v[120:123]
	v_mfma_f32_16x16x32_bf16 v[116:119], v[184:187], v[192:195], v[116:119]
	v_mfma_f32_16x16x32_bf16 v[104:107], v[176:179], v[200:203], v[104:107]
	v_mfma_f32_16x16x32_bf16 v[100:103], v[184:187], v[200:203], v[100:103]
	v_mfma_f32_16x16x32_bf16 v[88:91], v[176:179], v[208:211], v[88:91]
	v_mfma_f32_16x16x32_bf16 v[84:87], v[184:187], v[208:211], v[84:87]
	v_mfma_f32_16x16x32_bf16 v[64:67], v[176:179], v[216:219], v[64:67]
	v_mfma_f32_16x16x32_bf16 v[60:63], v[184:187], v[216:219], v[60:63]
	s_barrier
	s_add_i32 s12, s58, s20
	v_lshl_add_u64 v[220:221], s[52:53], 0, v[134:135]
	s_mov_b32 m0, s12
	ds_read_b128 v[188:191], v157 offset:16384
	ds_read_b128 v[192:195], v157 offset:17408
	ds_read_b128 v[196:199], v157 offset:18432
	ds_read_b128 v[200:203], v157 offset:19456
	ds_read_b128 v[204:207], v157 offset:20480
	ds_read_b128 v[208:211], v157 offset:21504
	ds_read_b128 v[212:215], v157 offset:22528
	ds_read_b128 v[216:219], v157 offset:23552
	global_load_lds_dwordx4 v[220:221], off
	s_add_i32 m0, s12, 0x2000
	s_add_u32 s12, s52, 0x4000
	v_lshl_add_u64 v[220:221], s[52:53], 0, v[138:139]
	s_addc_u32 s13, s53, 0
	s_add_i32 s14, s59, s20
	global_load_lds_dwordx4 v[220:221], off
	v_lshl_add_u64 v[220:221], s[12:13], 0, v[134:135]
	s_mov_b32 m0, s14
	v_lshl_add_u64 v[222:223], s[22:23], 0, v[136:137]
	global_load_lds_dwordx4 v[220:221], off
	v_lshl_add_u64 v[220:221], s[12:13], 0, v[138:139]
	s_add_i32 m0, s14, 0x2000
	s_nop 0
	global_load_lds_dwordx4 v[220:221], off
	v_lshl_add_u64 v[220:221], s[22:23], 0, v[132:133]
	s_mov_b32 m0, s21
	s_nop 0
	global_load_lds_dwordx4 v[220:221], off
	s_mov_b32 m0, s24
	s_nop 0
	global_load_lds_dwordx4 v[222:223], off
	s_waitcnt vmcnt(8)
	s_waitcnt lgkmcnt(0)
	s_barrier
	v_mfma_f32_16x16x32_bf16 v[72:75], v[146:149], v[188:191], v[72:75]
	v_mfma_f32_16x16x32_bf16 v[68:71], v[164:167], v[188:191], v[68:71]
	v_mfma_f32_16x16x32_bf16 v[48:51], v[146:149], v[196:199], v[48:51]
	v_mfma_f32_16x16x32_bf16 v[44:47], v[164:167], v[196:199], v[44:47]
	v_mfma_f32_16x16x32_bf16 v[32:35], v[146:149], v[204:207], v[32:35]
	v_mfma_f32_16x16x32_bf16 v[28:31], v[164:167], v[204:207], v[28:31]
	v_mfma_f32_16x16x32_bf16 v[16:19], v[146:149], v[212:215], v[16:19]
	v_mfma_f32_16x16x32_bf16 v[12:15], v[164:167], v[212:215], v[12:15]
	v_mfma_f32_16x16x32_bf16 v[72:75], v[160:163], v[192:195], v[72:75]
	v_mfma_f32_16x16x32_bf16 v[68:71], v[168:171], v[192:195], v[68:71]
	v_mfma_f32_16x16x32_bf16 v[48:51], v[160:163], v[200:203], v[48:51]
	v_mfma_f32_16x16x32_bf16 v[44:47], v[168:171], v[200:203], v[44:47]
	v_mfma_f32_16x16x32_bf16 v[32:35], v[160:163], v[208:211], v[32:35]
	v_mfma_f32_16x16x32_bf16 v[28:31], v[168:171], v[208:211], v[28:31]
	v_mfma_f32_16x16x32_bf16 v[16:19], v[160:163], v[216:219], v[16:19]
	v_mfma_f32_16x16x32_bf16 v[12:15], v[168:171], v[216:219], v[12:15]
	v_mfma_f32_16x16x32_bf16 v[56:59], v[172:175], v[188:191], v[56:59]
	v_mfma_f32_16x16x32_bf16 v[52:55], v[180:183], v[188:191], v[52:55]
	v_mfma_f32_16x16x32_bf16 v[40:43], v[172:175], v[196:199], v[40:43]
	v_mfma_f32_16x16x32_bf16 v[36:39], v[180:183], v[196:199], v[36:39]
	v_mfma_f32_16x16x32_bf16 v[24:27], v[172:175], v[204:207], v[24:27]
	v_mfma_f32_16x16x32_bf16 v[20:23], v[180:183], v[204:207], v[20:23]
	v_mfma_f32_16x16x32_bf16 v[8:11], v[172:175], v[212:215], v[8:11]
	v_mfma_f32_16x16x32_bf16 v[4:7], v[180:183], v[212:215], v[4:7]
	v_mfma_f32_16x16x32_bf16 v[56:59], v[176:179], v[192:195], v[56:59]
	v_mfma_f32_16x16x32_bf16 v[52:55], v[184:187], v[192:195], v[52:55]
	v_mfma_f32_16x16x32_bf16 v[40:43], v[176:179], v[200:203], v[40:43]
	v_mfma_f32_16x16x32_bf16 v[36:39], v[184:187], v[200:203], v[36:39]
	v_mfma_f32_16x16x32_bf16 v[24:27], v[176:179], v[208:211], v[24:27]
	v_mfma_f32_16x16x32_bf16 v[20:23], v[184:187], v[208:211], v[20:23]
	v_mfma_f32_16x16x32_bf16 v[8:11], v[176:179], v[216:219], v[8:11]
	v_mfma_f32_16x16x32_bf16 v[4:7], v[184:187], v[216:219], v[4:7]
	s_barrier
	s_add_i32 s14, 0, 0x18000
	v_add_u32_e32 v0, s14, v154
	s_add_i32 s72, 0, 0x1c000
	ds_read_b128 v[146:149], v0
	ds_read_b128 v[160:163], v0 offset:1024
	ds_read_b128 v[164:167], v0 offset:2048
	ds_read_b128 v[168:171], v0 offset:3072
	v_add_u32_e32 v0, s72, v154
	ds_read_b128 v[172:175], v0
	ds_read_b128 v[176:179], v0 offset:1024
	ds_read_b128 v[180:183], v0 offset:2048
	ds_read_b128 v[184:187], v0 offset:3072
	s_add_u32 s12, s22, 0x100000
	s_addc_u32 s13, s23, 0
	s_mov_b32 m0, s25
	v_lshl_add_u64 v[224:225], s[12:13], 0, v[132:133]
	ds_read_b128 v[188:191], v157 offset:32768
	ds_read_b128 v[192:195], v157 offset:33792
	ds_read_b128 v[196:199], v157 offset:34816
	ds_read_b128 v[200:203], v157 offset:35840
	ds_read_b128 v[204:207], v157 offset:36864
	ds_read_b128 v[208:211], v157 offset:37888
	ds_read_b128 v[212:215], v157 offset:38912
	ds_read_b128 v[216:219], v157 offset:39936
	global_load_lds_dwordx4 v[224:225], off
	v_lshl_add_u64 v[224:225], s[12:13], 0, v[136:137]
	s_mov_b32 m0, s33
	s_nop 0
	global_load_lds_dwordx4 v[224:225], off
	s_waitcnt vmcnt(8)
	s_waitcnt lgkmcnt(0)
	s_barrier
	v_mfma_f32_16x16x32_bf16 v[128:131], v[146:149], v[188:191], v[128:131]
	v_mfma_f32_16x16x32_bf16 v[124:127], v[164:167], v[188:191], v[124:127]
	v_mfma_f32_16x16x32_bf16 v[112:115], v[146:149], v[196:199], v[112:115]
	v_mfma_f32_16x16x32_bf16 v[108:111], v[164:167], v[196:199], v[108:111]
	v_mfma_f32_16x16x32_bf16 v[96:99], v[146:149], v[204:207], v[96:99]
	v_mfma_f32_16x16x32_bf16 v[92:95], v[164:167], v[204:207], v[92:95]
	v_mfma_f32_16x16x32_bf16 v[80:83], v[146:149], v[212:215], v[80:83]
	v_mfma_f32_16x16x32_bf16 v[76:79], v[164:167], v[212:215], v[76:79]
	v_mfma_f32_16x16x32_bf16 v[128:131], v[160:163], v[192:195], v[128:131]
	v_mfma_f32_16x16x32_bf16 v[124:127], v[168:171], v[192:195], v[124:127]
	v_mfma_f32_16x16x32_bf16 v[112:115], v[160:163], v[200:203], v[112:115]
	v_mfma_f32_16x16x32_bf16 v[108:111], v[168:171], v[200:203], v[108:111]
	v_mfma_f32_16x16x32_bf16 v[96:99], v[160:163], v[208:211], v[96:99]
	v_mfma_f32_16x16x32_bf16 v[92:95], v[168:171], v[208:211], v[92:95]
	v_mfma_f32_16x16x32_bf16 v[80:83], v[160:163], v[216:219], v[80:83]
	v_mfma_f32_16x16x32_bf16 v[76:79], v[168:171], v[216:219], v[76:79]
	v_mfma_f32_16x16x32_bf16 v[120:123], v[172:175], v[188:191], v[120:123]
	v_mfma_f32_16x16x32_bf16 v[116:119], v[180:183], v[188:191], v[116:119]
	v_mfma_f32_16x16x32_bf16 v[104:107], v[172:175], v[196:199], v[104:107]
	v_mfma_f32_16x16x32_bf16 v[100:103], v[180:183], v[196:199], v[100:103]
	v_mfma_f32_16x16x32_bf16 v[88:91], v[172:175], v[204:207], v[88:91]
	v_mfma_f32_16x16x32_bf16 v[84:87], v[180:183], v[204:207], v[84:87]
	v_mfma_f32_16x16x32_bf16 v[64:67], v[172:175], v[212:215], v[64:67]
	v_mfma_f32_16x16x32_bf16 v[60:63], v[180:183], v[212:215], v[60:63]
	v_mfma_f32_16x16x32_bf16 v[120:123], v[176:179], v[192:195], v[120:123]
	v_mfma_f32_16x16x32_bf16 v[116:119], v[184:187], v[192:195], v[116:119]
	v_mfma_f32_16x16x32_bf16 v[104:107], v[176:179], v[200:203], v[104:107]
	v_mfma_f32_16x16x32_bf16 v[100:103], v[184:187], v[200:203], v[100:103]
	v_mfma_f32_16x16x32_bf16 v[88:91], v[176:179], v[208:211], v[88:91]
	v_mfma_f32_16x16x32_bf16 v[84:87], v[184:187], v[208:211], v[84:87]
	v_mfma_f32_16x16x32_bf16 v[64:67], v[176:179], v[216:219], v[64:67]
	v_mfma_f32_16x16x32_bf16 v[60:63], v[184:187], v[216:219], v[60:63]
	s_barrier
	s_add_u32 s12, s52, 0x8000
	s_addc_u32 s13, s53, 0
	s_add_i32 s14, s14, s20
	v_lshl_add_u64 v[224:225], s[12:13], 0, v[134:135]
	s_mov_b32 m0, s14
	ds_read_b128 v[188:191], v157 offset:49152
	ds_read_b128 v[192:195], v157 offset:50176
	ds_read_b128 v[196:199], v157 offset:51200
	ds_read_b128 v[200:203], v157 offset:52224
	ds_read_b128 v[204:207], v157 offset:53248
	ds_read_b128 v[208:211], v157 offset:54272
	ds_read_b128 v[212:215], v157 offset:55296
	ds_read_b128 v[216:219], v157 offset:56320
	global_load_lds_dwordx4 v[224:225], off
	s_add_i32 m0, s14, 0x2000
	v_lshl_add_u64 v[224:225], s[12:13], 0, v[138:139]
	s_add_u32 s12, s52, 0xc000
	s_addc_u32 s13, s53, 0
	s_add_i32 s14, s72, s20
	global_load_lds_dwordx4 v[224:225], off
	v_lshl_add_u64 v[224:225], s[12:13], 0, v[134:135]
	s_mov_b32 m0, s14
	v_lshl_add_u64 v[220:221], v[220:221], 0, s[28:29]
	global_load_lds_dwordx4 v[224:225], off
	v_lshl_add_u64 v[224:225], s[12:13], 0, v[138:139]
	s_add_i32 m0, s14, 0x2000
	s_nop 0
	global_load_lds_dwordx4 v[224:225], off
	s_mov_b32 m0, s54
	s_nop 0
	global_load_lds_dwordx4 v[220:221], off
	v_lshl_add_u64 v[220:221], v[222:223], 0, s[28:29]
	s_mov_b32 m0, s55
	s_nop 0
	global_load_lds_dwordx4 v[220:221], off
	s_waitcnt vmcnt(8)
	s_waitcnt lgkmcnt(0)
	s_barrier
	v_mfma_f32_16x16x32_bf16 v[72:75], v[146:149], v[188:191], v[72:75]
	v_mfma_f32_16x16x32_bf16 v[68:71], v[164:167], v[188:191], v[68:71]
	v_mfma_f32_16x16x32_bf16 v[48:51], v[146:149], v[196:199], v[48:51]
	v_mfma_f32_16x16x32_bf16 v[44:47], v[164:167], v[196:199], v[44:47]
	v_mfma_f32_16x16x32_bf16 v[32:35], v[146:149], v[204:207], v[32:35]
	v_mfma_f32_16x16x32_bf16 v[28:31], v[164:167], v[204:207], v[28:31]
	v_mfma_f32_16x16x32_bf16 v[16:19], v[146:149], v[212:215], v[16:19]
	v_mfma_f32_16x16x32_bf16 v[12:15], v[164:167], v[212:215], v[12:15]
	v_mfma_f32_16x16x32_bf16 v[72:75], v[160:163], v[192:195], v[72:75]
	v_mfma_f32_16x16x32_bf16 v[68:71], v[168:171], v[192:195], v[68:71]
	v_mfma_f32_16x16x32_bf16 v[48:51], v[160:163], v[200:203], v[48:51]
	v_mfma_f32_16x16x32_bf16 v[44:47], v[168:171], v[200:203], v[44:47]
	v_mfma_f32_16x16x32_bf16 v[32:35], v[160:163], v[208:211], v[32:35]
	v_mfma_f32_16x16x32_bf16 v[28:31], v[168:171], v[208:211], v[28:31]
	v_mfma_f32_16x16x32_bf16 v[16:19], v[160:163], v[216:219], v[16:19]
	v_mfma_f32_16x16x32_bf16 v[12:15], v[168:171], v[216:219], v[12:15]
	v_mfma_f32_16x16x32_bf16 v[56:59], v[172:175], v[188:191], v[56:59]
	v_mfma_f32_16x16x32_bf16 v[52:55], v[180:183], v[188:191], v[52:55]
	v_mfma_f32_16x16x32_bf16 v[40:43], v[172:175], v[196:199], v[40:43]
	v_mfma_f32_16x16x32_bf16 v[36:39], v[180:183], v[196:199], v[36:39]
	v_mfma_f32_16x16x32_bf16 v[24:27], v[172:175], v[204:207], v[24:27]
	v_mfma_f32_16x16x32_bf16 v[20:23], v[180:183], v[204:207], v[20:23]
	v_mfma_f32_16x16x32_bf16 v[8:11], v[172:175], v[212:215], v[8:11]
	v_mfma_f32_16x16x32_bf16 v[4:7], v[180:183], v[212:215], v[4:7]
	v_mfma_f32_16x16x32_bf16 v[56:59], v[176:179], v[192:195], v[56:59]
	v_mfma_f32_16x16x32_bf16 v[52:55], v[184:187], v[192:195], v[52:55]
	v_mfma_f32_16x16x32_bf16 v[40:43], v[176:179], v[200:203], v[40:43]
	v_mfma_f32_16x16x32_bf16 v[36:39], v[184:187], v[200:203], v[36:39]
	v_mfma_f32_16x16x32_bf16 v[24:27], v[176:179], v[208:211], v[24:27]
	v_mfma_f32_16x16x32_bf16 v[20:23], v[184:187], v[208:211], v[20:23]
	v_mfma_f32_16x16x32_bf16 v[8:11], v[176:179], v[216:219], v[8:11]
	v_mfma_f32_16x16x32_bf16 v[4:7], v[184:187], v[216:219], v[4:7]
	s_barrier
	s_add_i32 s65, s65, 2
	s_add_u32 s66, s66, 0x10000
	s_addc_u32 s67, s67, 0
	s_add_u32 s68, s68, 0x100
	s_addc_u32 s69, s69, 0
	s_add_u32 s6, s6, 0xffffff00
	s_addc_u32 s7, s7, -1
	v_lshl_add_u64 v[2:3], v[2:3], 0, s[36:37]
	s_cmp_gt_u32 s65, 61
	v_lshl_add_u64 v[150:151], v[150:151], 0, s[36:37]
	s_cbranch_scc0 .LBB0_1053
	s_and_b64 vcc, exec, s[34:35]
	s_cbranch_vccnz .LBB0_1061
	s_and_b64 s[0:1], s[10:11], s[4:5]
	s_andn2_b64 vcc, exec, s[0:1]
	s_cbranch_vccz .LBB0_1062

.LBB0_1729:
	ds_read_b128 v[2:5], v153
	ds_read_b128 v[6:9], v153 offset:1024
	ds_read_b128 v[10:13], v153 offset:2048
	ds_read_b128 v[14:17], v153 offset:3072
	ds_read_b128 v[18:21], v154
	ds_read_b128 v[22:25], v154 offset:1024
	ds_read_b128 v[26:29], v154 offset:2048
	ds_read_b128 v[30:33], v154 offset:3072
	s_add_u32 s0, s44, 0x10000
	s_addc_u32 s1, s45, 0
	ds_read_b128 v[34:37], v155
	ds_read_b128 v[38:41], v155 offset:1024
	ds_read_b128 v[42:45], v155 offset:2048
	ds_read_b128 v[46:49], v155 offset:3072
	ds_read_b128 v[50:53], v155 offset:4096
	ds_read_b128 v[54:57], v155 offset:5120
	ds_read_b128 v[58:61], v155 offset:6144
	ds_read_b128 v[62:65], v155 offset:7168
	s_waitcnt vmcnt(24)
	s_waitcnt lgkmcnt(0)
	s_barrier
	v_mfma_f32_16x16x32_bf16 v[66:69], v[2:5], v[34:37], 0
	v_mfma_f32_16x16x32_bf16 v[70:73], v[10:13], v[34:37], 0
	v_mfma_f32_16x16x32_bf16 v[74:77], v[2:5], v[42:45], 0
	v_mfma_f32_16x16x32_bf16 v[78:81], v[10:13], v[42:45], 0
	v_mfma_f32_16x16x32_bf16 v[82:85], v[2:5], v[50:53], 0
	v_mfma_f32_16x16x32_bf16 v[86:89], v[10:13], v[50:53], 0
	v_mfma_f32_16x16x32_bf16 v[90:93], v[2:5], v[58:61], 0
	v_mfma_f32_16x16x32_bf16 v[94:97], v[10:13], v[58:61], 0
	v_mfma_f32_16x16x32_bf16 v[66:69], v[6:9], v[38:41], v[66:69]
	v_mfma_f32_16x16x32_bf16 v[70:73], v[14:17], v[38:41], v[70:73]
	v_mfma_f32_16x16x32_bf16 v[74:77], v[6:9], v[46:49], v[74:77]
	v_mfma_f32_16x16x32_bf16 v[78:81], v[14:17], v[46:49], v[78:81]
	v_mfma_f32_16x16x32_bf16 v[82:85], v[6:9], v[54:57], v[82:85]
	v_mfma_f32_16x16x32_bf16 v[86:89], v[14:17], v[54:57], v[86:89]
	v_mfma_f32_16x16x32_bf16 v[90:93], v[6:9], v[62:65], v[90:93]
	v_mfma_f32_16x16x32_bf16 v[104:107], v[14:17], v[62:65], v[94:97]
	v_mfma_f32_16x16x32_bf16 v[94:97], v[18:21], v[34:37], 0
	v_mfma_f32_16x16x32_bf16 v[34:37], v[26:29], v[34:37], 0
	v_mfma_f32_16x16x32_bf16 v[108:111], v[22:25], v[38:41], v[94:97]
	v_mfma_f32_16x16x32_bf16 v[34:37], v[30:33], v[38:41], v[34:37]
	v_mfma_f32_16x16x32_bf16 v[38:41], v[18:21], v[42:45], 0
	v_mfma_f32_16x16x32_bf16 v[42:45], v[26:29], v[42:45], 0
	v_mfma_f32_16x16x32_bf16 v[38:41], v[22:25], v[46:49], v[38:41]
	v_mfma_f32_16x16x32_bf16 v[42:45], v[30:33], v[46:49], v[42:45]
	v_mfma_f32_16x16x32_bf16 v[46:49], v[18:21], v[50:53], 0
	v_mfma_f32_16x16x32_bf16 v[50:53], v[26:29], v[50:53], 0
	v_mfma_f32_16x16x32_bf16 v[46:49], v[22:25], v[54:57], v[46:49]
	v_mfma_f32_16x16x32_bf16 v[50:53], v[30:33], v[54:57], v[50:53]
	v_mfma_f32_16x16x32_bf16 v[54:57], v[18:21], v[58:61], 0
	v_mfma_f32_16x16x32_bf16 v[58:61], v[26:29], v[58:61], 0
	v_mfma_f32_16x16x32_bf16 v[54:57], v[22:25], v[62:65], v[54:57]
	v_mfma_f32_16x16x32_bf16 v[58:61], v[30:33], v[62:65], v[58:61]
	s_barrier
	s_add_i32 s12, s52, s17
	v_lshl_add_u64 v[102:103], s[0:1], 0, v[134:135]
	s_mov_b32 m0, s12
	ds_read_b128 v[62:65], v155 offset:16384
	ds_read_b128 v[94:97], v155 offset:17408
	ds_read_b128 v[98:101], v155 offset:18432
	ds_read_b128 v[112:115], v155 offset:19456
	ds_read_b128 v[116:119], v155 offset:20480
	ds_read_b128 v[120:123], v155 offset:21504
	ds_read_b128 v[124:127], v155 offset:22528
	ds_read_b128 v[128:131], v155 offset:23552
	global_load_lds_dwordx4 v[102:103], off
	s_add_i32 m0, s12, 0x2000
	v_lshl_add_u64 v[102:103], s[0:1], 0, v[138:139]
	s_add_u32 s0, s44, 0x14000
	s_addc_u32 s1, s45, 0
	s_add_i32 s12, s53, s17
	global_load_lds_dwordx4 v[102:103], off
	v_lshl_add_u64 v[102:103], s[0:1], 0, v[134:135]
	s_mov_b32 m0, s12
	v_lshl_add_u64 v[148:149], s[46:47], 0, v[132:133]
	global_load_lds_dwordx4 v[102:103], off
	v_lshl_add_u64 v[102:103], s[0:1], 0, v[138:139]
	s_add_i32 m0, s12, 0x2000
	v_lshl_add_u64 v[144:145], s[46:47], 0, v[136:137]
	global_load_lds_dwordx4 v[102:103], off
	v_lshl_add_u64 v[102:103], v[148:149], 0, s[38:39]
	s_mov_b32 m0, s18
	s_nop 0
	global_load_lds_dwordx4 v[102:103], off
	v_lshl_add_u64 v[102:103], v[144:145], 0, s[38:39]
	s_mov_b32 m0, s19
	s_nop 0
	global_load_lds_dwordx4 v[102:103], off
	s_waitcnt vmcnt(24)
	s_waitcnt lgkmcnt(0)
	s_barrier
	v_mfma_f32_16x16x32_bf16 v[158:161], v[2:5], v[62:65], 0
	v_mfma_f32_16x16x32_bf16 v[166:169], v[2:5], v[98:101], 0
	v_mfma_f32_16x16x32_bf16 v[174:177], v[2:5], v[116:119], 0
	v_mfma_f32_16x16x32_bf16 v[2:5], v[2:5], v[124:127], 0
	v_mfma_f32_16x16x32_bf16 v[158:161], v[6:9], v[94:97], v[158:161]
	v_mfma_f32_16x16x32_bf16 v[166:169], v[6:9], v[112:115], v[166:169]
	v_mfma_f32_16x16x32_bf16 v[174:177], v[6:9], v[120:123], v[174:177]
	v_mfma_f32_16x16x32_bf16 v[2:5], v[6:9], v[128:131], v[2:5]
	v_mfma_f32_16x16x32_bf16 v[6:9], v[10:13], v[124:127], 0
	v_mfma_f32_16x16x32_bf16 v[162:165], v[10:13], v[62:65], 0
	v_mfma_f32_16x16x32_bf16 v[170:173], v[10:13], v[98:101], 0
	v_mfma_f32_16x16x32_bf16 v[178:181], v[10:13], v[116:119], 0
	v_mfma_f32_16x16x32_bf16 v[6:9], v[14:17], v[128:131], v[6:9]
	v_mfma_f32_16x16x32_bf16 v[162:165], v[14:17], v[94:97], v[162:165]
	v_mfma_f32_16x16x32_bf16 v[170:173], v[14:17], v[112:115], v[170:173]
	v_mfma_f32_16x16x32_bf16 v[178:181], v[14:17], v[120:123], v[178:181]
	v_mfma_f32_16x16x32_bf16 v[14:17], v[26:29], v[62:65], 0
	v_mfma_f32_16x16x32_bf16 v[182:185], v[30:33], v[94:97], v[14:17]
	v_mfma_f32_16x16x32_bf16 v[14:17], v[18:21], v[98:101], 0
	v_mfma_f32_16x16x32_bf16 v[186:189], v[22:25], v[112:115], v[14:17]
	v_mfma_f32_16x16x32_bf16 v[14:17], v[26:29], v[98:101], 0
	v_mfma_f32_16x16x32_bf16 v[190:193], v[30:33], v[112:115], v[14:17]
	v_mfma_f32_16x16x32_bf16 v[14:17], v[18:21], v[116:119], 0
	v_mfma_f32_16x16x32_bf16 v[194:197], v[22:25], v[120:123], v[14:17]
	v_mfma_f32_16x16x32_bf16 v[14:17], v[26:29], v[116:119], 0
	v_mfma_f32_16x16x32_bf16 v[10:13], v[18:21], v[62:65], 0
	v_mfma_f32_16x16x32_bf16 v[198:201], v[30:33], v[120:123], v[14:17]
	v_mfma_f32_16x16x32_bf16 v[14:17], v[18:21], v[124:127], 0
	v_mfma_f32_16x16x32_bf16 v[10:13], v[22:25], v[94:97], v[10:13]
	v_mfma_f32_16x16x32_bf16 v[202:205], v[22:25], v[128:131], v[14:17]
	v_mfma_f32_16x16x32_bf16 v[14:17], v[26:29], v[124:127], 0
	v_mfma_f32_16x16x32_bf16 v[206:209], v[30:33], v[128:131], v[14:17]
	s_barrier
	s_add_i32 s12, 0, 0x18000
	v_add_u32_e32 v1, s12, v151
	s_add_i32 s13, 0, 0x1c000
	s_nop 1
	ds_read_b128 v[14:17], v1
	ds_read_b128 v[24:27], v1 offset:1024
	ds_read_b128 v[28:31], v1 offset:2048
	ds_read_b128 v[210:213], v1 offset:3072
	v_add_u32_e32 v1, s13, v151
	ds_read_b128 v[214:217], v1
	ds_read_b128 v[218:221], v1 offset:1024
	ds_read_b128 v[222:225], v1 offset:2048
	ds_read_b128 v[226:229], v1 offset:3072
	s_add_u32 s0, s46, 0x2b0100
	s_addc_u32 s1, s47, 0
	s_mov_b32 m0, s20
	v_lshl_add_u64 v[22:23], s[0:1], 0, v[132:133]
	ds_read_b128 v[18:21], v155 offset:32768
	ds_read_b128 v[120:123], v155 offset:33792
	ds_read_b128 v[230:233], v155 offset:34816
	ds_read_b128 v[234:237], v155 offset:35840
	ds_read_b128 v[238:241], v155 offset:36864
	ds_read_b128 v[242:245], v155 offset:37888
	ds_read_b128 v[246:249], v155 offset:38912
	ds_read_b128 v[250:253], v155 offset:39936
	global_load_lds_dwordx4 v[22:23], off
	v_lshl_add_u64 v[22:23], s[0:1], 0, v[136:137]
	s_mov_b32 m0, s21
	s_nop 0
	global_load_lds_dwordx4 v[22:23], off
	s_waitcnt vmcnt(24)
	s_waitcnt lgkmcnt(0)
	s_barrier
	v_mfma_f32_16x16x32_bf16 v[62:65], v[14:17], v[18:21], v[66:69]
	v_mfma_f32_16x16x32_bf16 v[128:131], v[24:27], v[120:123], v[62:65]
	v_mfma_f32_16x16x32_bf16 v[62:65], v[28:31], v[18:21], v[70:73]
	v_mfma_f32_16x16x32_bf16 v[116:119], v[210:213], v[120:123], v[62:65]
	v_mfma_f32_16x16x32_bf16 v[62:65], v[14:17], v[230:233], v[74:77]
	v_mfma_f32_16x16x32_bf16 v[112:115], v[24:27], v[234:237], v[62:65]
	v_mfma_f32_16x16x32_bf16 v[62:65], v[28:31], v[230:233], v[78:81]
	v_mfma_f32_16x16x32_bf16 v[100:103], v[210:213], v[234:237], v[62:65]
	v_mfma_f32_16x16x32_bf16 v[62:65], v[14:17], v[238:241], v[82:85]
	v_mfma_f32_16x16x32_bf16 v[96:99], v[24:27], v[242:245], v[62:65]
	v_mfma_f32_16x16x32_bf16 v[62:65], v[28:31], v[238:241], v[86:89]
	v_mfma_f32_16x16x32_bf16 v[84:87], v[210:213], v[242:245], v[62:65]
	v_mfma_f32_16x16x32_bf16 v[62:65], v[14:17], v[246:249], v[90:93]
	v_mfma_f32_16x16x32_bf16 v[80:83], v[24:27], v[250:253], v[62:65]
	v_mfma_f32_16x16x32_bf16 v[62:65], v[28:31], v[246:249], v[104:107]
	v_mfma_f32_16x16x32_bf16 v[64:67], v[210:213], v[250:253], v[62:65]
	v_mfma_f32_16x16x32_bf16 v[68:71], v[214:217], v[18:21], v[108:111]
	v_mfma_f32_16x16x32_bf16 v[18:21], v[222:225], v[18:21], v[34:37]
	v_mfma_f32_16x16x32_bf16 v[124:127], v[218:221], v[120:123], v[68:71]
	v_mfma_f32_16x16x32_bf16 v[120:123], v[226:229], v[120:123], v[18:21]
	v_mfma_f32_16x16x32_bf16 v[18:21], v[214:217], v[230:233], v[38:41]
	v_mfma_f32_16x16x32_bf16 v[108:111], v[218:221], v[234:237], v[18:21]
	v_mfma_f32_16x16x32_bf16 v[18:21], v[222:225], v[230:233], v[42:45]
	v_mfma_f32_16x16x32_bf16 v[104:107], v[226:229], v[234:237], v[18:21]
	v_mfma_f32_16x16x32_bf16 v[18:21], v[214:217], v[238:241], v[46:49]
	v_mfma_f32_16x16x32_bf16 v[92:95], v[218:221], v[242:245], v[18:21]
	v_mfma_f32_16x16x32_bf16 v[18:21], v[222:225], v[238:241], v[50:53]
	v_mfma_f32_16x16x32_bf16 v[88:91], v[226:229], v[242:245], v[18:21]
	v_mfma_f32_16x16x32_bf16 v[18:21], v[214:217], v[246:249], v[54:57]
	v_mfma_f32_16x16x32_bf16 v[72:75], v[218:221], v[250:253], v[18:21]
	v_mfma_f32_16x16x32_bf16 v[18:21], v[222:225], v[246:249], v[58:61]
	v_mfma_f32_16x16x32_bf16 v[68:71], v[226:229], v[250:253], v[18:21]
	s_barrier
	s_add_u32 s0, s44, 0x18000
	s_addc_u32 s1, s45, 0
	s_add_i32 s12, s12, s17
	s_nop 1
	v_lshl_add_u64 v[18:19], s[0:1], 0, v[134:135]
	s_mov_b32 m0, s12
	ds_read_b128 v[40:43], v155 offset:49152
	ds_read_b128 v[44:47], v155 offset:50176
	ds_read_b128 v[230:233], v155 offset:51200
	ds_read_b128 v[234:237], v155 offset:52224
	ds_read_b128 v[238:241], v155 offset:53248
	ds_read_b128 v[242:245], v155 offset:54272
	ds_read_b128 v[246:249], v155 offset:55296
	ds_read_b128 v[250:253], v155 offset:56320
	global_load_lds_dwordx4 v[18:19], off
	s_add_i32 m0, s12, 0x2000
	v_lshl_add_u64 v[18:19], s[0:1], 0, v[138:139]
	s_add_u32 s0, s44, 0x1c000
	s_addc_u32 s1, s45, 0
	s_add_i32 s12, s13, s17
	global_load_lds_dwordx4 v[18:19], off
	v_lshl_add_u64 v[18:19], s[0:1], 0, v[134:135]
	s_mov_b32 m0, s12
	s_nop 0
	global_load_lds_dwordx4 v[18:19], off
	v_lshl_add_u64 v[18:19], s[0:1], 0, v[138:139]
	s_add_i32 m0, s12, 0x2000
	s_nop 0
	global_load_lds_dwordx4 v[18:19], off
	v_lshl_add_u64 v[18:19], v[148:149], 0, s[40:41]
	s_mov_b32 m0, s48
	s_nop 0
	global_load_lds_dwordx4 v[18:19], off
	v_lshl_add_u64 v[18:19], v[144:145], 0, s[40:41]
	s_mov_b32 m0, s49
	s_nop 0
	global_load_lds_dwordx4 v[18:19], off
	s_waitcnt vmcnt(8)
	s_waitcnt lgkmcnt(0)
	s_barrier
	v_mfma_f32_16x16x32_bf16 v[18:21], v[14:17], v[40:43], v[158:161]
	v_mfma_f32_16x16x32_bf16 v[76:79], v[24:27], v[44:47], v[18:21]
	v_mfma_f32_16x16x32_bf16 v[18:21], v[28:31], v[40:43], v[162:165]
	v_mfma_f32_16x16x32_bf16 v[52:55], v[210:213], v[44:47], v[18:21]
	v_mfma_f32_16x16x32_bf16 v[18:21], v[14:17], v[230:233], v[166:169]
	v_mfma_f32_16x16x32_bf16 v[48:51], v[24:27], v[234:237], v[18:21]
	v_mfma_f32_16x16x32_bf16 v[18:21], v[28:31], v[230:233], v[170:173]
	v_mfma_f32_16x16x32_bf16 v[36:39], v[210:213], v[234:237], v[18:21]
	v_mfma_f32_16x16x32_bf16 v[18:21], v[14:17], v[238:241], v[174:177]
	v_mfma_f32_16x16x32_bf16 v[32:35], v[24:27], v[242:245], v[18:21]
	v_mfma_f32_16x16x32_bf16 v[18:21], v[28:31], v[238:241], v[178:181]
	v_mfma_f32_16x16x32_bf16 v[2:5], v[14:17], v[246:249], v[2:5]
	v_mfma_f32_16x16x32_bf16 v[20:23], v[210:213], v[242:245], v[18:21]
	v_mfma_f32_16x16x32_bf16 v[16:19], v[24:27], v[250:253], v[2:5]
	v_mfma_f32_16x16x32_bf16 v[2:5], v[28:31], v[246:249], v[6:9]
	v_mfma_f32_16x16x32_bf16 v[4:7], v[210:213], v[250:253], v[2:5]
	v_mfma_f32_16x16x32_bf16 v[8:11], v[214:217], v[40:43], v[10:13]
	v_mfma_f32_16x16x32_bf16 v[60:63], v[218:221], v[44:47], v[8:11]
	v_mfma_f32_16x16x32_bf16 v[8:11], v[222:225], v[40:43], v[182:185]
	v_mfma_f32_16x16x32_bf16 v[56:59], v[226:229], v[44:47], v[8:11]
	v_mfma_f32_16x16x32_bf16 v[8:11], v[214:217], v[230:233], v[186:189]
	v_mfma_f32_16x16x32_bf16 v[44:47], v[218:221], v[234:237], v[8:11]
	v_mfma_f32_16x16x32_bf16 v[8:11], v[222:225], v[230:233], v[190:193]
	v_mfma_f32_16x16x32_bf16 v[40:43], v[226:229], v[234:237], v[8:11]
	v_mfma_f32_16x16x32_bf16 v[8:11], v[214:217], v[238:241], v[194:197]
	v_mfma_f32_16x16x32_bf16 v[28:31], v[218:221], v[242:245], v[8:11]
	v_mfma_f32_16x16x32_bf16 v[8:11], v[222:225], v[238:241], v[198:201]
	v_mfma_f32_16x16x32_bf16 v[24:27], v[226:229], v[242:245], v[8:11]
	v_mfma_f32_16x16x32_bf16 v[8:11], v[214:217], v[246:249], v[202:205]
	v_mfma_f32_16x16x32_bf16 v[12:15], v[218:221], v[250:253], v[8:11]
	v_mfma_f32_16x16x32_bf16 v[8:11], v[222:225], v[246:249], v[206:209]
	v_mfma_f32_16x16x32_bf16 v[8:11], v[226:229], v[250:253], v[8:11]
	s_barrier
	s_mov_b32 s22, 2
	s_branch .LBB0_1733

.LBB0_1734:
	ds_read_b128 v[158:161], v153
	ds_read_b128 v[162:165], v153 offset:1024
	ds_read_b128 v[166:169], v153 offset:2048
	ds_read_b128 v[170:173], v153 offset:3072
	ds_read_b128 v[174:177], v154
	ds_read_b128 v[178:181], v154 offset:1024
	ds_read_b128 v[182:185], v154 offset:2048
	ds_read_b128 v[186:189], v154 offset:3072
	s_add_u32 s12, s60, s24
	s_addc_u32 s13, s61, 0
	s_cmp_eq_u32 s24, s44
	s_cselect_b32 s23, s9, s13
	s_cselect_b32 s22, s8, s12
	s_cselect_b32 s47, s43, s59
	s_cselect_b32 s46, s42, s1
	s_add_i32 s63, s18, 0xc000
	v_lshl_add_u64 v[144:145], v[2:3], 0, s[24:25]
	s_mov_b32 m0, s63
	s_add_i32 s62, s18, 0xe000
	ds_read_b128 v[190:193], v155
	ds_read_b128 v[194:197], v155 offset:1024
	ds_read_b128 v[198:201], v155 offset:2048
	ds_read_b128 v[202:205], v155 offset:3072
	ds_read_b128 v[206:209], v155 offset:4096
	ds_read_b128 v[210:213], v155 offset:5120
	ds_read_b128 v[214:217], v155 offset:6144
	ds_read_b128 v[218:221], v155 offset:7168
	global_load_lds_dwordx4 v[144:145], off
	v_lshl_add_u64 v[144:145], v[148:149], 0, s[24:25]
	s_mov_b32 m0, s62
	s_nop 0
	global_load_lds_dwordx4 v[144:145], off
	s_waitcnt vmcnt(8)
	s_waitcnt lgkmcnt(0)
	s_barrier
	v_mfma_f32_16x16x32_bf16 v[128:131], v[158:161], v[190:193], v[128:131]
	v_mfma_f32_16x16x32_bf16 v[116:119], v[166:169], v[190:193], v[116:119]
	v_mfma_f32_16x16x32_bf16 v[112:115], v[158:161], v[198:201], v[112:115]
	v_mfma_f32_16x16x32_bf16 v[100:103], v[166:169], v[198:201], v[100:103]
	v_mfma_f32_16x16x32_bf16 v[96:99], v[158:161], v[206:209], v[96:99]
	v_mfma_f32_16x16x32_bf16 v[84:87], v[166:169], v[206:209], v[84:87]
	v_mfma_f32_16x16x32_bf16 v[80:83], v[158:161], v[214:217], v[80:83]
	v_mfma_f32_16x16x32_bf16 v[64:67], v[166:169], v[214:217], v[64:67]
	v_mfma_f32_16x16x32_bf16 v[128:131], v[162:165], v[194:197], v[128:131]
	v_mfma_f32_16x16x32_bf16 v[116:119], v[170:173], v[194:197], v[116:119]
	v_mfma_f32_16x16x32_bf16 v[112:115], v[162:165], v[202:205], v[112:115]
	v_mfma_f32_16x16x32_bf16 v[100:103], v[170:173], v[202:205], v[100:103]
	v_mfma_f32_16x16x32_bf16 v[96:99], v[162:165], v[210:213], v[96:99]
	v_mfma_f32_16x16x32_bf16 v[84:87], v[170:173], v[210:213], v[84:87]
	v_mfma_f32_16x16x32_bf16 v[80:83], v[162:165], v[218:221], v[80:83]
	v_mfma_f32_16x16x32_bf16 v[64:67], v[170:173], v[218:221], v[64:67]
	v_mfma_f32_16x16x32_bf16 v[124:127], v[174:177], v[190:193], v[124:127]
	v_mfma_f32_16x16x32_bf16 v[120:123], v[182:185], v[190:193], v[120:123]
	v_mfma_f32_16x16x32_bf16 v[108:111], v[174:177], v[198:201], v[108:111]
	v_mfma_f32_16x16x32_bf16 v[104:107], v[182:185], v[198:201], v[104:107]
	v_mfma_f32_16x16x32_bf16 v[92:95], v[174:177], v[206:209], v[92:95]
	v_mfma_f32_16x16x32_bf16 v[88:91], v[182:185], v[206:209], v[88:91]
	v_mfma_f32_16x16x32_bf16 v[72:75], v[174:177], v[214:217], v[72:75]
	v_mfma_f32_16x16x32_bf16 v[68:71], v[182:185], v[214:217], v[68:71]
	v_mfma_f32_16x16x32_bf16 v[124:127], v[178:181], v[194:197], v[124:127]
	v_mfma_f32_16x16x32_bf16 v[120:123], v[186:189], v[194:197], v[120:123]
	v_mfma_f32_16x16x32_bf16 v[108:111], v[178:181], v[202:205], v[108:111]
	v_mfma_f32_16x16x32_bf16 v[104:107], v[186:189], v[202:205], v[104:107]
	v_mfma_f32_16x16x32_bf16 v[92:95], v[178:181], v[210:213], v[92:95]
	v_mfma_f32_16x16x32_bf16 v[88:91], v[186:189], v[210:213], v[88:91]
	v_mfma_f32_16x16x32_bf16 v[72:75], v[178:181], v[218:221], v[72:75]
	v_mfma_f32_16x16x32_bf16 v[68:71], v[186:189], v[218:221], v[68:71]
	s_barrier
	s_add_i32 s12, s52, s17
	v_lshl_add_u64 v[144:145], s[46:47], 0, v[134:135]
	s_mov_b32 m0, s12
	ds_read_b128 v[190:193], v155 offset:16384
	ds_read_b128 v[194:197], v155 offset:17408
	ds_read_b128 v[198:201], v155 offset:18432
	ds_read_b128 v[202:205], v155 offset:19456
	ds_read_b128 v[206:209], v155 offset:20480
	ds_read_b128 v[210:213], v155 offset:21504
	ds_read_b128 v[214:217], v155 offset:22528
	ds_read_b128 v[218:221], v155 offset:23552
	global_load_lds_dwordx4 v[144:145], off
	s_add_i32 m0, s12, 0x2000
	s_add_u32 s12, s46, 0x4000
	v_lshl_add_u64 v[144:145], s[46:47], 0, v[138:139]
	s_addc_u32 s13, s47, 0
	s_add_i32 s14, s53, s17
	global_load_lds_dwordx4 v[144:145], off
	v_lshl_add_u64 v[144:145], s[12:13], 0, v[134:135]
	s_mov_b32 m0, s14
	v_lshl_add_u64 v[222:223], s[22:23], 0, v[136:137]
	global_load_lds_dwordx4 v[144:145], off
	v_lshl_add_u64 v[144:145], s[12:13], 0, v[138:139]
	s_add_i32 m0, s14, 0x2000
	s_nop 0
	global_load_lds_dwordx4 v[144:145], off
	v_lshl_add_u64 v[144:145], s[22:23], 0, v[132:133]
	s_mov_b32 m0, s18
	s_nop 0
	global_load_lds_dwordx4 v[144:145], off
	s_mov_b32 m0, s19
	s_nop 0
	global_load_lds_dwordx4 v[222:223], off
	s_waitcnt vmcnt(8)
	s_waitcnt lgkmcnt(0)
	s_barrier
	v_mfma_f32_16x16x32_bf16 v[76:79], v[158:161], v[190:193], v[76:79]
	v_mfma_f32_16x16x32_bf16 v[52:55], v[166:169], v[190:193], v[52:55]
	v_mfma_f32_16x16x32_bf16 v[48:51], v[158:161], v[198:201], v[48:51]
	v_mfma_f32_16x16x32_bf16 v[36:39], v[166:169], v[198:201], v[36:39]
	v_mfma_f32_16x16x32_bf16 v[32:35], v[158:161], v[206:209], v[32:35]
	v_mfma_f32_16x16x32_bf16 v[20:23], v[166:169], v[206:209], v[20:23]
	v_mfma_f32_16x16x32_bf16 v[16:19], v[158:161], v[214:217], v[16:19]
	v_mfma_f32_16x16x32_bf16 v[4:7], v[166:169], v[214:217], v[4:7]
	v_mfma_f32_16x16x32_bf16 v[76:79], v[162:165], v[194:197], v[76:79]
	v_mfma_f32_16x16x32_bf16 v[52:55], v[170:173], v[194:197], v[52:55]
	v_mfma_f32_16x16x32_bf16 v[48:51], v[162:165], v[202:205], v[48:51]
	v_mfma_f32_16x16x32_bf16 v[36:39], v[170:173], v[202:205], v[36:39]
	v_mfma_f32_16x16x32_bf16 v[32:35], v[162:165], v[210:213], v[32:35]
	v_mfma_f32_16x16x32_bf16 v[20:23], v[170:173], v[210:213], v[20:23]
	v_mfma_f32_16x16x32_bf16 v[16:19], v[162:165], v[218:221], v[16:19]
	v_mfma_f32_16x16x32_bf16 v[4:7], v[170:173], v[218:221], v[4:7]
	v_mfma_f32_16x16x32_bf16 v[60:63], v[174:177], v[190:193], v[60:63]
	v_mfma_f32_16x16x32_bf16 v[56:59], v[182:185], v[190:193], v[56:59]
	v_mfma_f32_16x16x32_bf16 v[44:47], v[174:177], v[198:201], v[44:47]
	v_mfma_f32_16x16x32_bf16 v[40:43], v[182:185], v[198:201], v[40:43]
	v_mfma_f32_16x16x32_bf16 v[28:31], v[174:177], v[206:209], v[28:31]
	v_mfma_f32_16x16x32_bf16 v[24:27], v[182:185], v[206:209], v[24:27]
	v_mfma_f32_16x16x32_bf16 v[12:15], v[174:177], v[214:217], v[12:15]
	v_mfma_f32_16x16x32_bf16 v[8:11], v[182:185], v[214:217], v[8:11]
	v_mfma_f32_16x16x32_bf16 v[60:63], v[178:181], v[194:197], v[60:63]
	v_mfma_f32_16x16x32_bf16 v[56:59], v[186:189], v[194:197], v[56:59]
	v_mfma_f32_16x16x32_bf16 v[44:47], v[178:181], v[202:205], v[44:47]
	v_mfma_f32_16x16x32_bf16 v[40:43], v[186:189], v[202:205], v[40:43]
	v_mfma_f32_16x16x32_bf16 v[28:31], v[178:181], v[210:213], v[28:31]
	v_mfma_f32_16x16x32_bf16 v[24:27], v[186:189], v[210:213], v[24:27]
	v_mfma_f32_16x16x32_bf16 v[12:15], v[178:181], v[218:221], v[12:15]
	v_mfma_f32_16x16x32_bf16 v[8:11], v[186:189], v[218:221], v[8:11]
	s_barrier
	s_add_i32 s14, 0, 0x18000
	v_add_u32_e32 v1, s14, v151
	s_add_i32 s64, 0, 0x1c000
	ds_read_b128 v[158:161], v1
	ds_read_b128 v[162:165], v1 offset:1024
	ds_read_b128 v[166:169], v1 offset:2048
	ds_read_b128 v[170:173], v1 offset:3072
	v_add_u32_e32 v1, s64, v151
	ds_read_b128 v[174:177], v1
	ds_read_b128 v[178:181], v1 offset:1024
	ds_read_b128 v[182:185], v1 offset:2048
	ds_read_b128 v[186:189], v1 offset:3072
	s_add_u32 s12, s22, 0x2b0000
	s_addc_u32 s13, s23, 0
	s_mov_b32 m0, s20
	v_lshl_add_u64 v[224:225], s[12:13], 0, v[132:133]
	ds_read_b128 v[190:193], v155 offset:32768
	ds_read_b128 v[194:197], v155 offset:33792
	ds_read_b128 v[198:201], v155 offset:34816
	ds_read_b128 v[202:205], v155 offset:35840
	ds_read_b128 v[206:209], v155 offset:36864
	ds_read_b128 v[210:213], v155 offset:37888
	ds_read_b128 v[214:217], v155 offset:38912
	ds_read_b128 v[218:221], v155 offset:39936
	global_load_lds_dwordx4 v[224:225], off
	v_lshl_add_u64 v[224:225], s[12:13], 0, v[136:137]
	s_mov_b32 m0, s21
	s_nop 0
	global_load_lds_dwordx4 v[224:225], off
	s_waitcnt vmcnt(8)
	s_waitcnt lgkmcnt(0)
	s_barrier
	v_mfma_f32_16x16x32_bf16 v[128:131], v[158:161], v[190:193], v[128:131]
	v_mfma_f32_16x16x32_bf16 v[116:119], v[166:169], v[190:193], v[116:119]
	v_mfma_f32_16x16x32_bf16 v[112:115], v[158:161], v[198:201], v[112:115]
	v_mfma_f32_16x16x32_bf16 v[100:103], v[166:169], v[198:201], v[100:103]
	v_mfma_f32_16x16x32_bf16 v[96:99], v[158:161], v[206:209], v[96:99]
	v_mfma_f32_16x16x32_bf16 v[84:87], v[166:169], v[206:209], v[84:87]
	v_mfma_f32_16x16x32_bf16 v[80:83], v[158:161], v[214:217], v[80:83]
	v_mfma_f32_16x16x32_bf16 v[64:67], v[166:169], v[214:217], v[64:67]
	v_mfma_f32_16x16x32_bf16 v[128:131], v[162:165], v[194:197], v[128:131]
	v_mfma_f32_16x16x32_bf16 v[116:119], v[170:173], v[194:197], v[116:119]
	v_mfma_f32_16x16x32_bf16 v[112:115], v[162:165], v[202:205], v[112:115]
	v_mfma_f32_16x16x32_bf16 v[100:103], v[170:173], v[202:205], v[100:103]
	v_mfma_f32_16x16x32_bf16 v[96:99], v[162:165], v[210:213], v[96:99]
	v_mfma_f32_16x16x32_bf16 v[84:87], v[170:173], v[210:213], v[84:87]
	v_mfma_f32_16x16x32_bf16 v[80:83], v[162:165], v[218:221], v[80:83]
	v_mfma_f32_16x16x32_bf16 v[64:67], v[170:173], v[218:221], v[64:67]
	v_mfma_f32_16x16x32_bf16 v[124:127], v[174:177], v[190:193], v[124:127]
	v_mfma_f32_16x16x32_bf16 v[120:123], v[182:185], v[190:193], v[120:123]
	v_mfma_f32_16x16x32_bf16 v[108:111], v[174:177], v[198:201], v[108:111]
	v_mfma_f32_16x16x32_bf16 v[104:107], v[182:185], v[198:201], v[104:107]
	v_mfma_f32_16x16x32_bf16 v[92:95], v[174:177], v[206:209], v[92:95]
	v_mfma_f32_16x16x32_bf16 v[88:91], v[182:185], v[206:209], v[88:91]
	v_mfma_f32_16x16x32_bf16 v[72:75], v[174:177], v[214:217], v[72:75]
	v_mfma_f32_16x16x32_bf16 v[68:71], v[182:185], v[214:217], v[68:71]
	v_mfma_f32_16x16x32_bf16 v[124:127], v[178:181], v[194:197], v[124:127]
	v_mfma_f32_16x16x32_bf16 v[120:123], v[186:189], v[194:197], v[120:123]
	v_mfma_f32_16x16x32_bf16 v[108:111], v[178:181], v[202:205], v[108:111]
	v_mfma_f32_16x16x32_bf16 v[104:107], v[186:189], v[202:205], v[104:107]
	v_mfma_f32_16x16x32_bf16 v[92:95], v[178:181], v[210:213], v[92:95]
	v_mfma_f32_16x16x32_bf16 v[88:91], v[186:189], v[210:213], v[88:91]
	v_mfma_f32_16x16x32_bf16 v[72:75], v[178:181], v[218:221], v[72:75]
	v_mfma_f32_16x16x32_bf16 v[68:71], v[186:189], v[218:221], v[68:71]
	s_barrier
	s_add_u32 s12, s46, 0x8000
	s_addc_u32 s13, s47, 0
	s_add_i32 s14, s14, s17
	v_lshl_add_u64 v[224:225], s[12:13], 0, v[134:135]
	s_mov_b32 m0, s14
	ds_read_b128 v[190:193], v155 offset:49152
	ds_read_b128 v[194:197], v155 offset:50176
	ds_read_b128 v[198:201], v155 offset:51200
	ds_read_b128 v[202:205], v155 offset:52224
	ds_read_b128 v[206:209], v155 offset:53248
	ds_read_b128 v[210:213], v155 offset:54272
	ds_read_b128 v[214:217], v155 offset:55296
	ds_read_b128 v[218:221], v155 offset:56320
	global_load_lds_dwordx4 v[224:225], off
	s_add_i32 m0, s14, 0x2000
	v_lshl_add_u64 v[224:225], s[12:13], 0, v[138:139]
	s_add_u32 s12, s46, 0xc000
	s_addc_u32 s13, s47, 0
	s_add_i32 s14, s64, s17
	global_load_lds_dwordx4 v[224:225], off
	v_lshl_add_u64 v[224:225], s[12:13], 0, v[134:135]
	s_mov_b32 m0, s14
	v_lshl_add_u64 v[144:145], v[144:145], 0, s[34:35]
	global_load_lds_dwordx4 v[224:225], off
	v_lshl_add_u64 v[224:225], s[12:13], 0, v[138:139]
	s_add_i32 m0, s14, 0x2000
	s_nop 0
	global_load_lds_dwordx4 v[224:225], off
	s_mov_b32 m0, s48
	s_nop 0
	global_load_lds_dwordx4 v[144:145], off
	v_lshl_add_u64 v[144:145], v[222:223], 0, s[34:35]
	s_mov_b32 m0, s49
	s_nop 0
	global_load_lds_dwordx4 v[144:145], off
	s_waitcnt vmcnt(8)
	s_waitcnt lgkmcnt(0)
	s_barrier
	v_mfma_f32_16x16x32_bf16 v[76:79], v[158:161], v[190:193], v[76:79]
	v_mfma_f32_16x16x32_bf16 v[52:55], v[166:169], v[190:193], v[52:55]
	v_mfma_f32_16x16x32_bf16 v[48:51], v[158:161], v[198:201], v[48:51]
	v_mfma_f32_16x16x32_bf16 v[36:39], v[166:169], v[198:201], v[36:39]
	v_mfma_f32_16x16x32_bf16 v[32:35], v[158:161], v[206:209], v[32:35]
	v_mfma_f32_16x16x32_bf16 v[20:23], v[166:169], v[206:209], v[20:23]
	v_mfma_f32_16x16x32_bf16 v[16:19], v[158:161], v[214:217], v[16:19]
	v_mfma_f32_16x16x32_bf16 v[4:7], v[166:169], v[214:217], v[4:7]
	v_mfma_f32_16x16x32_bf16 v[76:79], v[162:165], v[194:197], v[76:79]
	v_mfma_f32_16x16x32_bf16 v[52:55], v[170:173], v[194:197], v[52:55]
	v_mfma_f32_16x16x32_bf16 v[48:51], v[162:165], v[202:205], v[48:51]
	v_mfma_f32_16x16x32_bf16 v[36:39], v[170:173], v[202:205], v[36:39]
	v_mfma_f32_16x16x32_bf16 v[32:35], v[162:165], v[210:213], v[32:35]
	v_mfma_f32_16x16x32_bf16 v[20:23], v[170:173], v[210:213], v[20:23]
	v_mfma_f32_16x16x32_bf16 v[16:19], v[162:165], v[218:221], v[16:19]
	v_mfma_f32_16x16x32_bf16 v[4:7], v[170:173], v[218:221], v[4:7]
	v_mfma_f32_16x16x32_bf16 v[60:63], v[174:177], v[190:193], v[60:63]
	v_mfma_f32_16x16x32_bf16 v[56:59], v[182:185], v[190:193], v[56:59]
	v_mfma_f32_16x16x32_bf16 v[44:47], v[174:177], v[198:201], v[44:47]
	v_mfma_f32_16x16x32_bf16 v[40:43], v[182:185], v[198:201], v[40:43]
	v_mfma_f32_16x16x32_bf16 v[28:31], v[174:177], v[206:209], v[28:31]
	v_mfma_f32_16x16x32_bf16 v[24:27], v[182:185], v[206:209], v[24:27]
	v_mfma_f32_16x16x32_bf16 v[12:15], v[174:177], v[214:217], v[12:15]
	v_mfma_f32_16x16x32_bf16 v[8:11], v[182:185], v[214:217], v[8:11]
	v_mfma_f32_16x16x32_bf16 v[60:63], v[178:181], v[194:197], v[60:63]
	v_mfma_f32_16x16x32_bf16 v[56:59], v[186:189], v[194:197], v[56:59]
	v_mfma_f32_16x16x32_bf16 v[44:47], v[178:181], v[202:205], v[44:47]
	v_mfma_f32_16x16x32_bf16 v[40:43], v[186:189], v[202:205], v[40:43]
	v_mfma_f32_16x16x32_bf16 v[28:31], v[178:181], v[210:213], v[28:31]
	v_mfma_f32_16x16x32_bf16 v[24:27], v[186:189], v[210:213], v[24:27]
	v_mfma_f32_16x16x32_bf16 v[12:15], v[178:181], v[218:221], v[12:15]
	v_mfma_f32_16x16x32_bf16 v[8:11], v[186:189], v[218:221], v[8:11]
	s_barrier
	s_add_i32 s0, s0, 2
	s_add_u32 s1, s1, 0x10000
	s_addc_u32 s59, s59, 0
	s_add_u32 s60, s60, 0x100
	s_addc_u32 s61, s61, 0
	s_add_u32 s44, s44, 0xffffff00
	s_addc_u32 s45, s45, -1
	v_lshl_add_u64 v[2:3], v[2:3], 0, s[38:39]
	s_cmpk_gt_u32 s0, 0xa9
	v_lshl_add_u64 v[148:149], v[148:149], 0, s[38:39]
	s_cbranch_scc0 .LBB0_1734
	s_and_b64 vcc, exec, s[36:37]
	s_cbranch_vccz .LBB0_1737
	s_barrier
